# fgate inner loop rewritten: weights resident in VGPRs, batched loads, permlane/DPP reductions instead of ds_bpermute chains
# speedup vs baseline: 1.0122x; 1.0122x over previous
; #define LAS __attribute__((address_space(3)))
; __device__ __forceinline__ void fgate_phase(const bfr* x, const float* wf, const float* bfg, float* cl, float* ctot, LAS float* scr, int bx, int G, int tid, int lane, int wave) {
;     for (int chunk = bx; chunk < M / 64; chunk += G) {
; #pragma unroll 1
;         for (int j = 0; j < 8; j += 2) { const int row = chunk * 64 + wave * 8 + j; typedef unsigned u32x2 __attribute__((ext_vector_type(2))); const u32x2* xa = (const u32x2*)(x + (size_t)row * D) + lane; const u32x2* xb2 = xa + D / 4; f32x4 va[4], vb[4]; float r[18]; int zo = 0; asm volatile("" : "+v"(zo));
; #pragma unroll
;             for (int jj = 0; jj < 4; ++jj) { const u32x2 wa = xa[64 * jj], wb = xb2[64 * jj]; va[jj] = (f32x4){bf_lo(wa.x), bf_hi(wa.x), bf_lo(wa.y), bf_hi(wa.y)}; vb[jj] = (f32x4){bf_lo(wb.x), bf_hi(wb.x), bf_lo(wb.y), bf_hi(wb.y)}; }
;             r[16] = 0.f; r[17] = 0.f;
; #pragma unroll
;             for (int jj = 0; jj < 4; ++jj) { r[16] += (va[jj].x * va[jj].x + va[jj].y * va[jj].y) + (va[jj].z * va[jj].z + va[jj].w * va[jj].w); r[17] += (vb[jj].x * vb[jj].x + vb[jj].y * vb[jj].y) + (vb[jj].z * vb[jj].z + vb[jj].w * vb[jj].w); }
; #pragma unroll
;             for (int h = 0; h < NH; ++h) { const f32x4* wr = (const f32x4*)(wf + h * D) + lane + zo; float da = 0.f, db = 0.f;
; #pragma unroll
;                 for (int jj = 0; jj < 4; ++jj) { const f32x4 w = wr[64 * jj]; da += (va[jj].x * w.x + va[jj].y * w.y) + (va[jj].z * w.z + va[jj].w * w.w); db += (vb[jj].x * w.x + vb[jj].y * w.y) + (vb[jj].z * w.z + vb[jj].w * w.w); }
;                 r[h] = da; r[8 + h] = db; }
.LBB0_424:
	s_mov_b32 s38, s33
	s_ashr_i32 s39, s33, 31
	s_lshl_b64 s[38:39], s[38:39], 11
	s_mov_b64 s[98:99], 0x1000
	s_mov_b64 s[100:101], 0x2000
	v_lshl_add_u64 v[26:27], v[28:29], 0, s[38:39]
	v_lshl_add_u64 v[42:43], v[30:31], 0, s[98:99]
	v_lshl_add_u64 v[40:41], v[26:27], 0, s[98:99]
	global_load_dwordx2 v[38:39], v[26:27], off
	global_load_dwordx2 v[98:99], v[26:27], off offset:512
	global_load_dwordx2 v[160:161], v[26:27], off offset:1024
	global_load_dwordx2 v[0:1], v[26:27], off offset:1536
	global_load_dwordx2 v[2:3], v[26:27], off offset:2048
	global_load_dwordx2 v[4:5], v[26:27], off offset:2560
	global_load_dwordx2 v[6:7], v[26:27], off offset:3072
	global_load_dwordx2 v[8:9], v[26:27], off offset:3584
	global_load_dwordx2 v[10:11], v[40:41], off
	global_load_dwordx2 v[12:13], v[40:41], off offset:512
	global_load_dwordx2 v[14:15], v[40:41], off offset:1024
	global_load_dwordx2 v[16:17], v[40:41], off offset:1536
	global_load_dwordx2 v[18:19], v[40:41], off offset:2048
	global_load_dwordx2 v[20:21], v[40:41], off offset:2560
	global_load_dwordx2 v[22:23], v[40:41], off offset:3072
	global_load_dwordx2 v[24:25], v[40:41], off offset:3584
	global_load_dword v105, v[32:33], off
	global_load_dwordx4 v[248:251], v[42:43], off offset:-4096
	global_load_dwordx4 v[244:247], v[42:43], off offset:-3072
	global_load_dwordx4 v[240:243], v[42:43], off offset:-2048
	global_load_dwordx4 v[236:239], v[42:43], off offset:-1024
	global_load_dwordx4 v[232:235], v[42:43], off
	global_load_dwordx4 v[228:231], v[42:43], off offset:1024
	global_load_dwordx4 v[224:227], v[42:43], off offset:2048
	global_load_dwordx4 v[220:223], v[42:43], off offset:3072
	v_lshl_add_u64 v[42:43], v[42:43], 0, s[100:101]
	global_load_dwordx4 v[216:219], v[42:43], off offset:-4096
	global_load_dwordx4 v[212:215], v[42:43], off offset:-3072
	global_load_dwordx4 v[208:211], v[42:43], off offset:-2048
	global_load_dwordx4 v[204:207], v[42:43], off offset:-1024
	global_load_dwordx4 v[200:203], v[42:43], off
	global_load_dwordx4 v[196:199], v[42:43], off offset:1024
	global_load_dwordx4 v[192:195], v[42:43], off offset:2048
	global_load_dwordx4 v[188:191], v[42:43], off offset:3072
	v_lshl_add_u64 v[42:43], v[42:43], 0, s[100:101]
	global_load_dwordx4 v[182:185], v[42:43], off offset:-4096
	global_load_dwordx4 v[178:181], v[42:43], off offset:-3072
	global_load_dwordx4 v[174:177], v[42:43], off offset:-2048
	global_load_dwordx4 v[170:173], v[42:43], off offset:-1024
	global_load_dwordx4 v[166:169], v[42:43], off
	global_load_dwordx4 v[162:165], v[42:43], off offset:1024
	global_load_dwordx4 v[154:157], v[42:43], off offset:2048
	global_load_dwordx4 v[150:153], v[42:43], off offset:3072
	v_lshl_add_u64 v[42:43], v[42:43], 0, s[100:101]
	global_load_dwordx4 v[146:149], v[42:43], off offset:-4096
	global_load_dwordx4 v[142:145], v[42:43], off offset:-3072
	global_load_dwordx4 v[138:141], v[42:43], off offset:-2048
	global_load_dwordx4 v[134:137], v[42:43], off offset:-1024
	global_load_dwordx4 v[130:133], v[42:43], off
	global_load_dwordx4 v[124:127], v[42:43], off offset:1024
	global_load_dwordx4 v[120:123], v[42:43], off offset:2048
	global_load_dwordx4 v[116:119], v[42:43], off offset:3072
	v_and_b32_e32 v108, 7, v158
	v_cmp_eq_u32_e64 s[6:7], 1, v108
	v_cmp_eq_u32_e64 s[8:9], 2, v108
	v_cmp_eq_u32_e64 s[10:11], 3, v108
	v_cmp_eq_u32_e64 s[12:13], 4, v108
	v_cmp_eq_u32_e64 s[14:15], 5, v108
	v_cmp_eq_u32_e64 s[16:17], 6, v108
	v_cmp_eq_u32_e64 s[18:19], 7, v108
	v_lshrrev_b32_e32 v106, 4, v158
	v_lshlrev_b32_e32 v106, 5, v106
	v_sub_u32_e32 v109, v95, v106
	s_mov_b32 s40, 0xffff0000
	s_waitcnt vmcnt(0)
	v_lshlrev_b32_e32 v97, 16, v38
	v_and_b32_e32 v159, s40, v38
	v_lshlrev_b32_e32 v187, 16, v39
	v_and_b32_e32 v44, s40, v39
	v_lshlrev_b32_e32 v45, 16, v98
	v_and_b32_e32 v46, s40, v98
	v_lshlrev_b32_e32 v47, 16, v99
	v_and_b32_e32 v48, s40, v99
	v_lshlrev_b32_e32 v49, 16, v160
	v_and_b32_e32 v50, s40, v160
	v_lshlrev_b32_e32 v51, 16, v161
	v_and_b32_e32 v52, s40, v161
	v_lshlrev_b32_e32 v53, 16, v0
	v_and_b32_e32 v54, s40, v0
	v_lshlrev_b32_e32 v55, 16, v1
	v_and_b32_e32 v56, s40, v1
	v_mul_f32_e32 v101, v97, v97
	v_mul_f32_e32 v57, v97, v248
	v_mul_f32_e32 v58, v97, v232
	v_mul_f32_e32 v59, v97, v216
	v_mul_f32_e32 v60, v97, v200
	v_mul_f32_e32 v61, v97, v182
	v_mul_f32_e32 v62, v97, v166
	v_mul_f32_e32 v63, v97, v146
	v_mul_f32_e32 v64, v97, v130
	v_fmac_f32_e32 v101, v159, v159
	v_fmac_f32_e32 v57, v159, v249
	v_fmac_f32_e32 v58, v159, v233
	v_fmac_f32_e32 v59, v159, v217
	v_fmac_f32_e32 v60, v159, v201
	v_fmac_f32_e32 v61, v159, v183
	v_fmac_f32_e32 v62, v159, v167
	v_fmac_f32_e32 v63, v159, v147
	v_fmac_f32_e32 v64, v159, v131
	v_fmac_f32_e32 v101, v187, v187
	v_fmac_f32_e32 v57, v187, v250
	v_fmac_f32_e32 v58, v187, v234
	v_fmac_f32_e32 v59, v187, v218
	v_fmac_f32_e32 v60, v187, v202
	v_fmac_f32_e32 v61, v187, v184
	v_fmac_f32_e32 v62, v187, v168
	v_fmac_f32_e32 v63, v187, v148
	v_fmac_f32_e32 v64, v187, v132
	v_fmac_f32_e32 v101, v44, v44
	v_fmac_f32_e32 v57, v44, v251
	v_fmac_f32_e32 v58, v44, v235
	v_fmac_f32_e32 v59, v44, v219
	v_fmac_f32_e32 v60, v44, v203
	v_fmac_f32_e32 v61, v44, v185
	v_fmac_f32_e32 v62, v44, v169
	v_fmac_f32_e32 v63, v44, v149
	v_fmac_f32_e32 v64, v44, v133
	v_fmac_f32_e32 v101, v45, v45
	v_fmac_f32_e32 v57, v45, v244
	v_fmac_f32_e32 v58, v45, v228
	v_fmac_f32_e32 v59, v45, v212
	v_fmac_f32_e32 v60, v45, v196
	v_fmac_f32_e32 v61, v45, v178
	v_fmac_f32_e32 v62, v45, v162
	v_fmac_f32_e32 v63, v45, v142
	v_fmac_f32_e32 v64, v45, v124
	v_fmac_f32_e32 v101, v46, v46
	v_fmac_f32_e32 v57, v46, v245
	v_fmac_f32_e32 v58, v46, v229
; __device__ __forceinline__ void fgate_phase(const bfr* x, const float* wf, const float* bfg, float* cl, float* ctot, LAS float* scr, int bx, int G, int tid, int lane, int wave) {
;     ...
;             for (int jj = 0; jj < 4; ++jj) { r[16] += (va[jj].x * va[jj].x + va[jj].y * va[jj].y) + (va[jj].z * va[jj].z + va[jj].w * va[jj].w); r[17] += (vb[jj].x * vb[jj].x + vb[jj].y * vb[jj].y) + (vb[jj].z * vb[jj].z + vb[jj].w * vb[jj].w); }
; #pragma unroll
;             for (int h = 0; h < NH; ++h) { const f32x4* wr = (const f32x4*)(wf + h * D) + lane + zo; float da = 0.f, db = 0.f;
; #pragma unroll
;                 for (int jj = 0; jj < 4; ++jj) { const f32x4 w = wr[64 * jj]; da += (va[jj].x * w.x + va[jj].y * w.y) + (va[jj].z * w.z + va[jj].w * w.w); db += (vb[jj].x * w.x + vb[jj].y * w.y) + (vb[jj].z * w.z + vb[jj].w * w.w); }
;                 r[h] = da; r[8 + h] = db; }
	v_fmac_f32_e32 v59, v46, v213
	v_fmac_f32_e32 v60, v46, v197
	v_fmac_f32_e32 v61, v46, v179
	v_fmac_f32_e32 v62, v46, v163
	v_fmac_f32_e32 v63, v46, v143
	v_fmac_f32_e32 v64, v46, v125
	v_fmac_f32_e32 v101, v47, v47
	v_fmac_f32_e32 v57, v47, v246
	v_fmac_f32_e32 v58, v47, v230
	v_fmac_f32_e32 v59, v47, v214
	v_fmac_f32_e32 v60, v47, v198
	v_fmac_f32_e32 v61, v47, v180
	v_fmac_f32_e32 v62, v47, v164
	v_fmac_f32_e32 v63, v47, v144
	v_fmac_f32_e32 v64, v47, v126
	v_fmac_f32_e32 v101, v48, v48
	v_fmac_f32_e32 v57, v48, v247
	v_fmac_f32_e32 v58, v48, v231
	v_fmac_f32_e32 v59, v48, v215
	v_fmac_f32_e32 v60, v48, v199
	v_fmac_f32_e32 v61, v48, v181
	v_fmac_f32_e32 v62, v48, v165
	v_fmac_f32_e32 v63, v48, v145
	v_fmac_f32_e32 v64, v48, v127
	v_fmac_f32_e32 v101, v49, v49
	v_fmac_f32_e32 v57, v49, v240
	v_fmac_f32_e32 v58, v49, v224
	v_fmac_f32_e32 v59, v49, v208
	v_fmac_f32_e32 v60, v49, v192
	v_fmac_f32_e32 v61, v49, v174
	v_fmac_f32_e32 v62, v49, v154
	v_fmac_f32_e32 v63, v49, v138
	v_fmac_f32_e32 v64, v49, v120
	v_fmac_f32_e32 v101, v50, v50
	v_fmac_f32_e32 v57, v50, v241
	v_fmac_f32_e32 v58, v50, v225
	v_fmac_f32_e32 v59, v50, v209
	v_fmac_f32_e32 v60, v50, v193
	v_fmac_f32_e32 v61, v50, v175
	v_fmac_f32_e32 v62, v50, v155
	v_fmac_f32_e32 v63, v50, v139
	v_fmac_f32_e32 v64, v50, v121
	v_fmac_f32_e32 v101, v51, v51
	v_fmac_f32_e32 v57, v51, v242
	v_fmac_f32_e32 v58, v51, v226
	v_fmac_f32_e32 v59, v51, v210
	v_fmac_f32_e32 v60, v51, v194
	v_fmac_f32_e32 v61, v51, v176
	v_fmac_f32_e32 v62, v51, v156
	v_fmac_f32_e32 v63, v51, v140
	v_fmac_f32_e32 v64, v51, v122
	v_fmac_f32_e32 v101, v52, v52
	v_fmac_f32_e32 v57, v52, v243
	v_fmac_f32_e32 v58, v52, v227
	v_fmac_f32_e32 v59, v52, v211
	v_fmac_f32_e32 v60, v52, v195
	v_fmac_f32_e32 v61, v52, v177
	v_fmac_f32_e32 v62, v52, v157
	v_fmac_f32_e32 v63, v52, v141
	v_fmac_f32_e32 v64, v52, v123
	v_fmac_f32_e32 v101, v53, v53
	v_fmac_f32_e32 v57, v53, v236
	v_fmac_f32_e32 v58, v53, v220
	v_fmac_f32_e32 v59, v53, v204
	v_fmac_f32_e32 v60, v53, v188
	v_fmac_f32_e32 v61, v53, v170
	v_fmac_f32_e32 v62, v53, v150
	v_fmac_f32_e32 v63, v53, v134
	v_fmac_f32_e32 v64, v53, v116
	v_fmac_f32_e32 v101, v54, v54
	v_fmac_f32_e32 v57, v54, v237
	v_fmac_f32_e32 v58, v54, v221
	v_fmac_f32_e32 v59, v54, v205
	v_fmac_f32_e32 v60, v54, v189
	v_fmac_f32_e32 v61, v54, v171
	v_fmac_f32_e32 v62, v54, v151
	v_fmac_f32_e32 v63, v54, v135
	v_fmac_f32_e32 v64, v54, v117
	v_fmac_f32_e32 v101, v55, v55
	v_fmac_f32_e32 v57, v55, v238
	v_fmac_f32_e32 v58, v55, v222
	v_fmac_f32_e32 v59, v55, v206
	v_fmac_f32_e32 v60, v55, v190
	v_fmac_f32_e32 v61, v55, v172
	v_fmac_f32_e32 v62, v55, v152
	v_fmac_f32_e32 v63, v55, v136
	v_fmac_f32_e32 v64, v55, v118
	v_fmac_f32_e32 v101, v56, v56
	v_fmac_f32_e32 v57, v56, v239
	v_fmac_f32_e32 v58, v56, v223
	v_fmac_f32_e32 v59, v56, v207
	v_fmac_f32_e32 v60, v56, v191
	v_fmac_f32_e32 v61, v56, v173
	v_fmac_f32_e32 v62, v56, v153
	v_fmac_f32_e32 v63, v56, v137
	v_fmac_f32_e32 v64, v56, v119
	v_lshlrev_b32_e32 v97, 16, v2
	v_and_b32_e32 v159, s40, v2
	v_lshlrev_b32_e32 v187, 16, v3
	v_and_b32_e32 v44, s40, v3
	v_lshlrev_b32_e32 v45, 16, v4
	v_and_b32_e32 v46, s40, v4
	v_lshlrev_b32_e32 v47, 16, v5
	v_and_b32_e32 v48, s40, v5
	v_lshlrev_b32_e32 v49, 16, v6
	v_and_b32_e32 v50, s40, v6
	v_lshlrev_b32_e32 v51, 16, v7
	v_and_b32_e32 v52, s40, v7
	v_lshlrev_b32_e32 v53, 16, v8
	v_and_b32_e32 v54, s40, v8
	v_lshlrev_b32_e32 v55, 16, v9
	v_and_b32_e32 v56, s40, v9
	v_mul_f32_e32 v102, v97, v97
	v_mul_f32_e32 v65, v97, v248
	v_mul_f32_e32 v66, v97, v232
	v_mul_f32_e32 v67, v97, v216
	v_mul_f32_e32 v68, v97, v200
	v_mul_f32_e32 v69, v97, v182
	v_mul_f32_e32 v70, v97, v166
	v_mul_f32_e32 v71, v97, v146
	v_mul_f32_e32 v72, v97, v130
	v_fmac_f32_e32 v102, v159, v159
	v_fmac_f32_e32 v65, v159, v249
	v_fmac_f32_e32 v66, v159, v233
	v_fmac_f32_e32 v67, v159, v217
	v_fmac_f32_e32 v68, v159, v201
	v_fmac_f32_e32 v69, v159, v183
	v_fmac_f32_e32 v70, v159, v167
	v_fmac_f32_e32 v71, v159, v147
	v_fmac_f32_e32 v72, v159, v131
	v_fmac_f32_e32 v102, v187, v187
	v_fmac_f32_e32 v65, v187, v250
	v_fmac_f32_e32 v66, v187, v234
	v_fmac_f32_e32 v67, v187, v218
	v_fmac_f32_e32 v68, v187, v202
	v_fmac_f32_e32 v69, v187, v184
	v_fmac_f32_e32 v70, v187, v168
	v_fmac_f32_e32 v71, v187, v148
	v_fmac_f32_e32 v72, v187, v132
	v_fmac_f32_e32 v102, v44, v44
	v_fmac_f32_e32 v65, v44, v251
	v_fmac_f32_e32 v66, v44, v235
	v_fmac_f32_e32 v67, v44, v219
	v_fmac_f32_e32 v68, v44, v203
	v_fmac_f32_e32 v69, v44, v185
	v_fmac_f32_e32 v70, v44, v169
	v_fmac_f32_e32 v71, v44, v149
	v_fmac_f32_e32 v72, v44, v133
	v_fmac_f32_e32 v102, v45, v45
	v_fmac_f32_e32 v65, v45, v244
	v_fmac_f32_e32 v66, v45, v228
	v_fmac_f32_e32 v67, v45, v212
	v_fmac_f32_e32 v68, v45, v196
	v_fmac_f32_e32 v69, v45, v178
	v_fmac_f32_e32 v70, v45, v162
	v_fmac_f32_e32 v71, v45, v142
	v_fmac_f32_e32 v72, v45, v124
	v_fmac_f32_e32 v102, v46, v46
	v_fmac_f32_e32 v65, v46, v245
	v_fmac_f32_e32 v66, v46, v229
	v_fmac_f32_e32 v67, v46, v213
	v_fmac_f32_e32 v68, v46, v197
	v_fmac_f32_e32 v69, v46, v179
	v_fmac_f32_e32 v70, v46, v163
	v_fmac_f32_e32 v71, v46, v143
	v_fmac_f32_e32 v72, v46, v125
	v_fmac_f32_e32 v102, v47, v47
	v_fmac_f32_e32 v65, v47, v246
	v_fmac_f32_e32 v66, v47, v230
	v_fmac_f32_e32 v67, v47, v214
	v_fmac_f32_e32 v68, v47, v198
	v_fmac_f32_e32 v69, v47, v180
	v_fmac_f32_e32 v70, v47, v164
	v_fmac_f32_e32 v71, v47, v144
	v_fmac_f32_e32 v72, v47, v126
	v_fmac_f32_e32 v102, v48, v48
	v_fmac_f32_e32 v65, v48, v247
	v_fmac_f32_e32 v66, v48, v231
	v_fmac_f32_e32 v67, v48, v215
	v_fmac_f32_e32 v68, v48, v199
	v_fmac_f32_e32 v69, v48, v181
	v_fmac_f32_e32 v70, v48, v165
; __device__ __forceinline__ void fgate_phase(const bfr* x, const float* wf, const float* bfg, float* cl, float* ctot, LAS float* scr, int bx, int G, int tid, int lane, int wave) {
;     ...
;             for (int jj = 0; jj < 4; ++jj) { r[16] += (va[jj].x * va[jj].x + va[jj].y * va[jj].y) + (va[jj].z * va[jj].z + va[jj].w * va[jj].w); r[17] += (vb[jj].x * vb[jj].x + vb[jj].y * vb[jj].y) + (vb[jj].z * vb[jj].z + vb[jj].w * vb[jj].w); }
; #pragma unroll
;             for (int h = 0; h < NH; ++h) { const f32x4* wr = (const f32x4*)(wf + h * D) + lane + zo; float da = 0.f, db = 0.f;
; #pragma unroll
;                 for (int jj = 0; jj < 4; ++jj) { const f32x4 w = wr[64 * jj]; da += (va[jj].x * w.x + va[jj].y * w.y) + (va[jj].z * w.z + va[jj].w * w.w); db += (vb[jj].x * w.x + vb[jj].y * w.y) + (vb[jj].z * w.z + vb[jj].w * w.w); }
;                 r[h] = da; r[8 + h] = db; }
	v_fmac_f32_e32 v71, v48, v145
	v_fmac_f32_e32 v72, v48, v127
	v_fmac_f32_e32 v102, v49, v49
	v_fmac_f32_e32 v65, v49, v240
	v_fmac_f32_e32 v66, v49, v224
	v_fmac_f32_e32 v67, v49, v208
	v_fmac_f32_e32 v68, v49, v192
	v_fmac_f32_e32 v69, v49, v174
	v_fmac_f32_e32 v70, v49, v154
	v_fmac_f32_e32 v71, v49, v138
	v_fmac_f32_e32 v72, v49, v120
	v_fmac_f32_e32 v102, v50, v50
	v_fmac_f32_e32 v65, v50, v241
	v_fmac_f32_e32 v66, v50, v225
	v_fmac_f32_e32 v67, v50, v209
	v_fmac_f32_e32 v68, v50, v193
	v_fmac_f32_e32 v69, v50, v175
	v_fmac_f32_e32 v70, v50, v155
	v_fmac_f32_e32 v71, v50, v139
	v_fmac_f32_e32 v72, v50, v121
	v_fmac_f32_e32 v102, v51, v51
	v_fmac_f32_e32 v65, v51, v242
	v_fmac_f32_e32 v66, v51, v226
	v_fmac_f32_e32 v67, v51, v210
	v_fmac_f32_e32 v68, v51, v194
	v_fmac_f32_e32 v69, v51, v176
	v_fmac_f32_e32 v70, v51, v156
	v_fmac_f32_e32 v71, v51, v140
	v_fmac_f32_e32 v72, v51, v122
	v_fmac_f32_e32 v102, v52, v52
	v_fmac_f32_e32 v65, v52, v243
	v_fmac_f32_e32 v66, v52, v227
	v_fmac_f32_e32 v67, v52, v211
	v_fmac_f32_e32 v68, v52, v195
	v_fmac_f32_e32 v69, v52, v177
	v_fmac_f32_e32 v70, v52, v157
	v_fmac_f32_e32 v71, v52, v141
	v_fmac_f32_e32 v72, v52, v123
	v_fmac_f32_e32 v102, v53, v53
	v_fmac_f32_e32 v65, v53, v236
	v_fmac_f32_e32 v66, v53, v220
	v_fmac_f32_e32 v67, v53, v204
	v_fmac_f32_e32 v68, v53, v188
	v_fmac_f32_e32 v69, v53, v170
	v_fmac_f32_e32 v70, v53, v150
	v_fmac_f32_e32 v71, v53, v134
	v_fmac_f32_e32 v72, v53, v116
	v_fmac_f32_e32 v102, v54, v54
	v_fmac_f32_e32 v65, v54, v237
	v_fmac_f32_e32 v66, v54, v221
	v_fmac_f32_e32 v67, v54, v205
	v_fmac_f32_e32 v68, v54, v189
	v_fmac_f32_e32 v69, v54, v171
	v_fmac_f32_e32 v70, v54, v151
	v_fmac_f32_e32 v71, v54, v135
	v_fmac_f32_e32 v72, v54, v117
	v_fmac_f32_e32 v102, v55, v55
	v_fmac_f32_e32 v65, v55, v238
	v_fmac_f32_e32 v66, v55, v222
	v_fmac_f32_e32 v67, v55, v206
	v_fmac_f32_e32 v68, v55, v190
	v_fmac_f32_e32 v69, v55, v172
	v_fmac_f32_e32 v70, v55, v152
	v_fmac_f32_e32 v71, v55, v136
	v_fmac_f32_e32 v72, v55, v118
	v_fmac_f32_e32 v102, v56, v56
	v_fmac_f32_e32 v65, v56, v239
	v_fmac_f32_e32 v66, v56, v223
	v_fmac_f32_e32 v67, v56, v207
	v_fmac_f32_e32 v68, v56, v191
	v_fmac_f32_e32 v69, v56, v173
	v_fmac_f32_e32 v70, v56, v153
	v_fmac_f32_e32 v71, v56, v137
	v_fmac_f32_e32 v72, v56, v119
	v_lshlrev_b32_e32 v97, 16, v10
	v_and_b32_e32 v159, s40, v10
	v_lshlrev_b32_e32 v187, 16, v11
	v_and_b32_e32 v44, s40, v11
	v_lshlrev_b32_e32 v45, 16, v12
	v_and_b32_e32 v46, s40, v12
	v_lshlrev_b32_e32 v47, 16, v13
	v_and_b32_e32 v48, s40, v13
	v_lshlrev_b32_e32 v49, 16, v14
	v_and_b32_e32 v50, s40, v14
	v_lshlrev_b32_e32 v51, 16, v15
	v_and_b32_e32 v52, s40, v15
	v_lshlrev_b32_e32 v53, 16, v16
	v_and_b32_e32 v54, s40, v16
	v_lshlrev_b32_e32 v55, 16, v17
	v_and_b32_e32 v56, s40, v17
	v_mul_f32_e32 v103, v97, v97
	v_mul_f32_e32 v73, v97, v248
	v_mul_f32_e32 v74, v97, v232
	v_mul_f32_e32 v75, v97, v216
	v_mul_f32_e32 v76, v97, v200
	v_mul_f32_e32 v77, v97, v182
	v_mul_f32_e32 v78, v97, v166
	v_mul_f32_e32 v79, v97, v146
	v_mul_f32_e32 v80, v97, v130
	v_fmac_f32_e32 v103, v159, v159
	v_fmac_f32_e32 v73, v159, v249
	v_fmac_f32_e32 v74, v159, v233
	v_fmac_f32_e32 v75, v159, v217
	v_fmac_f32_e32 v76, v159, v201
	v_fmac_f32_e32 v77, v159, v183
	v_fmac_f32_e32 v78, v159, v167
	v_fmac_f32_e32 v79, v159, v147
	v_fmac_f32_e32 v80, v159, v131
	v_fmac_f32_e32 v103, v187, v187
	v_fmac_f32_e32 v73, v187, v250
	v_fmac_f32_e32 v74, v187, v234
	v_fmac_f32_e32 v75, v187, v218
	v_fmac_f32_e32 v76, v187, v202
	v_fmac_f32_e32 v77, v187, v184
	v_fmac_f32_e32 v78, v187, v168
	v_fmac_f32_e32 v79, v187, v148
	v_fmac_f32_e32 v80, v187, v132
	v_fmac_f32_e32 v103, v44, v44
	v_fmac_f32_e32 v73, v44, v251
	v_fmac_f32_e32 v74, v44, v235
	v_fmac_f32_e32 v75, v44, v219
	v_fmac_f32_e32 v76, v44, v203
	v_fmac_f32_e32 v77, v44, v185
	v_fmac_f32_e32 v78, v44, v169
	v_fmac_f32_e32 v79, v44, v149
	v_fmac_f32_e32 v80, v44, v133
	v_fmac_f32_e32 v103, v45, v45
	v_fmac_f32_e32 v73, v45, v244
	v_fmac_f32_e32 v74, v45, v228
	v_fmac_f32_e32 v75, v45, v212
	v_fmac_f32_e32 v76, v45, v196
	v_fmac_f32_e32 v77, v45, v178
	v_fmac_f32_e32 v78, v45, v162
	v_fmac_f32_e32 v79, v45, v142
	v_fmac_f32_e32 v80, v45, v124
	v_fmac_f32_e32 v103, v46, v46
	v_fmac_f32_e32 v73, v46, v245
	v_fmac_f32_e32 v74, v46, v229
	v_fmac_f32_e32 v75, v46, v213
	v_fmac_f32_e32 v76, v46, v197
	v_fmac_f32_e32 v77, v46, v179
	v_fmac_f32_e32 v78, v46, v163
	v_fmac_f32_e32 v79, v46, v143
	v_fmac_f32_e32 v80, v46, v125
	v_fmac_f32_e32 v103, v47, v47
	v_fmac_f32_e32 v73, v47, v246
	v_fmac_f32_e32 v74, v47, v230
	v_fmac_f32_e32 v75, v47, v214
	v_fmac_f32_e32 v76, v47, v198
	v_fmac_f32_e32 v77, v47, v180
	v_fmac_f32_e32 v78, v47, v164
	v_fmac_f32_e32 v79, v47, v144
	v_fmac_f32_e32 v80, v47, v126
	v_fmac_f32_e32 v103, v48, v48
	v_fmac_f32_e32 v73, v48, v247
	v_fmac_f32_e32 v74, v48, v231
	v_fmac_f32_e32 v75, v48, v215
	v_fmac_f32_e32 v76, v48, v199
	v_fmac_f32_e32 v77, v48, v181
	v_fmac_f32_e32 v78, v48, v165
	v_fmac_f32_e32 v79, v48, v145
	v_fmac_f32_e32 v80, v48, v127
	v_fmac_f32_e32 v103, v49, v49
	v_fmac_f32_e32 v73, v49, v240
	v_fmac_f32_e32 v74, v49, v224
	v_fmac_f32_e32 v75, v49, v208
	v_fmac_f32_e32 v76, v49, v192
	v_fmac_f32_e32 v77, v49, v174
	v_fmac_f32_e32 v78, v49, v154
	v_fmac_f32_e32 v79, v49, v138
	v_fmac_f32_e32 v80, v49, v120
	v_fmac_f32_e32 v103, v50, v50
	v_fmac_f32_e32 v73, v50, v241
	v_fmac_f32_e32 v74, v50, v225
	v_fmac_f32_e32 v75, v50, v209
	v_fmac_f32_e32 v76, v50, v193
	v_fmac_f32_e32 v77, v50, v175
	v_fmac_f32_e32 v78, v50, v155
	v_fmac_f32_e32 v79, v50, v139
	v_fmac_f32_e32 v80, v50, v121
	v_fmac_f32_e32 v103, v51, v51
	v_fmac_f32_e32 v73, v51, v242
; __device__ __forceinline__ void fgate_phase(const bfr* x, const float* wf, const float* bfg, float* cl, float* ctot, LAS float* scr, int bx, int G, int tid, int lane, int wave) {
;     ...
;             for (int jj = 0; jj < 4; ++jj) { r[16] += (va[jj].x * va[jj].x + va[jj].y * va[jj].y) + (va[jj].z * va[jj].z + va[jj].w * va[jj].w); r[17] += (vb[jj].x * vb[jj].x + vb[jj].y * vb[jj].y) + (vb[jj].z * vb[jj].z + vb[jj].w * vb[jj].w); }
; #pragma unroll
;             for (int h = 0; h < NH; ++h) { const f32x4* wr = (const f32x4*)(wf + h * D) + lane + zo; float da = 0.f, db = 0.f;
; #pragma unroll
;                 for (int jj = 0; jj < 4; ++jj) { const f32x4 w = wr[64 * jj]; da += (va[jj].x * w.x + va[jj].y * w.y) + (va[jj].z * w.z + va[jj].w * w.w); db += (vb[jj].x * w.x + vb[jj].y * w.y) + (vb[jj].z * w.z + vb[jj].w * w.w); }
;                 r[h] = da; r[8 + h] = db; }
	v_fmac_f32_e32 v74, v51, v226
	v_fmac_f32_e32 v75, v51, v210
	v_fmac_f32_e32 v76, v51, v194
	v_fmac_f32_e32 v77, v51, v176
	v_fmac_f32_e32 v78, v51, v156
	v_fmac_f32_e32 v79, v51, v140
	v_fmac_f32_e32 v80, v51, v122
	v_fmac_f32_e32 v103, v52, v52
	v_fmac_f32_e32 v73, v52, v243
	v_fmac_f32_e32 v74, v52, v227
	v_fmac_f32_e32 v75, v52, v211
	v_fmac_f32_e32 v76, v52, v195
	v_fmac_f32_e32 v77, v52, v177
	v_fmac_f32_e32 v78, v52, v157
	v_fmac_f32_e32 v79, v52, v141
	v_fmac_f32_e32 v80, v52, v123
	v_fmac_f32_e32 v103, v53, v53
	v_fmac_f32_e32 v73, v53, v236
	v_fmac_f32_e32 v74, v53, v220
	v_fmac_f32_e32 v75, v53, v204
	v_fmac_f32_e32 v76, v53, v188
	v_fmac_f32_e32 v77, v53, v170
	v_fmac_f32_e32 v78, v53, v150
	v_fmac_f32_e32 v79, v53, v134
	v_fmac_f32_e32 v80, v53, v116
	v_fmac_f32_e32 v103, v54, v54
	v_fmac_f32_e32 v73, v54, v237
	v_fmac_f32_e32 v74, v54, v221
	v_fmac_f32_e32 v75, v54, v205
	v_fmac_f32_e32 v76, v54, v189
	v_fmac_f32_e32 v77, v54, v171
	v_fmac_f32_e32 v78, v54, v151
	v_fmac_f32_e32 v79, v54, v135
	v_fmac_f32_e32 v80, v54, v117
	v_fmac_f32_e32 v103, v55, v55
	v_fmac_f32_e32 v73, v55, v238
	v_fmac_f32_e32 v74, v55, v222
	v_fmac_f32_e32 v75, v55, v206
	v_fmac_f32_e32 v76, v55, v190
	v_fmac_f32_e32 v77, v55, v172
	v_fmac_f32_e32 v78, v55, v152
	v_fmac_f32_e32 v79, v55, v136
	v_fmac_f32_e32 v80, v55, v118
	v_fmac_f32_e32 v103, v56, v56
	v_fmac_f32_e32 v73, v56, v239
	v_fmac_f32_e32 v74, v56, v223
	v_fmac_f32_e32 v75, v56, v207
	v_fmac_f32_e32 v76, v56, v191
	v_fmac_f32_e32 v77, v56, v173
	v_fmac_f32_e32 v78, v56, v153
	v_fmac_f32_e32 v79, v56, v137
	v_fmac_f32_e32 v80, v56, v119
	v_lshlrev_b32_e32 v97, 16, v18
	v_and_b32_e32 v159, s40, v18
	v_lshlrev_b32_e32 v187, 16, v19
	v_and_b32_e32 v44, s40, v19
	v_lshlrev_b32_e32 v45, 16, v20
	v_and_b32_e32 v46, s40, v20
	v_lshlrev_b32_e32 v47, 16, v21
	v_and_b32_e32 v48, s40, v21
	v_lshlrev_b32_e32 v49, 16, v22
	v_and_b32_e32 v50, s40, v22
	v_lshlrev_b32_e32 v51, 16, v23
	v_and_b32_e32 v52, s40, v23
	v_lshlrev_b32_e32 v53, 16, v24
	v_and_b32_e32 v54, s40, v24
	v_lshlrev_b32_e32 v55, 16, v25
	v_and_b32_e32 v56, s40, v25
	v_mul_f32_e32 v104, v97, v97
	v_mul_f32_e32 v81, v97, v248
	v_mul_f32_e32 v82, v97, v232
	v_mul_f32_e32 v83, v97, v216
	v_mul_f32_e32 v84, v97, v200
	v_mul_f32_e32 v85, v97, v182
	v_mul_f32_e32 v86, v97, v166
	v_mul_f32_e32 v87, v97, v146
	v_mul_f32_e32 v100, v97, v130
	v_fmac_f32_e32 v104, v159, v159
	v_fmac_f32_e32 v81, v159, v249
	v_fmac_f32_e32 v82, v159, v233
	v_fmac_f32_e32 v83, v159, v217
	v_fmac_f32_e32 v84, v159, v201
	v_fmac_f32_e32 v85, v159, v183
	v_fmac_f32_e32 v86, v159, v167
	v_fmac_f32_e32 v87, v159, v147
	v_fmac_f32_e32 v100, v159, v131
	v_fmac_f32_e32 v104, v187, v187
	v_fmac_f32_e32 v81, v187, v250
	v_fmac_f32_e32 v82, v187, v234
	v_fmac_f32_e32 v83, v187, v218
	v_fmac_f32_e32 v84, v187, v202
	v_fmac_f32_e32 v85, v187, v184
	v_fmac_f32_e32 v86, v187, v168
	v_fmac_f32_e32 v87, v187, v148
	v_fmac_f32_e32 v100, v187, v132
	v_fmac_f32_e32 v104, v44, v44
	v_fmac_f32_e32 v81, v44, v251
	v_fmac_f32_e32 v82, v44, v235
	v_fmac_f32_e32 v83, v44, v219
	v_fmac_f32_e32 v84, v44, v203
	v_fmac_f32_e32 v85, v44, v185
	v_fmac_f32_e32 v86, v44, v169
	v_fmac_f32_e32 v87, v44, v149
	v_fmac_f32_e32 v100, v44, v133
	v_fmac_f32_e32 v104, v45, v45
	v_fmac_f32_e32 v81, v45, v244
	v_fmac_f32_e32 v82, v45, v228
	v_fmac_f32_e32 v83, v45, v212
	v_fmac_f32_e32 v84, v45, v196
	v_fmac_f32_e32 v85, v45, v178
	v_fmac_f32_e32 v86, v45, v162
	v_fmac_f32_e32 v87, v45, v142
	v_fmac_f32_e32 v100, v45, v124
	v_fmac_f32_e32 v104, v46, v46
	v_fmac_f32_e32 v81, v46, v245
	v_fmac_f32_e32 v82, v46, v229
	v_fmac_f32_e32 v83, v46, v213
	v_fmac_f32_e32 v84, v46, v197
	v_fmac_f32_e32 v85, v46, v179
	v_fmac_f32_e32 v86, v46, v163
	v_fmac_f32_e32 v87, v46, v143
	v_fmac_f32_e32 v100, v46, v125
	v_fmac_f32_e32 v104, v47, v47
	v_fmac_f32_e32 v81, v47, v246
	v_fmac_f32_e32 v82, v47, v230
	v_fmac_f32_e32 v83, v47, v214
	v_fmac_f32_e32 v84, v47, v198
	v_fmac_f32_e32 v85, v47, v180
	v_fmac_f32_e32 v86, v47, v164
	v_fmac_f32_e32 v87, v47, v144
	v_fmac_f32_e32 v100, v47, v126
	v_fmac_f32_e32 v104, v48, v48
	v_fmac_f32_e32 v81, v48, v247
	v_fmac_f32_e32 v82, v48, v231
	v_fmac_f32_e32 v83, v48, v215
	v_fmac_f32_e32 v84, v48, v199
	v_fmac_f32_e32 v85, v48, v181
	v_fmac_f32_e32 v86, v48, v165
	v_fmac_f32_e32 v87, v48, v145
	v_fmac_f32_e32 v100, v48, v127
	v_fmac_f32_e32 v104, v49, v49
	v_fmac_f32_e32 v81, v49, v240
	v_fmac_f32_e32 v82, v49, v224
	v_fmac_f32_e32 v83, v49, v208
	v_fmac_f32_e32 v84, v49, v192
	v_fmac_f32_e32 v85, v49, v174
	v_fmac_f32_e32 v86, v49, v154
	v_fmac_f32_e32 v87, v49, v138
	v_fmac_f32_e32 v100, v49, v120
	v_fmac_f32_e32 v104, v50, v50
	v_fmac_f32_e32 v81, v50, v241
	v_fmac_f32_e32 v82, v50, v225
	v_fmac_f32_e32 v83, v50, v209
	v_fmac_f32_e32 v84, v50, v193
	v_fmac_f32_e32 v85, v50, v175
	v_fmac_f32_e32 v86, v50, v155
	v_fmac_f32_e32 v87, v50, v139
	v_fmac_f32_e32 v100, v50, v121
	v_fmac_f32_e32 v104, v51, v51
	v_fmac_f32_e32 v81, v51, v242
	v_fmac_f32_e32 v82, v51, v226
	v_fmac_f32_e32 v83, v51, v210
	v_fmac_f32_e32 v84, v51, v194
	v_fmac_f32_e32 v85, v51, v176
	v_fmac_f32_e32 v86, v51, v156
	v_fmac_f32_e32 v87, v51, v140
	v_fmac_f32_e32 v100, v51, v122
	v_fmac_f32_e32 v104, v52, v52
	v_fmac_f32_e32 v81, v52, v243
	v_fmac_f32_e32 v82, v52, v227
	v_fmac_f32_e32 v83, v52, v211
	v_fmac_f32_e32 v84, v52, v195
	v_fmac_f32_e32 v85, v52, v177
	v_fmac_f32_e32 v86, v52, v157
	v_fmac_f32_e32 v87, v52, v141
	v_fmac_f32_e32 v100, v52, v123
	v_fmac_f32_e32 v104, v53, v53
	v_fmac_f32_e32 v81, v53, v236
	v_fmac_f32_e32 v82, v53, v220
	v_fmac_f32_e32 v83, v53, v204
	v_fmac_f32_e32 v84, v53, v188
; __device__ __forceinline__ float lane_get(float v, int src_lane) { return __builtin_bit_cast(float, __builtin_amdgcn_ds_bpermute(src_lane << 2, __builtin_bit_cast(int, v))); }
; __device__ __forceinline__ void fgate_phase(const bfr* x, const float* wf, const float* bfg, float* cl, float* ctot, LAS float* scr, int bx, int G, int tid, int lane, int wave) {
;     ...
;         for (int j = 0; j < 8; j += 2) { const int row = chunk * 64 + wave * 8 + j; typedef unsigned u32x2 __attribute__((ext_vector_type(2))); const u32x2* xa = (const u32x2*)(x + (size_t)row * D) + lane; const u32x2* xb2 = xa + D / 4; f32x4 va[4], vb[4]; float r[18]; int zo = 0; asm volatile("" : "+v"(zo));
; #pragma unroll
;             for (int jj = 0; jj < 4; ++jj) { const u32x2 wa = xa[64 * jj], wb = xb2[64 * jj]; va[jj] = (f32x4){bf_lo(wa.x), bf_hi(wa.x), bf_lo(wa.y), bf_hi(wa.y)}; vb[jj] = (f32x4){bf_lo(wb.x), bf_hi(wb.x), bf_lo(wb.y), bf_hi(wb.y)}; }
;             r[16] = 0.f; r[17] = 0.f;
; #pragma unroll
;             for (int jj = 0; jj < 4; ++jj) { r[16] += (va[jj].x * va[jj].x + va[jj].y * va[jj].y) + (va[jj].z * va[jj].z + va[jj].w * va[jj].w); r[17] += (vb[jj].x * vb[jj].x + vb[jj].y * vb[jj].y) + (vb[jj].z * vb[jj].z + vb[jj].w * vb[jj].w); }
; #pragma unroll
;             for (int h = 0; h < NH; ++h) { const f32x4* wr = (const f32x4*)(wf + h * D) + lane + zo; float da = 0.f, db = 0.f;
; #pragma unroll
;                 for (int jj = 0; jj < 4; ++jj) { const f32x4 w = wr[64 * jj]; da += (va[jj].x * w.x + va[jj].y * w.y) + (va[jj].z * w.z + va[jj].w * w.w); db += (vb[jj].x * w.x + vb[jj].y * w.y) + (vb[jj].z * w.z + vb[jj].w * w.w); }
;                 r[h] = da; r[8 + h] = db; }
; #pragma unroll
;             for (int o = 1; o < 64; o <<= 1) {
; #pragma unroll
;                 for (int q = 0; q < 18; ++q) r[q] += lane_get(r[q], lane ^ o); }
	v_fmac_f32_e32 v85, v53, v170
	v_fmac_f32_e32 v86, v53, v150
	v_fmac_f32_e32 v87, v53, v134
	v_fmac_f32_e32 v100, v53, v116
	v_fmac_f32_e32 v104, v54, v54
	v_fmac_f32_e32 v81, v54, v237
	v_fmac_f32_e32 v82, v54, v221
	v_fmac_f32_e32 v83, v54, v205
	v_fmac_f32_e32 v84, v54, v189
	v_fmac_f32_e32 v85, v54, v171
	v_fmac_f32_e32 v86, v54, v151
	v_fmac_f32_e32 v87, v54, v135
	v_fmac_f32_e32 v100, v54, v117
	v_fmac_f32_e32 v104, v55, v55
	v_fmac_f32_e32 v81, v55, v238
	v_fmac_f32_e32 v82, v55, v222
	v_fmac_f32_e32 v83, v55, v206
	v_fmac_f32_e32 v84, v55, v190
	v_fmac_f32_e32 v85, v55, v172
	v_fmac_f32_e32 v86, v55, v152
	v_fmac_f32_e32 v87, v55, v136
	v_fmac_f32_e32 v100, v55, v118
	v_fmac_f32_e32 v104, v56, v56
	v_fmac_f32_e32 v81, v56, v239
	v_fmac_f32_e32 v82, v56, v223
	v_fmac_f32_e32 v83, v56, v207
	v_fmac_f32_e32 v84, v56, v191
	v_fmac_f32_e32 v85, v56, v173
	v_fmac_f32_e32 v86, v56, v153
	v_fmac_f32_e32 v87, v56, v137
	v_fmac_f32_e32 v100, v56, v119
	v_lshl_add_u64 v[26:27], v[26:27], 0, s[100:101]
	v_lshl_add_u64 v[40:41], v[40:41], 0, s[100:101]
	global_load_dwordx2 v[38:39], v[26:27], off
	global_load_dwordx2 v[98:99], v[26:27], off offset:512
	global_load_dwordx2 v[160:161], v[26:27], off offset:1024
	global_load_dwordx2 v[0:1], v[26:27], off offset:1536
	global_load_dwordx2 v[2:3], v[26:27], off offset:2048
	global_load_dwordx2 v[4:5], v[26:27], off offset:2560
	global_load_dwordx2 v[6:7], v[26:27], off offset:3072
	global_load_dwordx2 v[8:9], v[26:27], off offset:3584
	global_load_dwordx2 v[10:11], v[40:41], off
	global_load_dwordx2 v[12:13], v[40:41], off offset:512
	global_load_dwordx2 v[14:15], v[40:41], off offset:1024
	global_load_dwordx2 v[16:17], v[40:41], off offset:1536
	global_load_dwordx2 v[18:19], v[40:41], off offset:2048
	global_load_dwordx2 v[20:21], v[40:41], off offset:2560
	global_load_dwordx2 v[22:23], v[40:41], off offset:3072
	global_load_dwordx2 v[24:25], v[40:41], off offset:3584
	s_nop 1
	v_permlane32_swap_b32_e32 v57, v73
	v_permlane32_swap_b32_e32 v58, v74
	v_permlane32_swap_b32_e32 v59, v75
	v_permlane32_swap_b32_e32 v60, v76
	v_permlane32_swap_b32_e32 v61, v77
	v_permlane32_swap_b32_e32 v62, v78
	v_permlane32_swap_b32_e32 v63, v79
	v_permlane32_swap_b32_e32 v64, v80
	v_permlane32_swap_b32_e32 v65, v81
	v_permlane32_swap_b32_e32 v66, v82
	v_permlane32_swap_b32_e32 v67, v83
	v_permlane32_swap_b32_e32 v68, v84
	v_permlane32_swap_b32_e32 v69, v85
	v_permlane32_swap_b32_e32 v70, v86
	v_permlane32_swap_b32_e32 v71, v87
	v_permlane32_swap_b32_e32 v72, v100
	v_permlane32_swap_b32_e32 v101, v103
	v_permlane32_swap_b32_e32 v102, v104
	s_nop 1
	v_add_f32_e32 v57, v57, v73
	v_add_f32_e32 v58, v58, v74
	v_add_f32_e32 v59, v59, v75
	v_add_f32_e32 v60, v60, v76
	v_add_f32_e32 v61, v61, v77
	v_add_f32_e32 v62, v62, v78
	v_add_f32_e32 v63, v63, v79
	v_add_f32_e32 v64, v64, v80
	v_add_f32_e32 v65, v65, v81
	v_add_f32_e32 v66, v66, v82
	v_add_f32_e32 v67, v67, v83
	v_add_f32_e32 v68, v68, v84
	v_add_f32_e32 v69, v69, v85
	v_add_f32_e32 v70, v70, v86
	v_add_f32_e32 v71, v71, v87
	v_add_f32_e32 v72, v72, v100
	v_add_f32_e32 v101, v101, v103
	v_add_f32_e32 v102, v102, v104
	s_nop 1
	v_permlane16_swap_b32_e32 v57, v65
	v_permlane16_swap_b32_e32 v58, v66
	v_permlane16_swap_b32_e32 v59, v67
	v_permlane16_swap_b32_e32 v60, v68
	v_permlane16_swap_b32_e32 v61, v69
	v_permlane16_swap_b32_e32 v62, v70
	v_permlane16_swap_b32_e32 v63, v71
	v_permlane16_swap_b32_e32 v64, v72
	v_permlane16_swap_b32_e32 v101, v102
	s_nop 1
	v_add_f32_e32 v57, v57, v65
	v_add_f32_e32 v58, v58, v66
	v_add_f32_e32 v59, v59, v67
	v_add_f32_e32 v60, v60, v68
	v_add_f32_e32 v61, v61, v69
	v_add_f32_e32 v62, v62, v70
	v_add_f32_e32 v63, v63, v71
	v_add_f32_e32 v64, v64, v72
	v_add_f32_e32 v101, v101, v102
	s_nop 1
	v_add_f32_dpp v57, v57, v57 quad_perm:[1,0,3,2] row_mask:0xf bank_mask:0xf
	v_add_f32_dpp v58, v58, v58 quad_perm:[1,0,3,2] row_mask:0xf bank_mask:0xf
	v_add_f32_dpp v59, v59, v59 quad_perm:[1,0,3,2] row_mask:0xf bank_mask:0xf
	v_add_f32_dpp v60, v60, v60 quad_perm:[1,0,3,2] row_mask:0xf bank_mask:0xf
	v_add_f32_dpp v61, v61, v61 quad_perm:[1,0,3,2] row_mask:0xf bank_mask:0xf
	v_add_f32_dpp v62, v62, v62 quad_perm:[1,0,3,2] row_mask:0xf bank_mask:0xf
	v_add_f32_dpp v63, v63, v63 quad_perm:[1,0,3,2] row_mask:0xf bank_mask:0xf
	v_add_f32_dpp v64, v64, v64 quad_perm:[1,0,3,2] row_mask:0xf bank_mask:0xf
	v_add_f32_dpp v101, v101, v101 quad_perm:[1,0,3,2] row_mask:0xf bank_mask:0xf
	s_nop 1
	v_add_f32_dpp v57, v57, v57 quad_perm:[2,3,0,1] row_mask:0xf bank_mask:0xf
	v_add_f32_dpp v58, v58, v58 quad_perm:[2,3,0,1] row_mask:0xf bank_mask:0xf
	v_add_f32_dpp v59, v59, v59 quad_perm:[2,3,0,1] row_mask:0xf bank_mask:0xf
	v_add_f32_dpp v60, v60, v60 quad_perm:[2,3,0,1] row_mask:0xf bank_mask:0xf
	v_add_f32_dpp v61, v61, v61 quad_perm:[2,3,0,1] row_mask:0xf bank_mask:0xf
	v_add_f32_dpp v62, v62, v62 quad_perm:[2,3,0,1] row_mask:0xf bank_mask:0xf
	v_add_f32_dpp v63, v63, v63 quad_perm:[2,3,0,1] row_mask:0xf bank_mask:0xf
	v_add_f32_dpp v64, v64, v64 quad_perm:[2,3,0,1] row_mask:0xf bank_mask:0xf
	v_add_f32_dpp v101, v101, v101 quad_perm:[2,3,0,1] row_mask:0xf bank_mask:0xf
	s_nop 1
	v_add_f32_dpp v57, v57, v57 row_half_mirror row_mask:0xf bank_mask:0xf
	v_add_f32_dpp v58, v58, v58 row_half_mirror row_mask:0xf bank_mask:0xf
	v_add_f32_dpp v59, v59, v59 row_half_mirror row_mask:0xf bank_mask:0xf
	v_add_f32_dpp v60, v60, v60 row_half_mirror row_mask:0xf bank_mask:0xf
	v_add_f32_dpp v61, v61, v61 row_half_mirror row_mask:0xf bank_mask:0xf
	v_add_f32_dpp v62, v62, v62 row_half_mirror row_mask:0xf bank_mask:0xf
	v_add_f32_dpp v63, v63, v63 row_half_mirror row_mask:0xf bank_mask:0xf
; __device__ __forceinline__ float lane_get(float v, int src_lane) { return __builtin_bit_cast(float, __builtin_amdgcn_ds_bpermute(src_lane << 2, __builtin_bit_cast(int, v))); }
; __device__ __forceinline__ void fgate_phase(const bfr* x, const float* wf, const float* bfg, float* cl, float* ctot, LAS float* scr, int bx, int G, int tid, int lane, int wave) {
;     ...
;             for (int jj = 0; jj < 4; ++jj) { r[16] += (va[jj].x * va[jj].x + va[jj].y * va[jj].y) + (va[jj].z * va[jj].z + va[jj].w * va[jj].w); r[17] += (vb[jj].x * vb[jj].x + vb[jj].y * vb[jj].y) + (vb[jj].z * vb[jj].z + vb[jj].w * vb[jj].w); }
; #pragma unroll
;             for (int h = 0; h < NH; ++h) { const f32x4* wr = (const f32x4*)(wf + h * D) + lane + zo; float da = 0.f, db = 0.f;
; #pragma unroll
;                 for (int jj = 0; jj < 4; ++jj) { const f32x4 w = wr[64 * jj]; da += (va[jj].x * w.x + va[jj].y * w.y) + (va[jj].z * w.z + va[jj].w * w.w); db += (vb[jj].x * w.x + vb[jj].y * w.y) + (vb[jj].z * w.z + vb[jj].w * w.w); }
;                 r[h] = da; r[8 + h] = db; }
;     ...
;             for (int o = 1; o < 64; o <<= 1) {
; #pragma unroll
;                 for (int q = 0; q < 18; ++q) r[q] += lane_get(r[q], lane ^ o); }
;             const float rsa = rsqrtf(r[16] * (1.f / D) + EPS), rsb = rsqrtf(r[17] * (1.f / D) + EPS);
;             if (lane < 16) { const int h = lane & 7; float dsel = r[0];
; #pragma unroll
;                 for (int q = 1; q < 16; ++q) dsel = (lane == q) ? r[q] : dsel;
;                 const float zz = dsel * (lane < 8 ? rsa : rsb) + bfg[h]; const float lf = fminf(zz, 0.f) - 0.6931471805599453f * __builtin_amdgcn_logf(1.0f + __builtin_amdgcn_exp2f(-LOG2E * fabsf(zz)));
;                 scr[(wave * 8 + j + (lane >> 3)) * 8 + h] = lf; } }
	v_add_f32_dpp v64, v64, v64 row_half_mirror row_mask:0xf bank_mask:0xf
	v_add_f32_dpp v101, v101, v101 row_half_mirror row_mask:0xf bank_mask:0xf
	s_nop 1
	v_add_f32_dpp v57, v57, v57 row_mirror row_mask:0xf bank_mask:0xf
	v_add_f32_dpp v58, v58, v58 row_mirror row_mask:0xf bank_mask:0xf
	v_add_f32_dpp v59, v59, v59 row_mirror row_mask:0xf bank_mask:0xf
	v_add_f32_dpp v60, v60, v60 row_mirror row_mask:0xf bank_mask:0xf
	v_add_f32_dpp v61, v61, v61 row_mirror row_mask:0xf bank_mask:0xf
	v_add_f32_dpp v62, v62, v62 row_mirror row_mask:0xf bank_mask:0xf
	v_add_f32_dpp v63, v63, v63 row_mirror row_mask:0xf bank_mask:0xf
	v_add_f32_dpp v64, v64, v64 row_mirror row_mask:0xf bank_mask:0xf
	v_add_f32_dpp v101, v101, v101 row_mirror row_mask:0xf bank_mask:0xf
	s_nop 1
	v_mov_b32_e32 v106, v57
	v_cndmask_b32_e64 v106, v106, v58, s[6:7]
	v_cndmask_b32_e64 v106, v106, v59, s[8:9]
	v_cndmask_b32_e64 v106, v106, v60, s[10:11]
	v_cndmask_b32_e64 v106, v106, v61, s[12:13]
	v_cndmask_b32_e64 v106, v106, v62, s[14:15]
	v_cndmask_b32_e64 v106, v106, v63, s[16:17]
	v_cndmask_b32_e64 v106, v106, v64, s[18:19]
	v_mul_f32_e32 v107, 0x3a800000, v101
	v_add_f32_e32 v107, 0x358637bd, v107
	v_rsq_f32_e32 v107, v107
	s_nop 0
	v_fma_f32 v106, v106, v107, v105
	v_mul_f32_e64 v107, |v106|, s65
	v_exp_f32_e32 v107, v107
	v_min_f32_e32 v106, 0, v106
	v_add_f32_e32 v107, 1.0, v107
	v_log_f32_e32 v107, v107
	s_nop 0
	v_fmac_f32_e32 v106, 0xbf317218, v107
	s_mov_b64 s[54:55], exec
	s_mov_b32 exec_lo, 0xff00ff
	s_mov_b32 exec_hi, 0xff00ff
	ds_write_b32 v109, v106
	s_mov_b64 exec, s[54:55]
	s_waitcnt vmcnt(0)
	v_lshlrev_b32_e32 v97, 16, v38
	v_and_b32_e32 v159, s40, v38
	v_lshlrev_b32_e32 v187, 16, v39
	v_and_b32_e32 v44, s40, v39
	v_lshlrev_b32_e32 v45, 16, v98
	v_and_b32_e32 v46, s40, v98
	v_lshlrev_b32_e32 v47, 16, v99
	v_and_b32_e32 v48, s40, v99
	v_lshlrev_b32_e32 v49, 16, v160
	v_and_b32_e32 v50, s40, v160
	v_lshlrev_b32_e32 v51, 16, v161
	v_and_b32_e32 v52, s40, v161
	v_lshlrev_b32_e32 v53, 16, v0
	v_and_b32_e32 v54, s40, v0
	v_lshlrev_b32_e32 v55, 16, v1
	v_and_b32_e32 v56, s40, v1
	v_mul_f32_e32 v101, v97, v97
	v_mul_f32_e32 v57, v97, v248
	v_mul_f32_e32 v58, v97, v232
	v_mul_f32_e32 v59, v97, v216
	v_mul_f32_e32 v60, v97, v200
	v_mul_f32_e32 v61, v97, v182
	v_mul_f32_e32 v62, v97, v166
	v_mul_f32_e32 v63, v97, v146
	v_mul_f32_e32 v64, v97, v130
	v_fmac_f32_e32 v101, v159, v159
	v_fmac_f32_e32 v57, v159, v249
	v_fmac_f32_e32 v58, v159, v233
	v_fmac_f32_e32 v59, v159, v217
	v_fmac_f32_e32 v60, v159, v201
	v_fmac_f32_e32 v61, v159, v183
	v_fmac_f32_e32 v62, v159, v167
	v_fmac_f32_e32 v63, v159, v147
	v_fmac_f32_e32 v64, v159, v131
	v_fmac_f32_e32 v101, v187, v187
	v_fmac_f32_e32 v57, v187, v250
	v_fmac_f32_e32 v58, v187, v234
	v_fmac_f32_e32 v59, v187, v218
	v_fmac_f32_e32 v60, v187, v202
	v_fmac_f32_e32 v61, v187, v184
	v_fmac_f32_e32 v62, v187, v168
	v_fmac_f32_e32 v63, v187, v148
	v_fmac_f32_e32 v64, v187, v132
	v_fmac_f32_e32 v101, v44, v44
	v_fmac_f32_e32 v57, v44, v251
	v_fmac_f32_e32 v58, v44, v235
	v_fmac_f32_e32 v59, v44, v219
	v_fmac_f32_e32 v60, v44, v203
	v_fmac_f32_e32 v61, v44, v185
	v_fmac_f32_e32 v62, v44, v169
	v_fmac_f32_e32 v63, v44, v149
	v_fmac_f32_e32 v64, v44, v133
	v_fmac_f32_e32 v101, v45, v45
	v_fmac_f32_e32 v57, v45, v244
	v_fmac_f32_e32 v58, v45, v228
	v_fmac_f32_e32 v59, v45, v212
	v_fmac_f32_e32 v60, v45, v196
	v_fmac_f32_e32 v61, v45, v178
	v_fmac_f32_e32 v62, v45, v162
	v_fmac_f32_e32 v63, v45, v142
	v_fmac_f32_e32 v64, v45, v124
	v_fmac_f32_e32 v101, v46, v46
	v_fmac_f32_e32 v57, v46, v245
	v_fmac_f32_e32 v58, v46, v229
	v_fmac_f32_e32 v59, v46, v213
	v_fmac_f32_e32 v60, v46, v197
	v_fmac_f32_e32 v61, v46, v179
	v_fmac_f32_e32 v62, v46, v163
	v_fmac_f32_e32 v63, v46, v143
	v_fmac_f32_e32 v64, v46, v125
	v_fmac_f32_e32 v101, v47, v47
	v_fmac_f32_e32 v57, v47, v246
	v_fmac_f32_e32 v58, v47, v230
	v_fmac_f32_e32 v59, v47, v214
	v_fmac_f32_e32 v60, v47, v198
	v_fmac_f32_e32 v61, v47, v180
	v_fmac_f32_e32 v62, v47, v164
	v_fmac_f32_e32 v63, v47, v144
	v_fmac_f32_e32 v64, v47, v126
	v_fmac_f32_e32 v101, v48, v48
	v_fmac_f32_e32 v57, v48, v247
	v_fmac_f32_e32 v58, v48, v231
	v_fmac_f32_e32 v59, v48, v215
	v_fmac_f32_e32 v60, v48, v199
	v_fmac_f32_e32 v61, v48, v181
	v_fmac_f32_e32 v62, v48, v165
	v_fmac_f32_e32 v63, v48, v145
	v_fmac_f32_e32 v64, v48, v127
	v_fmac_f32_e32 v101, v49, v49
	v_fmac_f32_e32 v57, v49, v240
	v_fmac_f32_e32 v58, v49, v224
	v_fmac_f32_e32 v59, v49, v208
	v_fmac_f32_e32 v60, v49, v192
	v_fmac_f32_e32 v61, v49, v174
	v_fmac_f32_e32 v62, v49, v154
	v_fmac_f32_e32 v63, v49, v138
	v_fmac_f32_e32 v64, v49, v120
	v_fmac_f32_e32 v101, v50, v50
	v_fmac_f32_e32 v57, v50, v241
	v_fmac_f32_e32 v58, v50, v225
	v_fmac_f32_e32 v59, v50, v209
	v_fmac_f32_e32 v60, v50, v193
	v_fmac_f32_e32 v61, v50, v175
	v_fmac_f32_e32 v62, v50, v155
	v_fmac_f32_e32 v63, v50, v139
	v_fmac_f32_e32 v64, v50, v121
	v_fmac_f32_e32 v101, v51, v51
	v_fmac_f32_e32 v57, v51, v242
	v_fmac_f32_e32 v58, v51, v226
	v_fmac_f32_e32 v59, v51, v210
	v_fmac_f32_e32 v60, v51, v194
	v_fmac_f32_e32 v61, v51, v176
	v_fmac_f32_e32 v62, v51, v156
	v_fmac_f32_e32 v63, v51, v140
	v_fmac_f32_e32 v64, v51, v122
	v_fmac_f32_e32 v101, v52, v52
	v_fmac_f32_e32 v57, v52, v243
	v_fmac_f32_e32 v58, v52, v227
	v_fmac_f32_e32 v59, v52, v211
	v_fmac_f32_e32 v60, v52, v195
	v_fmac_f32_e32 v61, v52, v177
	v_fmac_f32_e32 v62, v52, v157
	v_fmac_f32_e32 v63, v52, v141
	v_fmac_f32_e32 v64, v52, v123
	v_fmac_f32_e32 v101, v53, v53
	v_fmac_f32_e32 v57, v53, v236
	v_fmac_f32_e32 v58, v53, v220
	v_fmac_f32_e32 v59, v53, v204
	v_fmac_f32_e32 v60, v53, v188
	v_fmac_f32_e32 v61, v53, v170
; __device__ __forceinline__ void fgate_phase(const bfr* x, const float* wf, const float* bfg, float* cl, float* ctot, LAS float* scr, int bx, int G, int tid, int lane, int wave) {
;     ...
;             for (int jj = 0; jj < 4; ++jj) { r[16] += (va[jj].x * va[jj].x + va[jj].y * va[jj].y) + (va[jj].z * va[jj].z + va[jj].w * va[jj].w); r[17] += (vb[jj].x * vb[jj].x + vb[jj].y * vb[jj].y) + (vb[jj].z * vb[jj].z + vb[jj].w * vb[jj].w); }
; #pragma unroll
;             for (int h = 0; h < NH; ++h) { const f32x4* wr = (const f32x4*)(wf + h * D) + lane + zo; float da = 0.f, db = 0.f;
; #pragma unroll
;                 for (int jj = 0; jj < 4; ++jj) { const f32x4 w = wr[64 * jj]; da += (va[jj].x * w.x + va[jj].y * w.y) + (va[jj].z * w.z + va[jj].w * w.w); db += (vb[jj].x * w.x + vb[jj].y * w.y) + (vb[jj].z * w.z + vb[jj].w * w.w); }
;                 r[h] = da; r[8 + h] = db; }
	v_fmac_f32_e32 v62, v53, v150
	v_fmac_f32_e32 v63, v53, v134
	v_fmac_f32_e32 v64, v53, v116
	v_fmac_f32_e32 v101, v54, v54
	v_fmac_f32_e32 v57, v54, v237
	v_fmac_f32_e32 v58, v54, v221
	v_fmac_f32_e32 v59, v54, v205
	v_fmac_f32_e32 v60, v54, v189
	v_fmac_f32_e32 v61, v54, v171
	v_fmac_f32_e32 v62, v54, v151
	v_fmac_f32_e32 v63, v54, v135
	v_fmac_f32_e32 v64, v54, v117
	v_fmac_f32_e32 v101, v55, v55
	v_fmac_f32_e32 v57, v55, v238
	v_fmac_f32_e32 v58, v55, v222
	v_fmac_f32_e32 v59, v55, v206
	v_fmac_f32_e32 v60, v55, v190
	v_fmac_f32_e32 v61, v55, v172
	v_fmac_f32_e32 v62, v55, v152
	v_fmac_f32_e32 v63, v55, v136
	v_fmac_f32_e32 v64, v55, v118
	v_fmac_f32_e32 v101, v56, v56
	v_fmac_f32_e32 v57, v56, v239
	v_fmac_f32_e32 v58, v56, v223
	v_fmac_f32_e32 v59, v56, v207
	v_fmac_f32_e32 v60, v56, v191
	v_fmac_f32_e32 v61, v56, v173
	v_fmac_f32_e32 v62, v56, v153
	v_fmac_f32_e32 v63, v56, v137
	v_fmac_f32_e32 v64, v56, v119
	v_lshlrev_b32_e32 v97, 16, v2
	v_and_b32_e32 v159, s40, v2
	v_lshlrev_b32_e32 v187, 16, v3
	v_and_b32_e32 v44, s40, v3
	v_lshlrev_b32_e32 v45, 16, v4
	v_and_b32_e32 v46, s40, v4
	v_lshlrev_b32_e32 v47, 16, v5
	v_and_b32_e32 v48, s40, v5
	v_lshlrev_b32_e32 v49, 16, v6
	v_and_b32_e32 v50, s40, v6
	v_lshlrev_b32_e32 v51, 16, v7
	v_and_b32_e32 v52, s40, v7
	v_lshlrev_b32_e32 v53, 16, v8
	v_and_b32_e32 v54, s40, v8
	v_lshlrev_b32_e32 v55, 16, v9
	v_and_b32_e32 v56, s40, v9
	v_mul_f32_e32 v102, v97, v97
	v_mul_f32_e32 v65, v97, v248
	v_mul_f32_e32 v66, v97, v232
	v_mul_f32_e32 v67, v97, v216
	v_mul_f32_e32 v68, v97, v200
	v_mul_f32_e32 v69, v97, v182
	v_mul_f32_e32 v70, v97, v166
	v_mul_f32_e32 v71, v97, v146
	v_mul_f32_e32 v72, v97, v130
	v_fmac_f32_e32 v102, v159, v159
	v_fmac_f32_e32 v65, v159, v249
	v_fmac_f32_e32 v66, v159, v233
	v_fmac_f32_e32 v67, v159, v217
	v_fmac_f32_e32 v68, v159, v201
	v_fmac_f32_e32 v69, v159, v183
	v_fmac_f32_e32 v70, v159, v167
	v_fmac_f32_e32 v71, v159, v147
	v_fmac_f32_e32 v72, v159, v131
	v_fmac_f32_e32 v102, v187, v187
	v_fmac_f32_e32 v65, v187, v250
	v_fmac_f32_e32 v66, v187, v234
	v_fmac_f32_e32 v67, v187, v218
	v_fmac_f32_e32 v68, v187, v202
	v_fmac_f32_e32 v69, v187, v184
	v_fmac_f32_e32 v70, v187, v168
	v_fmac_f32_e32 v71, v187, v148
	v_fmac_f32_e32 v72, v187, v132
	v_fmac_f32_e32 v102, v44, v44
	v_fmac_f32_e32 v65, v44, v251
	v_fmac_f32_e32 v66, v44, v235
	v_fmac_f32_e32 v67, v44, v219
	v_fmac_f32_e32 v68, v44, v203
	v_fmac_f32_e32 v69, v44, v185
	v_fmac_f32_e32 v70, v44, v169
	v_fmac_f32_e32 v71, v44, v149
	v_fmac_f32_e32 v72, v44, v133
	v_fmac_f32_e32 v102, v45, v45
	v_fmac_f32_e32 v65, v45, v244
	v_fmac_f32_e32 v66, v45, v228
	v_fmac_f32_e32 v67, v45, v212
	v_fmac_f32_e32 v68, v45, v196
	v_fmac_f32_e32 v69, v45, v178
	v_fmac_f32_e32 v70, v45, v162
	v_fmac_f32_e32 v71, v45, v142
	v_fmac_f32_e32 v72, v45, v124
	v_fmac_f32_e32 v102, v46, v46
	v_fmac_f32_e32 v65, v46, v245
	v_fmac_f32_e32 v66, v46, v229
	v_fmac_f32_e32 v67, v46, v213
	v_fmac_f32_e32 v68, v46, v197
	v_fmac_f32_e32 v69, v46, v179
	v_fmac_f32_e32 v70, v46, v163
	v_fmac_f32_e32 v71, v46, v143
	v_fmac_f32_e32 v72, v46, v125
	v_fmac_f32_e32 v102, v47, v47
	v_fmac_f32_e32 v65, v47, v246
	v_fmac_f32_e32 v66, v47, v230
	v_fmac_f32_e32 v67, v47, v214
	v_fmac_f32_e32 v68, v47, v198
	v_fmac_f32_e32 v69, v47, v180
	v_fmac_f32_e32 v70, v47, v164
	v_fmac_f32_e32 v71, v47, v144
	v_fmac_f32_e32 v72, v47, v126
	v_fmac_f32_e32 v102, v48, v48
	v_fmac_f32_e32 v65, v48, v247
	v_fmac_f32_e32 v66, v48, v231
	v_fmac_f32_e32 v67, v48, v215
	v_fmac_f32_e32 v68, v48, v199
	v_fmac_f32_e32 v69, v48, v181
	v_fmac_f32_e32 v70, v48, v165
	v_fmac_f32_e32 v71, v48, v145
	v_fmac_f32_e32 v72, v48, v127
	v_fmac_f32_e32 v102, v49, v49
	v_fmac_f32_e32 v65, v49, v240
	v_fmac_f32_e32 v66, v49, v224
	v_fmac_f32_e32 v67, v49, v208
	v_fmac_f32_e32 v68, v49, v192
	v_fmac_f32_e32 v69, v49, v174
	v_fmac_f32_e32 v70, v49, v154
	v_fmac_f32_e32 v71, v49, v138
	v_fmac_f32_e32 v72, v49, v120
	v_fmac_f32_e32 v102, v50, v50
	v_fmac_f32_e32 v65, v50, v241
	v_fmac_f32_e32 v66, v50, v225
	v_fmac_f32_e32 v67, v50, v209
	v_fmac_f32_e32 v68, v50, v193
	v_fmac_f32_e32 v69, v50, v175
	v_fmac_f32_e32 v70, v50, v155
	v_fmac_f32_e32 v71, v50, v139
	v_fmac_f32_e32 v72, v50, v121
	v_fmac_f32_e32 v102, v51, v51
	v_fmac_f32_e32 v65, v51, v242
	v_fmac_f32_e32 v66, v51, v226
	v_fmac_f32_e32 v67, v51, v210
	v_fmac_f32_e32 v68, v51, v194
	v_fmac_f32_e32 v69, v51, v176
	v_fmac_f32_e32 v70, v51, v156
	v_fmac_f32_e32 v71, v51, v140
	v_fmac_f32_e32 v72, v51, v122
	v_fmac_f32_e32 v102, v52, v52
	v_fmac_f32_e32 v65, v52, v243
	v_fmac_f32_e32 v66, v52, v227
	v_fmac_f32_e32 v67, v52, v211
	v_fmac_f32_e32 v68, v52, v195
	v_fmac_f32_e32 v69, v52, v177
	v_fmac_f32_e32 v70, v52, v157
	v_fmac_f32_e32 v71, v52, v141
	v_fmac_f32_e32 v72, v52, v123
	v_fmac_f32_e32 v102, v53, v53
	v_fmac_f32_e32 v65, v53, v236
	v_fmac_f32_e32 v66, v53, v220
	v_fmac_f32_e32 v67, v53, v204
	v_fmac_f32_e32 v68, v53, v188
	v_fmac_f32_e32 v69, v53, v170
	v_fmac_f32_e32 v70, v53, v150
	v_fmac_f32_e32 v71, v53, v134
	v_fmac_f32_e32 v72, v53, v116
	v_fmac_f32_e32 v102, v54, v54
	v_fmac_f32_e32 v65, v54, v237
	v_fmac_f32_e32 v66, v54, v221
	v_fmac_f32_e32 v67, v54, v205
	v_fmac_f32_e32 v68, v54, v189
	v_fmac_f32_e32 v69, v54, v171
	v_fmac_f32_e32 v70, v54, v151
	v_fmac_f32_e32 v71, v54, v135
	v_fmac_f32_e32 v72, v54, v117
	v_fmac_f32_e32 v102, v55, v55
	v_fmac_f32_e32 v65, v55, v238
	v_fmac_f32_e32 v66, v55, v222
	v_fmac_f32_e32 v67, v55, v206
	v_fmac_f32_e32 v68, v55, v190
	v_fmac_f32_e32 v69, v55, v172
	v_fmac_f32_e32 v70, v55, v152
	v_fmac_f32_e32 v71, v55, v136
	v_fmac_f32_e32 v72, v55, v118
	v_fmac_f32_e32 v102, v56, v56
; __device__ __forceinline__ void fgate_phase(const bfr* x, const float* wf, const float* bfg, float* cl, float* ctot, LAS float* scr, int bx, int G, int tid, int lane, int wave) {
;     ...
;             for (int jj = 0; jj < 4; ++jj) { r[16] += (va[jj].x * va[jj].x + va[jj].y * va[jj].y) + (va[jj].z * va[jj].z + va[jj].w * va[jj].w); r[17] += (vb[jj].x * vb[jj].x + vb[jj].y * vb[jj].y) + (vb[jj].z * vb[jj].z + vb[jj].w * vb[jj].w); }
; #pragma unroll
;             for (int h = 0; h < NH; ++h) { const f32x4* wr = (const f32x4*)(wf + h * D) + lane + zo; float da = 0.f, db = 0.f;
; #pragma unroll
;                 for (int jj = 0; jj < 4; ++jj) { const f32x4 w = wr[64 * jj]; da += (va[jj].x * w.x + va[jj].y * w.y) + (va[jj].z * w.z + va[jj].w * w.w); db += (vb[jj].x * w.x + vb[jj].y * w.y) + (vb[jj].z * w.z + vb[jj].w * w.w); }
;                 r[h] = da; r[8 + h] = db; }
	v_fmac_f32_e32 v65, v56, v239
	v_fmac_f32_e32 v66, v56, v223
	v_fmac_f32_e32 v67, v56, v207
	v_fmac_f32_e32 v68, v56, v191
	v_fmac_f32_e32 v69, v56, v173
	v_fmac_f32_e32 v70, v56, v153
	v_fmac_f32_e32 v71, v56, v137
	v_fmac_f32_e32 v72, v56, v119
	v_lshlrev_b32_e32 v97, 16, v10
	v_and_b32_e32 v159, s40, v10
	v_lshlrev_b32_e32 v187, 16, v11
	v_and_b32_e32 v44, s40, v11
	v_lshlrev_b32_e32 v45, 16, v12
	v_and_b32_e32 v46, s40, v12
	v_lshlrev_b32_e32 v47, 16, v13
	v_and_b32_e32 v48, s40, v13
	v_lshlrev_b32_e32 v49, 16, v14
	v_and_b32_e32 v50, s40, v14
	v_lshlrev_b32_e32 v51, 16, v15
	v_and_b32_e32 v52, s40, v15
	v_lshlrev_b32_e32 v53, 16, v16
	v_and_b32_e32 v54, s40, v16
	v_lshlrev_b32_e32 v55, 16, v17
	v_and_b32_e32 v56, s40, v17
	v_mul_f32_e32 v103, v97, v97
	v_mul_f32_e32 v73, v97, v248
	v_mul_f32_e32 v74, v97, v232
	v_mul_f32_e32 v75, v97, v216
	v_mul_f32_e32 v76, v97, v200
	v_mul_f32_e32 v77, v97, v182
	v_mul_f32_e32 v78, v97, v166
	v_mul_f32_e32 v79, v97, v146
	v_mul_f32_e32 v80, v97, v130
	v_fmac_f32_e32 v103, v159, v159
	v_fmac_f32_e32 v73, v159, v249
	v_fmac_f32_e32 v74, v159, v233
	v_fmac_f32_e32 v75, v159, v217
	v_fmac_f32_e32 v76, v159, v201
	v_fmac_f32_e32 v77, v159, v183
	v_fmac_f32_e32 v78, v159, v167
	v_fmac_f32_e32 v79, v159, v147
	v_fmac_f32_e32 v80, v159, v131
	v_fmac_f32_e32 v103, v187, v187
	v_fmac_f32_e32 v73, v187, v250
	v_fmac_f32_e32 v74, v187, v234
	v_fmac_f32_e32 v75, v187, v218
	v_fmac_f32_e32 v76, v187, v202
	v_fmac_f32_e32 v77, v187, v184
	v_fmac_f32_e32 v78, v187, v168
	v_fmac_f32_e32 v79, v187, v148
	v_fmac_f32_e32 v80, v187, v132
	v_fmac_f32_e32 v103, v44, v44
	v_fmac_f32_e32 v73, v44, v251
	v_fmac_f32_e32 v74, v44, v235
	v_fmac_f32_e32 v75, v44, v219
	v_fmac_f32_e32 v76, v44, v203
	v_fmac_f32_e32 v77, v44, v185
	v_fmac_f32_e32 v78, v44, v169
	v_fmac_f32_e32 v79, v44, v149
	v_fmac_f32_e32 v80, v44, v133
	v_fmac_f32_e32 v103, v45, v45
	v_fmac_f32_e32 v73, v45, v244
	v_fmac_f32_e32 v74, v45, v228
	v_fmac_f32_e32 v75, v45, v212
	v_fmac_f32_e32 v76, v45, v196
	v_fmac_f32_e32 v77, v45, v178
	v_fmac_f32_e32 v78, v45, v162
	v_fmac_f32_e32 v79, v45, v142
	v_fmac_f32_e32 v80, v45, v124
	v_fmac_f32_e32 v103, v46, v46
	v_fmac_f32_e32 v73, v46, v245
	v_fmac_f32_e32 v74, v46, v229
	v_fmac_f32_e32 v75, v46, v213
	v_fmac_f32_e32 v76, v46, v197
	v_fmac_f32_e32 v77, v46, v179
	v_fmac_f32_e32 v78, v46, v163
	v_fmac_f32_e32 v79, v46, v143
	v_fmac_f32_e32 v80, v46, v125
	v_fmac_f32_e32 v103, v47, v47
	v_fmac_f32_e32 v73, v47, v246
	v_fmac_f32_e32 v74, v47, v230
	v_fmac_f32_e32 v75, v47, v214
	v_fmac_f32_e32 v76, v47, v198
	v_fmac_f32_e32 v77, v47, v180
	v_fmac_f32_e32 v78, v47, v164
	v_fmac_f32_e32 v79, v47, v144
	v_fmac_f32_e32 v80, v47, v126
	v_fmac_f32_e32 v103, v48, v48
	v_fmac_f32_e32 v73, v48, v247
	v_fmac_f32_e32 v74, v48, v231
	v_fmac_f32_e32 v75, v48, v215
	v_fmac_f32_e32 v76, v48, v199
	v_fmac_f32_e32 v77, v48, v181
	v_fmac_f32_e32 v78, v48, v165
	v_fmac_f32_e32 v79, v48, v145
	v_fmac_f32_e32 v80, v48, v127
	v_fmac_f32_e32 v103, v49, v49
	v_fmac_f32_e32 v73, v49, v240
	v_fmac_f32_e32 v74, v49, v224
	v_fmac_f32_e32 v75, v49, v208
	v_fmac_f32_e32 v76, v49, v192
	v_fmac_f32_e32 v77, v49, v174
	v_fmac_f32_e32 v78, v49, v154
	v_fmac_f32_e32 v79, v49, v138
	v_fmac_f32_e32 v80, v49, v120
	v_fmac_f32_e32 v103, v50, v50
	v_fmac_f32_e32 v73, v50, v241
	v_fmac_f32_e32 v74, v50, v225
	v_fmac_f32_e32 v75, v50, v209
	v_fmac_f32_e32 v76, v50, v193
	v_fmac_f32_e32 v77, v50, v175
	v_fmac_f32_e32 v78, v50, v155
	v_fmac_f32_e32 v79, v50, v139
	v_fmac_f32_e32 v80, v50, v121
	v_fmac_f32_e32 v103, v51, v51
	v_fmac_f32_e32 v73, v51, v242
	v_fmac_f32_e32 v74, v51, v226
	v_fmac_f32_e32 v75, v51, v210
	v_fmac_f32_e32 v76, v51, v194
	v_fmac_f32_e32 v77, v51, v176
	v_fmac_f32_e32 v78, v51, v156
	v_fmac_f32_e32 v79, v51, v140
	v_fmac_f32_e32 v80, v51, v122
	v_fmac_f32_e32 v103, v52, v52
	v_fmac_f32_e32 v73, v52, v243
	v_fmac_f32_e32 v74, v52, v227
	v_fmac_f32_e32 v75, v52, v211
	v_fmac_f32_e32 v76, v52, v195
	v_fmac_f32_e32 v77, v52, v177
	v_fmac_f32_e32 v78, v52, v157
	v_fmac_f32_e32 v79, v52, v141
	v_fmac_f32_e32 v80, v52, v123
	v_fmac_f32_e32 v103, v53, v53
	v_fmac_f32_e32 v73, v53, v236
	v_fmac_f32_e32 v74, v53, v220
	v_fmac_f32_e32 v75, v53, v204
	v_fmac_f32_e32 v76, v53, v188
	v_fmac_f32_e32 v77, v53, v170
	v_fmac_f32_e32 v78, v53, v150
	v_fmac_f32_e32 v79, v53, v134
	v_fmac_f32_e32 v80, v53, v116
	v_fmac_f32_e32 v103, v54, v54
	v_fmac_f32_e32 v73, v54, v237
	v_fmac_f32_e32 v74, v54, v221
	v_fmac_f32_e32 v75, v54, v205
	v_fmac_f32_e32 v76, v54, v189
	v_fmac_f32_e32 v77, v54, v171
	v_fmac_f32_e32 v78, v54, v151
	v_fmac_f32_e32 v79, v54, v135
	v_fmac_f32_e32 v80, v54, v117
	v_fmac_f32_e32 v103, v55, v55
	v_fmac_f32_e32 v73, v55, v238
	v_fmac_f32_e32 v74, v55, v222
	v_fmac_f32_e32 v75, v55, v206
	v_fmac_f32_e32 v76, v55, v190
	v_fmac_f32_e32 v77, v55, v172
	v_fmac_f32_e32 v78, v55, v152
	v_fmac_f32_e32 v79, v55, v136
	v_fmac_f32_e32 v80, v55, v118
	v_fmac_f32_e32 v103, v56, v56
	v_fmac_f32_e32 v73, v56, v239
	v_fmac_f32_e32 v74, v56, v223
	v_fmac_f32_e32 v75, v56, v207
	v_fmac_f32_e32 v76, v56, v191
	v_fmac_f32_e32 v77, v56, v173
	v_fmac_f32_e32 v78, v56, v153
	v_fmac_f32_e32 v79, v56, v137
	v_fmac_f32_e32 v80, v56, v119
	v_lshlrev_b32_e32 v97, 16, v18
	v_and_b32_e32 v159, s40, v18
	v_lshlrev_b32_e32 v187, 16, v19
	v_and_b32_e32 v44, s40, v19
	v_lshlrev_b32_e32 v45, 16, v20
	v_and_b32_e32 v46, s40, v20
	v_lshlrev_b32_e32 v47, 16, v21
	v_and_b32_e32 v48, s40, v21
	v_lshlrev_b32_e32 v49, 16, v22
	v_and_b32_e32 v50, s40, v22
	v_lshlrev_b32_e32 v51, 16, v23
	v_and_b32_e32 v52, s40, v23
	v_lshlrev_b32_e32 v53, 16, v24
	v_and_b32_e32 v54, s40, v24
; __device__ __forceinline__ float lane_get(float v, int src_lane) { return __builtin_bit_cast(float, __builtin_amdgcn_ds_bpermute(src_lane << 2, __builtin_bit_cast(int, v))); }
; __device__ __forceinline__ void fgate_phase(const bfr* x, const float* wf, const float* bfg, float* cl, float* ctot, LAS float* scr, int bx, int G, int tid, int lane, int wave) {
;     ...
;             for (int jj = 0; jj < 4; ++jj) { r[16] += (va[jj].x * va[jj].x + va[jj].y * va[jj].y) + (va[jj].z * va[jj].z + va[jj].w * va[jj].w); r[17] += (vb[jj].x * vb[jj].x + vb[jj].y * vb[jj].y) + (vb[jj].z * vb[jj].z + vb[jj].w * vb[jj].w); }
; #pragma unroll
;             for (int h = 0; h < NH; ++h) { const f32x4* wr = (const f32x4*)(wf + h * D) + lane + zo; float da = 0.f, db = 0.f;
; #pragma unroll
;                 for (int jj = 0; jj < 4; ++jj) { const f32x4 w = wr[64 * jj]; da += (va[jj].x * w.x + va[jj].y * w.y) + (va[jj].z * w.z + va[jj].w * w.w); db += (vb[jj].x * w.x + vb[jj].y * w.y) + (vb[jj].z * w.z + vb[jj].w * w.w); }
;                 r[h] = da; r[8 + h] = db; }
; #pragma unroll
;             for (int o = 1; o < 64; o <<= 1) {
; #pragma unroll
;                 for (int q = 0; q < 18; ++q) r[q] += lane_get(r[q], lane ^ o); }
	v_lshlrev_b32_e32 v55, 16, v25
	v_and_b32_e32 v56, s40, v25
	v_mul_f32_e32 v104, v97, v97
	v_mul_f32_e32 v81, v97, v248
	v_mul_f32_e32 v82, v97, v232
	v_mul_f32_e32 v83, v97, v216
	v_mul_f32_e32 v84, v97, v200
	v_mul_f32_e32 v85, v97, v182
	v_mul_f32_e32 v86, v97, v166
	v_mul_f32_e32 v87, v97, v146
	v_mul_f32_e32 v100, v97, v130
	v_fmac_f32_e32 v104, v159, v159
	v_fmac_f32_e32 v81, v159, v249
	v_fmac_f32_e32 v82, v159, v233
	v_fmac_f32_e32 v83, v159, v217
	v_fmac_f32_e32 v84, v159, v201
	v_fmac_f32_e32 v85, v159, v183
	v_fmac_f32_e32 v86, v159, v167
	v_fmac_f32_e32 v87, v159, v147
	v_fmac_f32_e32 v100, v159, v131
	v_fmac_f32_e32 v104, v187, v187
	v_fmac_f32_e32 v81, v187, v250
	v_fmac_f32_e32 v82, v187, v234
	v_fmac_f32_e32 v83, v187, v218
	v_fmac_f32_e32 v84, v187, v202
	v_fmac_f32_e32 v85, v187, v184
	v_fmac_f32_e32 v86, v187, v168
	v_fmac_f32_e32 v87, v187, v148
	v_fmac_f32_e32 v100, v187, v132
	v_fmac_f32_e32 v104, v44, v44
	v_fmac_f32_e32 v81, v44, v251
	v_fmac_f32_e32 v82, v44, v235
	v_fmac_f32_e32 v83, v44, v219
	v_fmac_f32_e32 v84, v44, v203
	v_fmac_f32_e32 v85, v44, v185
	v_fmac_f32_e32 v86, v44, v169
	v_fmac_f32_e32 v87, v44, v149
	v_fmac_f32_e32 v100, v44, v133
	v_fmac_f32_e32 v104, v45, v45
	v_fmac_f32_e32 v81, v45, v244
	v_fmac_f32_e32 v82, v45, v228
	v_fmac_f32_e32 v83, v45, v212
	v_fmac_f32_e32 v84, v45, v196
	v_fmac_f32_e32 v85, v45, v178
	v_fmac_f32_e32 v86, v45, v162
	v_fmac_f32_e32 v87, v45, v142
	v_fmac_f32_e32 v100, v45, v124
	v_fmac_f32_e32 v104, v46, v46
	v_fmac_f32_e32 v81, v46, v245
	v_fmac_f32_e32 v82, v46, v229
	v_fmac_f32_e32 v83, v46, v213
	v_fmac_f32_e32 v84, v46, v197
	v_fmac_f32_e32 v85, v46, v179
	v_fmac_f32_e32 v86, v46, v163
	v_fmac_f32_e32 v87, v46, v143
	v_fmac_f32_e32 v100, v46, v125
	v_fmac_f32_e32 v104, v47, v47
	v_fmac_f32_e32 v81, v47, v246
	v_fmac_f32_e32 v82, v47, v230
	v_fmac_f32_e32 v83, v47, v214
	v_fmac_f32_e32 v84, v47, v198
	v_fmac_f32_e32 v85, v47, v180
	v_fmac_f32_e32 v86, v47, v164
	v_fmac_f32_e32 v87, v47, v144
	v_fmac_f32_e32 v100, v47, v126
	v_fmac_f32_e32 v104, v48, v48
	v_fmac_f32_e32 v81, v48, v247
	v_fmac_f32_e32 v82, v48, v231
	v_fmac_f32_e32 v83, v48, v215
	v_fmac_f32_e32 v84, v48, v199
	v_fmac_f32_e32 v85, v48, v181
	v_fmac_f32_e32 v86, v48, v165
	v_fmac_f32_e32 v87, v48, v145
	v_fmac_f32_e32 v100, v48, v127
	v_fmac_f32_e32 v104, v49, v49
	v_fmac_f32_e32 v81, v49, v240
	v_fmac_f32_e32 v82, v49, v224
	v_fmac_f32_e32 v83, v49, v208
	v_fmac_f32_e32 v84, v49, v192
	v_fmac_f32_e32 v85, v49, v174
	v_fmac_f32_e32 v86, v49, v154
	v_fmac_f32_e32 v87, v49, v138
	v_fmac_f32_e32 v100, v49, v120
	v_fmac_f32_e32 v104, v50, v50
	v_fmac_f32_e32 v81, v50, v241
	v_fmac_f32_e32 v82, v50, v225
	v_fmac_f32_e32 v83, v50, v209
	v_fmac_f32_e32 v84, v50, v193
	v_fmac_f32_e32 v85, v50, v175
	v_fmac_f32_e32 v86, v50, v155
	v_fmac_f32_e32 v87, v50, v139
	v_fmac_f32_e32 v100, v50, v121
	v_fmac_f32_e32 v104, v51, v51
	v_fmac_f32_e32 v81, v51, v242
	v_fmac_f32_e32 v82, v51, v226
	v_fmac_f32_e32 v83, v51, v210
	v_fmac_f32_e32 v84, v51, v194
	v_fmac_f32_e32 v85, v51, v176
	v_fmac_f32_e32 v86, v51, v156
	v_fmac_f32_e32 v87, v51, v140
	v_fmac_f32_e32 v100, v51, v122
	v_fmac_f32_e32 v104, v52, v52
	v_fmac_f32_e32 v81, v52, v243
	v_fmac_f32_e32 v82, v52, v227
	v_fmac_f32_e32 v83, v52, v211
	v_fmac_f32_e32 v84, v52, v195
	v_fmac_f32_e32 v85, v52, v177
	v_fmac_f32_e32 v86, v52, v157
	v_fmac_f32_e32 v87, v52, v141
	v_fmac_f32_e32 v100, v52, v123
	v_fmac_f32_e32 v104, v53, v53
	v_fmac_f32_e32 v81, v53, v236
	v_fmac_f32_e32 v82, v53, v220
	v_fmac_f32_e32 v83, v53, v204
	v_fmac_f32_e32 v84, v53, v188
	v_fmac_f32_e32 v85, v53, v170
	v_fmac_f32_e32 v86, v53, v150
	v_fmac_f32_e32 v87, v53, v134
	v_fmac_f32_e32 v100, v53, v116
	v_fmac_f32_e32 v104, v54, v54
	v_fmac_f32_e32 v81, v54, v237
	v_fmac_f32_e32 v82, v54, v221
	v_fmac_f32_e32 v83, v54, v205
	v_fmac_f32_e32 v84, v54, v189
	v_fmac_f32_e32 v85, v54, v171
	v_fmac_f32_e32 v86, v54, v151
	v_fmac_f32_e32 v87, v54, v135
	v_fmac_f32_e32 v100, v54, v117
	v_fmac_f32_e32 v104, v55, v55
	v_fmac_f32_e32 v81, v55, v238
	v_fmac_f32_e32 v82, v55, v222
	v_fmac_f32_e32 v83, v55, v206
	v_fmac_f32_e32 v84, v55, v190
	v_fmac_f32_e32 v85, v55, v172
	v_fmac_f32_e32 v86, v55, v152
	v_fmac_f32_e32 v87, v55, v136
	v_fmac_f32_e32 v100, v55, v118
	v_fmac_f32_e32 v104, v56, v56
	v_fmac_f32_e32 v81, v56, v239
	v_fmac_f32_e32 v82, v56, v223
	v_fmac_f32_e32 v83, v56, v207
	v_fmac_f32_e32 v84, v56, v191
	v_fmac_f32_e32 v85, v56, v173
	v_fmac_f32_e32 v86, v56, v153
	v_fmac_f32_e32 v87, v56, v137
	v_fmac_f32_e32 v100, v56, v119
	s_nop 1
	v_permlane32_swap_b32_e32 v57, v73
	v_permlane32_swap_b32_e32 v58, v74
	v_permlane32_swap_b32_e32 v59, v75
	v_permlane32_swap_b32_e32 v60, v76
	v_permlane32_swap_b32_e32 v61, v77
	v_permlane32_swap_b32_e32 v62, v78
	v_permlane32_swap_b32_e32 v63, v79
	v_permlane32_swap_b32_e32 v64, v80
	v_permlane32_swap_b32_e32 v65, v81
	v_permlane32_swap_b32_e32 v66, v82
; __device__ __forceinline__ float lane_get(float v, int src_lane) { return __builtin_bit_cast(float, __builtin_amdgcn_ds_bpermute(src_lane << 2, __builtin_bit_cast(int, v))); }
; __device__ __forceinline__ void fgate_phase(const bfr* x, const float* wf, const float* bfg, float* cl, float* ctot, LAS float* scr, int bx, int G, int tid, int lane, int wave) {
;     ...
;             for (int o = 1; o < 64; o <<= 1) {
; #pragma unroll
;                 for (int q = 0; q < 18; ++q) r[q] += lane_get(r[q], lane ^ o); }
;             const float rsa = rsqrtf(r[16] * (1.f / D) + EPS), rsb = rsqrtf(r[17] * (1.f / D) + EPS);
;             if (lane < 16) { const int h = lane & 7; float dsel = r[0];
; #pragma unroll
;                 for (int q = 1; q < 16; ++q) dsel = (lane == q) ? r[q] : dsel;
;                 const float zz = dsel * (lane < 8 ? rsa : rsb) + bfg[h]; const float lf = fminf(zz, 0.f) - 0.6931471805599453f * __builtin_amdgcn_logf(1.0f + __builtin_amdgcn_exp2f(-LOG2E * fabsf(zz)));
;                 scr[(wave * 8 + j + (lane >> 3)) * 8 + h] = lf; } }
	v_permlane32_swap_b32_e32 v67, v83
	v_permlane32_swap_b32_e32 v68, v84
	v_permlane32_swap_b32_e32 v69, v85
	v_permlane32_swap_b32_e32 v70, v86
	v_permlane32_swap_b32_e32 v71, v87
	v_permlane32_swap_b32_e32 v72, v100
	v_permlane32_swap_b32_e32 v101, v103
	v_permlane32_swap_b32_e32 v102, v104
	s_nop 1
	v_add_f32_e32 v57, v57, v73
	v_add_f32_e32 v58, v58, v74
	v_add_f32_e32 v59, v59, v75
	v_add_f32_e32 v60, v60, v76
	v_add_f32_e32 v61, v61, v77
	v_add_f32_e32 v62, v62, v78
	v_add_f32_e32 v63, v63, v79
	v_add_f32_e32 v64, v64, v80
	v_add_f32_e32 v65, v65, v81
	v_add_f32_e32 v66, v66, v82
	v_add_f32_e32 v67, v67, v83
	v_add_f32_e32 v68, v68, v84
	v_add_f32_e32 v69, v69, v85
	v_add_f32_e32 v70, v70, v86
	v_add_f32_e32 v71, v71, v87
	v_add_f32_e32 v72, v72, v100
	v_add_f32_e32 v101, v101, v103
	v_add_f32_e32 v102, v102, v104
	s_nop 1
	v_permlane16_swap_b32_e32 v57, v65
	v_permlane16_swap_b32_e32 v58, v66
	v_permlane16_swap_b32_e32 v59, v67
	v_permlane16_swap_b32_e32 v60, v68
	v_permlane16_swap_b32_e32 v61, v69
	v_permlane16_swap_b32_e32 v62, v70
	v_permlane16_swap_b32_e32 v63, v71
	v_permlane16_swap_b32_e32 v64, v72
	v_permlane16_swap_b32_e32 v101, v102
	s_nop 1
	v_add_f32_e32 v57, v57, v65
	v_add_f32_e32 v58, v58, v66
	v_add_f32_e32 v59, v59, v67
	v_add_f32_e32 v60, v60, v68
	v_add_f32_e32 v61, v61, v69
	v_add_f32_e32 v62, v62, v70
	v_add_f32_e32 v63, v63, v71
	v_add_f32_e32 v64, v64, v72
	v_add_f32_e32 v101, v101, v102
	s_nop 1
	v_add_f32_dpp v57, v57, v57 quad_perm:[1,0,3,2] row_mask:0xf bank_mask:0xf
	v_add_f32_dpp v58, v58, v58 quad_perm:[1,0,3,2] row_mask:0xf bank_mask:0xf
	v_add_f32_dpp v59, v59, v59 quad_perm:[1,0,3,2] row_mask:0xf bank_mask:0xf
	v_add_f32_dpp v60, v60, v60 quad_perm:[1,0,3,2] row_mask:0xf bank_mask:0xf
	v_add_f32_dpp v61, v61, v61 quad_perm:[1,0,3,2] row_mask:0xf bank_mask:0xf
	v_add_f32_dpp v62, v62, v62 quad_perm:[1,0,3,2] row_mask:0xf bank_mask:0xf
	v_add_f32_dpp v63, v63, v63 quad_perm:[1,0,3,2] row_mask:0xf bank_mask:0xf
	v_add_f32_dpp v64, v64, v64 quad_perm:[1,0,3,2] row_mask:0xf bank_mask:0xf
	v_add_f32_dpp v101, v101, v101 quad_perm:[1,0,3,2] row_mask:0xf bank_mask:0xf
	s_nop 1
	v_add_f32_dpp v57, v57, v57 quad_perm:[2,3,0,1] row_mask:0xf bank_mask:0xf
	v_add_f32_dpp v58, v58, v58 quad_perm:[2,3,0,1] row_mask:0xf bank_mask:0xf
	v_add_f32_dpp v59, v59, v59 quad_perm:[2,3,0,1] row_mask:0xf bank_mask:0xf
	v_add_f32_dpp v60, v60, v60 quad_perm:[2,3,0,1] row_mask:0xf bank_mask:0xf
	v_add_f32_dpp v61, v61, v61 quad_perm:[2,3,0,1] row_mask:0xf bank_mask:0xf
	v_add_f32_dpp v62, v62, v62 quad_perm:[2,3,0,1] row_mask:0xf bank_mask:0xf
	v_add_f32_dpp v63, v63, v63 quad_perm:[2,3,0,1] row_mask:0xf bank_mask:0xf
	v_add_f32_dpp v64, v64, v64 quad_perm:[2,3,0,1] row_mask:0xf bank_mask:0xf
	v_add_f32_dpp v101, v101, v101 quad_perm:[2,3,0,1] row_mask:0xf bank_mask:0xf
	s_nop 1
	v_add_f32_dpp v57, v57, v57 row_half_mirror row_mask:0xf bank_mask:0xf
	v_add_f32_dpp v58, v58, v58 row_half_mirror row_mask:0xf bank_mask:0xf
	v_add_f32_dpp v59, v59, v59 row_half_mirror row_mask:0xf bank_mask:0xf
	v_add_f32_dpp v60, v60, v60 row_half_mirror row_mask:0xf bank_mask:0xf
	v_add_f32_dpp v61, v61, v61 row_half_mirror row_mask:0xf bank_mask:0xf
	v_add_f32_dpp v62, v62, v62 row_half_mirror row_mask:0xf bank_mask:0xf
	v_add_f32_dpp v63, v63, v63 row_half_mirror row_mask:0xf bank_mask:0xf
	v_add_f32_dpp v64, v64, v64 row_half_mirror row_mask:0xf bank_mask:0xf
	v_add_f32_dpp v101, v101, v101 row_half_mirror row_mask:0xf bank_mask:0xf
	s_nop 1
	v_add_f32_dpp v57, v57, v57 row_mirror row_mask:0xf bank_mask:0xf
	v_add_f32_dpp v58, v58, v58 row_mirror row_mask:0xf bank_mask:0xf
	v_add_f32_dpp v59, v59, v59 row_mirror row_mask:0xf bank_mask:0xf
	v_add_f32_dpp v60, v60, v60 row_mirror row_mask:0xf bank_mask:0xf
	v_add_f32_dpp v61, v61, v61 row_mirror row_mask:0xf bank_mask:0xf
	v_add_f32_dpp v62, v62, v62 row_mirror row_mask:0xf bank_mask:0xf
	v_add_f32_dpp v63, v63, v63 row_mirror row_mask:0xf bank_mask:0xf
	v_add_f32_dpp v64, v64, v64 row_mirror row_mask:0xf bank_mask:0xf
	v_add_f32_dpp v101, v101, v101 row_mirror row_mask:0xf bank_mask:0xf
	s_nop 1
	v_mov_b32_e32 v106, v57
	v_cndmask_b32_e64 v106, v106, v58, s[6:7]
	v_cndmask_b32_e64 v106, v106, v59, s[8:9]
	v_cndmask_b32_e64 v106, v106, v60, s[10:11]
	v_cndmask_b32_e64 v106, v106, v61, s[12:13]
	v_cndmask_b32_e64 v106, v106, v62, s[14:15]
	v_cndmask_b32_e64 v106, v106, v63, s[16:17]
	v_cndmask_b32_e64 v106, v106, v64, s[18:19]
	v_mul_f32_e32 v107, 0x3a800000, v101
	v_add_f32_e32 v107, 0x358637bd, v107
	v_rsq_f32_e32 v107, v107
	s_nop 0
	v_fma_f32 v106, v106, v107, v105
	v_mul_f32_e64 v107, |v106|, s65
	v_exp_f32_e32 v107, v107
	v_min_f32_e32 v106, 0, v106
	v_add_f32_e32 v107, 1.0, v107
	v_log_f32_e32 v107, v107
	s_nop 0
	v_fmac_f32_e32 v106, 0xbf317218, v107
	s_mov_b64 s[54:55], exec
	s_mov_b32 exec_lo, 0xff00ff
	s_mov_b32 exec_hi, 0xff00ff
	ds_write_b32 v109, v106 offset:128
	s_mov_b64 exec, s[54:55]

; __device__ __forceinline__ void fgate_phase(const bfr* x, const float* wf, const float* bfg, float* cl, float* ctot, LAS float* scr, int bx, int G, int tid, int lane, int wave) {
;     ...
;         for (int j = 0; j < 8; j += 2) { const int row = chunk * 64 + wave * 8 + j; typedef unsigned u32x2 __attribute__((ext_vector_type(2))); const u32x2* xa = (const u32x2*)(x + (size_t)row * D) + lane; const u32x2* xb2 = xa + D / 4; f32x4 va[4], vb[4]; float r[18]; int zo = 0; asm volatile("" : "+v"(zo));
; #pragma unroll
;             for (int jj = 0; jj < 4; ++jj) { const u32x2 wa = xa[64 * jj], wb = xb2[64 * jj]; va[jj] = (f32x4){bf_lo(wa.x), bf_hi(wa.x), bf_lo(wa.y), bf_hi(wa.y)}; vb[jj] = (f32x4){bf_lo(wb.x), bf_hi(wb.x), bf_lo(wb.y), bf_hi(wb.y)}; }
;             r[16] = 0.f; r[17] = 0.f;
; #pragma unroll
;             for (int jj = 0; jj < 4; ++jj) { r[16] += (va[jj].x * va[jj].x + va[jj].y * va[jj].y) + (va[jj].z * va[jj].z + va[jj].w * va[jj].w); r[17] += (vb[jj].x * vb[jj].x + vb[jj].y * vb[jj].y) + (vb[jj].z * vb[jj].z + vb[jj].w * vb[jj].w); }
; #pragma unroll
;             for (int h = 0; h < NH; ++h) { const f32x4* wr = (const f32x4*)(wf + h * D) + lane + zo; float da = 0.f, db = 0.f;
; #pragma unroll
;                 for (int jj = 0; jj < 4; ++jj) { const f32x4 w = wr[64 * jj]; da += (va[jj].x * w.x + va[jj].y * w.y) + (va[jj].z * w.z + va[jj].w * w.w); db += (vb[jj].x * w.x + vb[jj].y * w.y) + (vb[jj].z * w.z + vb[jj].w * w.w); }
;                 r[h] = da; r[8 + h] = db; }
.LBB0_1459:
	s_mov_b32 s38, s33
	s_ashr_i32 s39, s33, 31
	s_lshl_b64 s[38:39], s[38:39], 11
	s_mov_b64 s[98:99], 0x1000
	s_mov_b64 s[100:101], 0x2000
	v_lshl_add_u64 v[26:27], v[28:29], 0, s[38:39]
	v_lshl_add_u64 v[42:43], v[30:31], 0, s[98:99]
	v_lshl_add_u64 v[40:41], v[26:27], 0, s[98:99]
	global_load_dwordx2 v[38:39], v[26:27], off
	global_load_dwordx2 v[98:99], v[26:27], off offset:512
	global_load_dwordx2 v[160:161], v[26:27], off offset:1024
	global_load_dwordx2 v[0:1], v[26:27], off offset:1536
	global_load_dwordx2 v[2:3], v[26:27], off offset:2048
	global_load_dwordx2 v[4:5], v[26:27], off offset:2560
	global_load_dwordx2 v[6:7], v[26:27], off offset:3072
	global_load_dwordx2 v[8:9], v[26:27], off offset:3584
	global_load_dwordx2 v[10:11], v[40:41], off
	global_load_dwordx2 v[12:13], v[40:41], off offset:512
	global_load_dwordx2 v[14:15], v[40:41], off offset:1024
	global_load_dwordx2 v[16:17], v[40:41], off offset:1536
	global_load_dwordx2 v[18:19], v[40:41], off offset:2048
	global_load_dwordx2 v[20:21], v[40:41], off offset:2560
	global_load_dwordx2 v[22:23], v[40:41], off offset:3072
	global_load_dwordx2 v[24:25], v[40:41], off offset:3584
	global_load_dword v105, v[32:33], off offset:32
	global_load_dwordx4 v[248:251], v[42:43], off offset:-4096
	global_load_dwordx4 v[244:247], v[42:43], off offset:-3072
	global_load_dwordx4 v[240:243], v[42:43], off offset:-2048
	global_load_dwordx4 v[236:239], v[42:43], off offset:-1024
	global_load_dwordx4 v[232:235], v[42:43], off
	global_load_dwordx4 v[228:231], v[42:43], off offset:1024
	global_load_dwordx4 v[224:227], v[42:43], off offset:2048
	global_load_dwordx4 v[220:223], v[42:43], off offset:3072
	v_lshl_add_u64 v[42:43], v[42:43], 0, s[100:101]
	global_load_dwordx4 v[216:219], v[42:43], off offset:-4096
	global_load_dwordx4 v[212:215], v[42:43], off offset:-3072
	global_load_dwordx4 v[208:211], v[42:43], off offset:-2048
	global_load_dwordx4 v[204:207], v[42:43], off offset:-1024
	global_load_dwordx4 v[200:203], v[42:43], off
	global_load_dwordx4 v[196:199], v[42:43], off offset:1024
	global_load_dwordx4 v[192:195], v[42:43], off offset:2048
	global_load_dwordx4 v[188:191], v[42:43], off offset:3072
	v_lshl_add_u64 v[42:43], v[42:43], 0, s[100:101]
	global_load_dwordx4 v[182:185], v[42:43], off offset:-4096
	global_load_dwordx4 v[178:181], v[42:43], off offset:-3072
	global_load_dwordx4 v[174:177], v[42:43], off offset:-2048
	global_load_dwordx4 v[170:173], v[42:43], off offset:-1024
	global_load_dwordx4 v[166:169], v[42:43], off
	global_load_dwordx4 v[162:165], v[42:43], off offset:1024
	global_load_dwordx4 v[154:157], v[42:43], off offset:2048
	global_load_dwordx4 v[150:153], v[42:43], off offset:3072
	v_lshl_add_u64 v[42:43], v[42:43], 0, s[100:101]
	global_load_dwordx4 v[146:149], v[42:43], off offset:-4096
	global_load_dwordx4 v[142:145], v[42:43], off offset:-3072
	global_load_dwordx4 v[138:141], v[42:43], off offset:-2048
	global_load_dwordx4 v[134:137], v[42:43], off offset:-1024
	global_load_dwordx4 v[130:133], v[42:43], off
	global_load_dwordx4 v[124:127], v[42:43], off offset:1024
	global_load_dwordx4 v[120:123], v[42:43], off offset:2048
	global_load_dwordx4 v[116:119], v[42:43], off offset:3072
	v_and_b32_e32 v108, 7, v158
	v_cmp_eq_u32_e64 s[6:7], 1, v108
	v_cmp_eq_u32_e64 s[8:9], 2, v108
	v_cmp_eq_u32_e64 s[10:11], 3, v108
	v_cmp_eq_u32_e64 s[12:13], 4, v108
	v_cmp_eq_u32_e64 s[14:15], 5, v108
	v_cmp_eq_u32_e64 s[16:17], 6, v108
	v_cmp_eq_u32_e64 s[18:19], 7, v108
	v_lshrrev_b32_e32 v106, 4, v158
	v_lshlrev_b32_e32 v106, 5, v106
	v_sub_u32_e32 v109, v95, v106
	s_mov_b32 s40, 0xffff0000
	s_waitcnt vmcnt(0)
	v_lshlrev_b32_e32 v97, 16, v38
	v_and_b32_e32 v159, s40, v38
	v_lshlrev_b32_e32 v187, 16, v39
	v_and_b32_e32 v44, s40, v39
	v_lshlrev_b32_e32 v45, 16, v98
	v_and_b32_e32 v46, s40, v98
	v_lshlrev_b32_e32 v47, 16, v99
	v_and_b32_e32 v48, s40, v99
	v_lshlrev_b32_e32 v49, 16, v160
	v_and_b32_e32 v50, s40, v160
	v_lshlrev_b32_e32 v51, 16, v161
	v_and_b32_e32 v52, s40, v161
	v_lshlrev_b32_e32 v53, 16, v0
	v_and_b32_e32 v54, s40, v0
	v_lshlrev_b32_e32 v55, 16, v1
	v_and_b32_e32 v56, s40, v1
	v_mul_f32_e32 v101, v97, v97
	v_mul_f32_e32 v57, v97, v248
	v_mul_f32_e32 v58, v97, v232
	v_mul_f32_e32 v59, v97, v216
	v_mul_f32_e32 v60, v97, v200
	v_mul_f32_e32 v61, v97, v182
	v_mul_f32_e32 v62, v97, v166
	v_mul_f32_e32 v63, v97, v146
	v_mul_f32_e32 v64, v97, v130
	v_fmac_f32_e32 v101, v159, v159
	v_fmac_f32_e32 v57, v159, v249
	v_fmac_f32_e32 v58, v159, v233
	v_fmac_f32_e32 v59, v159, v217
	v_fmac_f32_e32 v60, v159, v201
	v_fmac_f32_e32 v61, v159, v183
	v_fmac_f32_e32 v62, v159, v167
	v_fmac_f32_e32 v63, v159, v147
	v_fmac_f32_e32 v64, v159, v131
	v_fmac_f32_e32 v101, v187, v187
	v_fmac_f32_e32 v57, v187, v250
	v_fmac_f32_e32 v58, v187, v234
	v_fmac_f32_e32 v59, v187, v218
	v_fmac_f32_e32 v60, v187, v202
	v_fmac_f32_e32 v61, v187, v184
	v_fmac_f32_e32 v62, v187, v168
	v_fmac_f32_e32 v63, v187, v148
	v_fmac_f32_e32 v64, v187, v132
	v_fmac_f32_e32 v101, v44, v44
	v_fmac_f32_e32 v57, v44, v251
	v_fmac_f32_e32 v58, v44, v235
	v_fmac_f32_e32 v59, v44, v219
	v_fmac_f32_e32 v60, v44, v203
	v_fmac_f32_e32 v61, v44, v185
	v_fmac_f32_e32 v62, v44, v169
	v_fmac_f32_e32 v63, v44, v149
	v_fmac_f32_e32 v64, v44, v133
	v_fmac_f32_e32 v101, v45, v45
	v_fmac_f32_e32 v57, v45, v244
	v_fmac_f32_e32 v58, v45, v228
	v_fmac_f32_e32 v59, v45, v212
	v_fmac_f32_e32 v60, v45, v196
	v_fmac_f32_e32 v61, v45, v178
	v_fmac_f32_e32 v62, v45, v162
	v_fmac_f32_e32 v63, v45, v142
	v_fmac_f32_e32 v64, v45, v124
	v_fmac_f32_e32 v101, v46, v46
	v_fmac_f32_e32 v57, v46, v245
	v_fmac_f32_e32 v58, v46, v229
; __device__ __forceinline__ void fgate_phase(const bfr* x, const float* wf, const float* bfg, float* cl, float* ctot, LAS float* scr, int bx, int G, int tid, int lane, int wave) {
;     ...
;             for (int jj = 0; jj < 4; ++jj) { const u32x2 wa = xa[64 * jj], wb = xb2[64 * jj]; va[jj] = (f32x4){bf_lo(wa.x), bf_hi(wa.x), bf_lo(wa.y), bf_hi(wa.y)}; vb[jj] = (f32x4){bf_lo(wb.x), bf_hi(wb.x), bf_lo(wb.y), bf_hi(wb.y)}; }
;             r[16] = 0.f; r[17] = 0.f;
; #pragma unroll
;             for (int jj = 0; jj < 4; ++jj) { r[16] += (va[jj].x * va[jj].x + va[jj].y * va[jj].y) + (va[jj].z * va[jj].z + va[jj].w * va[jj].w); r[17] += (vb[jj].x * vb[jj].x + vb[jj].y * vb[jj].y) + (vb[jj].z * vb[jj].z + vb[jj].w * vb[jj].w); }
; #pragma unroll
;             for (int h = 0; h < NH; ++h) { const f32x4* wr = (const f32x4*)(wf + h * D) + lane + zo; float da = 0.f, db = 0.f;
; #pragma unroll
;                 for (int jj = 0; jj < 4; ++jj) { const f32x4 w = wr[64 * jj]; da += (va[jj].x * w.x + va[jj].y * w.y) + (va[jj].z * w.z + va[jj].w * w.w); db += (vb[jj].x * w.x + vb[jj].y * w.y) + (vb[jj].z * w.z + vb[jj].w * w.w); }
;                 r[h] = da; r[8 + h] = db; }
	v_fmac_f32_e32 v59, v46, v213
	v_fmac_f32_e32 v60, v46, v197
	v_fmac_f32_e32 v61, v46, v179
	v_fmac_f32_e32 v62, v46, v163
	v_fmac_f32_e32 v63, v46, v143
	v_fmac_f32_e32 v64, v46, v125
	v_fmac_f32_e32 v101, v47, v47
	v_fmac_f32_e32 v57, v47, v246
	v_fmac_f32_e32 v58, v47, v230
	v_fmac_f32_e32 v59, v47, v214
	v_fmac_f32_e32 v60, v47, v198
	v_fmac_f32_e32 v61, v47, v180
	v_fmac_f32_e32 v62, v47, v164
	v_fmac_f32_e32 v63, v47, v144
	v_fmac_f32_e32 v64, v47, v126
	v_fmac_f32_e32 v101, v48, v48
	v_fmac_f32_e32 v57, v48, v247
	v_fmac_f32_e32 v58, v48, v231
	v_fmac_f32_e32 v59, v48, v215
	v_fmac_f32_e32 v60, v48, v199
	v_fmac_f32_e32 v61, v48, v181
	v_fmac_f32_e32 v62, v48, v165
	v_fmac_f32_e32 v63, v48, v145
	v_fmac_f32_e32 v64, v48, v127
	v_fmac_f32_e32 v101, v49, v49
	v_fmac_f32_e32 v57, v49, v240
	v_fmac_f32_e32 v58, v49, v224
	v_fmac_f32_e32 v59, v49, v208
	v_fmac_f32_e32 v60, v49, v192
	v_fmac_f32_e32 v61, v49, v174
	v_fmac_f32_e32 v62, v49, v154
	v_fmac_f32_e32 v63, v49, v138
	v_fmac_f32_e32 v64, v49, v120
	v_fmac_f32_e32 v101, v50, v50
	v_fmac_f32_e32 v57, v50, v241
	v_fmac_f32_e32 v58, v50, v225
	v_fmac_f32_e32 v59, v50, v209
	v_fmac_f32_e32 v60, v50, v193
	v_fmac_f32_e32 v61, v50, v175
	v_fmac_f32_e32 v62, v50, v155
	v_fmac_f32_e32 v63, v50, v139
	v_fmac_f32_e32 v64, v50, v121
	v_fmac_f32_e32 v101, v51, v51
	v_fmac_f32_e32 v57, v51, v242
	v_fmac_f32_e32 v58, v51, v226
	v_fmac_f32_e32 v59, v51, v210
	v_fmac_f32_e32 v60, v51, v194
	v_fmac_f32_e32 v61, v51, v176
	v_fmac_f32_e32 v62, v51, v156
	v_fmac_f32_e32 v63, v51, v140
	v_fmac_f32_e32 v64, v51, v122
	v_fmac_f32_e32 v101, v52, v52
	v_fmac_f32_e32 v57, v52, v243
	v_fmac_f32_e32 v58, v52, v227
	v_fmac_f32_e32 v59, v52, v211
	v_fmac_f32_e32 v60, v52, v195
	v_fmac_f32_e32 v61, v52, v177
	v_fmac_f32_e32 v62, v52, v157
	v_fmac_f32_e32 v63, v52, v141
	v_fmac_f32_e32 v64, v52, v123
	v_fmac_f32_e32 v101, v53, v53
	v_fmac_f32_e32 v57, v53, v236
	v_fmac_f32_e32 v58, v53, v220
	v_fmac_f32_e32 v59, v53, v204
	v_fmac_f32_e32 v60, v53, v188
	v_fmac_f32_e32 v61, v53, v170
	v_fmac_f32_e32 v62, v53, v150
	v_fmac_f32_e32 v63, v53, v134
	v_fmac_f32_e32 v64, v53, v116
	v_fmac_f32_e32 v101, v54, v54
	v_fmac_f32_e32 v57, v54, v237
	v_fmac_f32_e32 v58, v54, v221
	v_fmac_f32_e32 v59, v54, v205
	v_fmac_f32_e32 v60, v54, v189
	v_fmac_f32_e32 v61, v54, v171
	v_fmac_f32_e32 v62, v54, v151
	v_fmac_f32_e32 v63, v54, v135
	v_fmac_f32_e32 v64, v54, v117
	v_fmac_f32_e32 v101, v55, v55
	v_fmac_f32_e32 v57, v55, v238
	v_fmac_f32_e32 v58, v55, v222
	v_fmac_f32_e32 v59, v55, v206
	v_fmac_f32_e32 v60, v55, v190
	v_fmac_f32_e32 v61, v55, v172
	v_fmac_f32_e32 v62, v55, v152
	v_fmac_f32_e32 v63, v55, v136
	v_fmac_f32_e32 v64, v55, v118
	v_fmac_f32_e32 v101, v56, v56
	v_fmac_f32_e32 v57, v56, v239
	v_fmac_f32_e32 v58, v56, v223
	v_fmac_f32_e32 v59, v56, v207
	v_fmac_f32_e32 v60, v56, v191
	v_fmac_f32_e32 v61, v56, v173
	v_fmac_f32_e32 v62, v56, v153
	v_fmac_f32_e32 v63, v56, v137
	v_fmac_f32_e32 v64, v56, v119
	v_lshlrev_b32_e32 v97, 16, v2
	v_and_b32_e32 v159, s40, v2
	v_lshlrev_b32_e32 v187, 16, v3
	v_and_b32_e32 v44, s40, v3
	v_lshlrev_b32_e32 v45, 16, v4
	v_and_b32_e32 v46, s40, v4
	v_lshlrev_b32_e32 v47, 16, v5
	v_and_b32_e32 v48, s40, v5
	v_lshlrev_b32_e32 v49, 16, v6
	v_and_b32_e32 v50, s40, v6
	v_lshlrev_b32_e32 v51, 16, v7
	v_and_b32_e32 v52, s40, v7
	v_lshlrev_b32_e32 v53, 16, v8
	v_and_b32_e32 v54, s40, v8
	v_lshlrev_b32_e32 v55, 16, v9
	v_and_b32_e32 v56, s40, v9
	v_mul_f32_e32 v102, v97, v97
	v_mul_f32_e32 v65, v97, v248
	v_mul_f32_e32 v66, v97, v232
	v_mul_f32_e32 v67, v97, v216
	v_mul_f32_e32 v68, v97, v200
	v_mul_f32_e32 v69, v97, v182
	v_mul_f32_e32 v70, v97, v166
	v_mul_f32_e32 v71, v97, v146
	v_mul_f32_e32 v72, v97, v130
	v_fmac_f32_e32 v102, v159, v159
	v_fmac_f32_e32 v65, v159, v249
	v_fmac_f32_e32 v66, v159, v233
	v_fmac_f32_e32 v67, v159, v217
	v_fmac_f32_e32 v68, v159, v201
	v_fmac_f32_e32 v69, v159, v183
	v_fmac_f32_e32 v70, v159, v167
	v_fmac_f32_e32 v71, v159, v147
	v_fmac_f32_e32 v72, v159, v131
	v_fmac_f32_e32 v102, v187, v187
	v_fmac_f32_e32 v65, v187, v250
	v_fmac_f32_e32 v66, v187, v234
	v_fmac_f32_e32 v67, v187, v218
	v_fmac_f32_e32 v68, v187, v202
	v_fmac_f32_e32 v69, v187, v184
	v_fmac_f32_e32 v70, v187, v168
	v_fmac_f32_e32 v71, v187, v148
	v_fmac_f32_e32 v72, v187, v132
	v_fmac_f32_e32 v102, v44, v44
	v_fmac_f32_e32 v65, v44, v251
	v_fmac_f32_e32 v66, v44, v235
	v_fmac_f32_e32 v67, v44, v219
	v_fmac_f32_e32 v68, v44, v203
	v_fmac_f32_e32 v69, v44, v185
	v_fmac_f32_e32 v70, v44, v169
	v_fmac_f32_e32 v71, v44, v149
	v_fmac_f32_e32 v72, v44, v133
	v_fmac_f32_e32 v102, v45, v45
	v_fmac_f32_e32 v65, v45, v244
	v_fmac_f32_e32 v66, v45, v228
	v_fmac_f32_e32 v67, v45, v212
	v_fmac_f32_e32 v68, v45, v196
	v_fmac_f32_e32 v69, v45, v178
	v_fmac_f32_e32 v70, v45, v162
	v_fmac_f32_e32 v71, v45, v142
	v_fmac_f32_e32 v72, v45, v124
	v_fmac_f32_e32 v102, v46, v46
	v_fmac_f32_e32 v65, v46, v245
	v_fmac_f32_e32 v66, v46, v229
	v_fmac_f32_e32 v67, v46, v213
	v_fmac_f32_e32 v68, v46, v197
	v_fmac_f32_e32 v69, v46, v179
	v_fmac_f32_e32 v70, v46, v163
	v_fmac_f32_e32 v71, v46, v143
	v_fmac_f32_e32 v72, v46, v125
	v_fmac_f32_e32 v102, v47, v47
	v_fmac_f32_e32 v65, v47, v246
	v_fmac_f32_e32 v66, v47, v230
	v_fmac_f32_e32 v67, v47, v214
	v_fmac_f32_e32 v68, v47, v198
	v_fmac_f32_e32 v69, v47, v180
	v_fmac_f32_e32 v70, v47, v164
	v_fmac_f32_e32 v71, v47, v144
	v_fmac_f32_e32 v72, v47, v126
	v_fmac_f32_e32 v102, v48, v48
	v_fmac_f32_e32 v65, v48, v247
	v_fmac_f32_e32 v66, v48, v231
	v_fmac_f32_e32 v67, v48, v215
	v_fmac_f32_e32 v68, v48, v199
	v_fmac_f32_e32 v69, v48, v181
	v_fmac_f32_e32 v70, v48, v165
; __device__ __forceinline__ void fgate_phase(const bfr* x, const float* wf, const float* bfg, float* cl, float* ctot, LAS float* scr, int bx, int G, int tid, int lane, int wave) {
;     ...
;             for (int jj = 0; jj < 4; ++jj) { const u32x2 wa = xa[64 * jj], wb = xb2[64 * jj]; va[jj] = (f32x4){bf_lo(wa.x), bf_hi(wa.x), bf_lo(wa.y), bf_hi(wa.y)}; vb[jj] = (f32x4){bf_lo(wb.x), bf_hi(wb.x), bf_lo(wb.y), bf_hi(wb.y)}; }
;             r[16] = 0.f; r[17] = 0.f;
; #pragma unroll
;             for (int jj = 0; jj < 4; ++jj) { r[16] += (va[jj].x * va[jj].x + va[jj].y * va[jj].y) + (va[jj].z * va[jj].z + va[jj].w * va[jj].w); r[17] += (vb[jj].x * vb[jj].x + vb[jj].y * vb[jj].y) + (vb[jj].z * vb[jj].z + vb[jj].w * vb[jj].w); }
; #pragma unroll
;             for (int h = 0; h < NH; ++h) { const f32x4* wr = (const f32x4*)(wf + h * D) + lane + zo; float da = 0.f, db = 0.f;
; #pragma unroll
;                 for (int jj = 0; jj < 4; ++jj) { const f32x4 w = wr[64 * jj]; da += (va[jj].x * w.x + va[jj].y * w.y) + (va[jj].z * w.z + va[jj].w * w.w); db += (vb[jj].x * w.x + vb[jj].y * w.y) + (vb[jj].z * w.z + vb[jj].w * w.w); }
;                 r[h] = da; r[8 + h] = db; }
	v_fmac_f32_e32 v71, v48, v145
	v_fmac_f32_e32 v72, v48, v127
	v_fmac_f32_e32 v102, v49, v49
	v_fmac_f32_e32 v65, v49, v240
	v_fmac_f32_e32 v66, v49, v224
	v_fmac_f32_e32 v67, v49, v208
	v_fmac_f32_e32 v68, v49, v192
	v_fmac_f32_e32 v69, v49, v174
	v_fmac_f32_e32 v70, v49, v154
	v_fmac_f32_e32 v71, v49, v138
	v_fmac_f32_e32 v72, v49, v120
	v_fmac_f32_e32 v102, v50, v50
	v_fmac_f32_e32 v65, v50, v241
	v_fmac_f32_e32 v66, v50, v225
	v_fmac_f32_e32 v67, v50, v209
	v_fmac_f32_e32 v68, v50, v193
	v_fmac_f32_e32 v69, v50, v175
	v_fmac_f32_e32 v70, v50, v155
	v_fmac_f32_e32 v71, v50, v139
	v_fmac_f32_e32 v72, v50, v121
	v_fmac_f32_e32 v102, v51, v51
	v_fmac_f32_e32 v65, v51, v242
	v_fmac_f32_e32 v66, v51, v226
	v_fmac_f32_e32 v67, v51, v210
	v_fmac_f32_e32 v68, v51, v194
	v_fmac_f32_e32 v69, v51, v176
	v_fmac_f32_e32 v70, v51, v156
	v_fmac_f32_e32 v71, v51, v140
	v_fmac_f32_e32 v72, v51, v122
	v_fmac_f32_e32 v102, v52, v52
	v_fmac_f32_e32 v65, v52, v243
	v_fmac_f32_e32 v66, v52, v227
	v_fmac_f32_e32 v67, v52, v211
	v_fmac_f32_e32 v68, v52, v195
	v_fmac_f32_e32 v69, v52, v177
	v_fmac_f32_e32 v70, v52, v157
	v_fmac_f32_e32 v71, v52, v141
	v_fmac_f32_e32 v72, v52, v123
	v_fmac_f32_e32 v102, v53, v53
	v_fmac_f32_e32 v65, v53, v236
	v_fmac_f32_e32 v66, v53, v220
	v_fmac_f32_e32 v67, v53, v204
	v_fmac_f32_e32 v68, v53, v188
	v_fmac_f32_e32 v69, v53, v170
	v_fmac_f32_e32 v70, v53, v150
	v_fmac_f32_e32 v71, v53, v134
	v_fmac_f32_e32 v72, v53, v116
	v_fmac_f32_e32 v102, v54, v54
	v_fmac_f32_e32 v65, v54, v237
	v_fmac_f32_e32 v66, v54, v221
	v_fmac_f32_e32 v67, v54, v205
	v_fmac_f32_e32 v68, v54, v189
	v_fmac_f32_e32 v69, v54, v171
	v_fmac_f32_e32 v70, v54, v151
	v_fmac_f32_e32 v71, v54, v135
	v_fmac_f32_e32 v72, v54, v117
	v_fmac_f32_e32 v102, v55, v55
	v_fmac_f32_e32 v65, v55, v238
	v_fmac_f32_e32 v66, v55, v222
	v_fmac_f32_e32 v67, v55, v206
	v_fmac_f32_e32 v68, v55, v190
	v_fmac_f32_e32 v69, v55, v172
	v_fmac_f32_e32 v70, v55, v152
	v_fmac_f32_e32 v71, v55, v136
	v_fmac_f32_e32 v72, v55, v118
	v_fmac_f32_e32 v102, v56, v56
	v_fmac_f32_e32 v65, v56, v239
	v_fmac_f32_e32 v66, v56, v223
	v_fmac_f32_e32 v67, v56, v207
	v_fmac_f32_e32 v68, v56, v191
	v_fmac_f32_e32 v69, v56, v173
	v_fmac_f32_e32 v70, v56, v153
	v_fmac_f32_e32 v71, v56, v137
	v_fmac_f32_e32 v72, v56, v119
	v_lshlrev_b32_e32 v97, 16, v10
	v_and_b32_e32 v159, s40, v10
	v_lshlrev_b32_e32 v187, 16, v11
	v_and_b32_e32 v44, s40, v11
	v_lshlrev_b32_e32 v45, 16, v12
	v_and_b32_e32 v46, s40, v12
	v_lshlrev_b32_e32 v47, 16, v13
	v_and_b32_e32 v48, s40, v13
	v_lshlrev_b32_e32 v49, 16, v14
	v_and_b32_e32 v50, s40, v14
	v_lshlrev_b32_e32 v51, 16, v15
	v_and_b32_e32 v52, s40, v15
	v_lshlrev_b32_e32 v53, 16, v16
	v_and_b32_e32 v54, s40, v16
	v_lshlrev_b32_e32 v55, 16, v17
	v_and_b32_e32 v56, s40, v17
	v_mul_f32_e32 v103, v97, v97
	v_mul_f32_e32 v73, v97, v248
	v_mul_f32_e32 v74, v97, v232
	v_mul_f32_e32 v75, v97, v216
	v_mul_f32_e32 v76, v97, v200
	v_mul_f32_e32 v77, v97, v182
	v_mul_f32_e32 v78, v97, v166
	v_mul_f32_e32 v79, v97, v146
	v_mul_f32_e32 v80, v97, v130
	v_fmac_f32_e32 v103, v159, v159
	v_fmac_f32_e32 v73, v159, v249
	v_fmac_f32_e32 v74, v159, v233
	v_fmac_f32_e32 v75, v159, v217
	v_fmac_f32_e32 v76, v159, v201
	v_fmac_f32_e32 v77, v159, v183
	v_fmac_f32_e32 v78, v159, v167
	v_fmac_f32_e32 v79, v159, v147
	v_fmac_f32_e32 v80, v159, v131
	v_fmac_f32_e32 v103, v187, v187
	v_fmac_f32_e32 v73, v187, v250
	v_fmac_f32_e32 v74, v187, v234
	v_fmac_f32_e32 v75, v187, v218
	v_fmac_f32_e32 v76, v187, v202
	v_fmac_f32_e32 v77, v187, v184
	v_fmac_f32_e32 v78, v187, v168
	v_fmac_f32_e32 v79, v187, v148
	v_fmac_f32_e32 v80, v187, v132
	v_fmac_f32_e32 v103, v44, v44
	v_fmac_f32_e32 v73, v44, v251
	v_fmac_f32_e32 v74, v44, v235
	v_fmac_f32_e32 v75, v44, v219
	v_fmac_f32_e32 v76, v44, v203
	v_fmac_f32_e32 v77, v44, v185
	v_fmac_f32_e32 v78, v44, v169
	v_fmac_f32_e32 v79, v44, v149
	v_fmac_f32_e32 v80, v44, v133
	v_fmac_f32_e32 v103, v45, v45
	v_fmac_f32_e32 v73, v45, v244
	v_fmac_f32_e32 v74, v45, v228
	v_fmac_f32_e32 v75, v45, v212
	v_fmac_f32_e32 v76, v45, v196
	v_fmac_f32_e32 v77, v45, v178
	v_fmac_f32_e32 v78, v45, v162
	v_fmac_f32_e32 v79, v45, v142
	v_fmac_f32_e32 v80, v45, v124
	v_fmac_f32_e32 v103, v46, v46
	v_fmac_f32_e32 v73, v46, v245
	v_fmac_f32_e32 v74, v46, v229
	v_fmac_f32_e32 v75, v46, v213
	v_fmac_f32_e32 v76, v46, v197
	v_fmac_f32_e32 v77, v46, v179
	v_fmac_f32_e32 v78, v46, v163
	v_fmac_f32_e32 v79, v46, v143
	v_fmac_f32_e32 v80, v46, v125
	v_fmac_f32_e32 v103, v47, v47
	v_fmac_f32_e32 v73, v47, v246
	v_fmac_f32_e32 v74, v47, v230
	v_fmac_f32_e32 v75, v47, v214
	v_fmac_f32_e32 v76, v47, v198
	v_fmac_f32_e32 v77, v47, v180
	v_fmac_f32_e32 v78, v47, v164
	v_fmac_f32_e32 v79, v47, v144
	v_fmac_f32_e32 v80, v47, v126
	v_fmac_f32_e32 v103, v48, v48
	v_fmac_f32_e32 v73, v48, v247
	v_fmac_f32_e32 v74, v48, v231
	v_fmac_f32_e32 v75, v48, v215
	v_fmac_f32_e32 v76, v48, v199
	v_fmac_f32_e32 v77, v48, v181
	v_fmac_f32_e32 v78, v48, v165
	v_fmac_f32_e32 v79, v48, v145
	v_fmac_f32_e32 v80, v48, v127
	v_fmac_f32_e32 v103, v49, v49
	v_fmac_f32_e32 v73, v49, v240
	v_fmac_f32_e32 v74, v49, v224
	v_fmac_f32_e32 v75, v49, v208
	v_fmac_f32_e32 v76, v49, v192
	v_fmac_f32_e32 v77, v49, v174
	v_fmac_f32_e32 v78, v49, v154
	v_fmac_f32_e32 v79, v49, v138
	v_fmac_f32_e32 v80, v49, v120
	v_fmac_f32_e32 v103, v50, v50
	v_fmac_f32_e32 v73, v50, v241
	v_fmac_f32_e32 v74, v50, v225
	v_fmac_f32_e32 v75, v50, v209
	v_fmac_f32_e32 v76, v50, v193
	v_fmac_f32_e32 v77, v50, v175
	v_fmac_f32_e32 v78, v50, v155
	v_fmac_f32_e32 v79, v50, v139
	v_fmac_f32_e32 v80, v50, v121
	v_fmac_f32_e32 v103, v51, v51
	v_fmac_f32_e32 v73, v51, v242
; __device__ __forceinline__ void fgate_phase(const bfr* x, const float* wf, const float* bfg, float* cl, float* ctot, LAS float* scr, int bx, int G, int tid, int lane, int wave) {
;     ...
;             for (int jj = 0; jj < 4; ++jj) { const u32x2 wa = xa[64 * jj], wb = xb2[64 * jj]; va[jj] = (f32x4){bf_lo(wa.x), bf_hi(wa.x), bf_lo(wa.y), bf_hi(wa.y)}; vb[jj] = (f32x4){bf_lo(wb.x), bf_hi(wb.x), bf_lo(wb.y), bf_hi(wb.y)}; }
;             r[16] = 0.f; r[17] = 0.f;
; #pragma unroll
;             for (int jj = 0; jj < 4; ++jj) { r[16] += (va[jj].x * va[jj].x + va[jj].y * va[jj].y) + (va[jj].z * va[jj].z + va[jj].w * va[jj].w); r[17] += (vb[jj].x * vb[jj].x + vb[jj].y * vb[jj].y) + (vb[jj].z * vb[jj].z + vb[jj].w * vb[jj].w); }
; #pragma unroll
;             for (int h = 0; h < NH; ++h) { const f32x4* wr = (const f32x4*)(wf + h * D) + lane + zo; float da = 0.f, db = 0.f;
; #pragma unroll
;                 for (int jj = 0; jj < 4; ++jj) { const f32x4 w = wr[64 * jj]; da += (va[jj].x * w.x + va[jj].y * w.y) + (va[jj].z * w.z + va[jj].w * w.w); db += (vb[jj].x * w.x + vb[jj].y * w.y) + (vb[jj].z * w.z + vb[jj].w * w.w); }
;                 r[h] = da; r[8 + h] = db; }
	v_fmac_f32_e32 v74, v51, v226
	v_fmac_f32_e32 v75, v51, v210
	v_fmac_f32_e32 v76, v51, v194
	v_fmac_f32_e32 v77, v51, v176
	v_fmac_f32_e32 v78, v51, v156
	v_fmac_f32_e32 v79, v51, v140
	v_fmac_f32_e32 v80, v51, v122
	v_fmac_f32_e32 v103, v52, v52
	v_fmac_f32_e32 v73, v52, v243
	v_fmac_f32_e32 v74, v52, v227
	v_fmac_f32_e32 v75, v52, v211
	v_fmac_f32_e32 v76, v52, v195
	v_fmac_f32_e32 v77, v52, v177
	v_fmac_f32_e32 v78, v52, v157
	v_fmac_f32_e32 v79, v52, v141
	v_fmac_f32_e32 v80, v52, v123
	v_fmac_f32_e32 v103, v53, v53
	v_fmac_f32_e32 v73, v53, v236
	v_fmac_f32_e32 v74, v53, v220
	v_fmac_f32_e32 v75, v53, v204
	v_fmac_f32_e32 v76, v53, v188
	v_fmac_f32_e32 v77, v53, v170
	v_fmac_f32_e32 v78, v53, v150
	v_fmac_f32_e32 v79, v53, v134
	v_fmac_f32_e32 v80, v53, v116
	v_fmac_f32_e32 v103, v54, v54
	v_fmac_f32_e32 v73, v54, v237
	v_fmac_f32_e32 v74, v54, v221
	v_fmac_f32_e32 v75, v54, v205
	v_fmac_f32_e32 v76, v54, v189
	v_fmac_f32_e32 v77, v54, v171
	v_fmac_f32_e32 v78, v54, v151
	v_fmac_f32_e32 v79, v54, v135
	v_fmac_f32_e32 v80, v54, v117
	v_fmac_f32_e32 v103, v55, v55
	v_fmac_f32_e32 v73, v55, v238
	v_fmac_f32_e32 v74, v55, v222
	v_fmac_f32_e32 v75, v55, v206
	v_fmac_f32_e32 v76, v55, v190
	v_fmac_f32_e32 v77, v55, v172
	v_fmac_f32_e32 v78, v55, v152
	v_fmac_f32_e32 v79, v55, v136
	v_fmac_f32_e32 v80, v55, v118
	v_fmac_f32_e32 v103, v56, v56
	v_fmac_f32_e32 v73, v56, v239
	v_fmac_f32_e32 v74, v56, v223
	v_fmac_f32_e32 v75, v56, v207
	v_fmac_f32_e32 v76, v56, v191
	v_fmac_f32_e32 v77, v56, v173
	v_fmac_f32_e32 v78, v56, v153
	v_fmac_f32_e32 v79, v56, v137
	v_fmac_f32_e32 v80, v56, v119
	v_lshlrev_b32_e32 v97, 16, v18
	v_and_b32_e32 v159, s40, v18
	v_lshlrev_b32_e32 v187, 16, v19
	v_and_b32_e32 v44, s40, v19
	v_lshlrev_b32_e32 v45, 16, v20
	v_and_b32_e32 v46, s40, v20
	v_lshlrev_b32_e32 v47, 16, v21
	v_and_b32_e32 v48, s40, v21
	v_lshlrev_b32_e32 v49, 16, v22
	v_and_b32_e32 v50, s40, v22
	v_lshlrev_b32_e32 v51, 16, v23
	v_and_b32_e32 v52, s40, v23
	v_lshlrev_b32_e32 v53, 16, v24
	v_and_b32_e32 v54, s40, v24
	v_lshlrev_b32_e32 v55, 16, v25
	v_and_b32_e32 v56, s40, v25
	v_mul_f32_e32 v104, v97, v97
	v_mul_f32_e32 v81, v97, v248
	v_mul_f32_e32 v82, v97, v232
	v_mul_f32_e32 v83, v97, v216
	v_mul_f32_e32 v84, v97, v200
	v_mul_f32_e32 v85, v97, v182
	v_mul_f32_e32 v86, v97, v166
	v_mul_f32_e32 v87, v97, v146
	v_mul_f32_e32 v100, v97, v130
	v_fmac_f32_e32 v104, v159, v159
	v_fmac_f32_e32 v81, v159, v249
	v_fmac_f32_e32 v82, v159, v233
	v_fmac_f32_e32 v83, v159, v217
	v_fmac_f32_e32 v84, v159, v201
	v_fmac_f32_e32 v85, v159, v183
	v_fmac_f32_e32 v86, v159, v167
	v_fmac_f32_e32 v87, v159, v147
	v_fmac_f32_e32 v100, v159, v131
	v_fmac_f32_e32 v104, v187, v187
	v_fmac_f32_e32 v81, v187, v250
	v_fmac_f32_e32 v82, v187, v234
	v_fmac_f32_e32 v83, v187, v218
	v_fmac_f32_e32 v84, v187, v202
	v_fmac_f32_e32 v85, v187, v184
	v_fmac_f32_e32 v86, v187, v168
	v_fmac_f32_e32 v87, v187, v148
	v_fmac_f32_e32 v100, v187, v132
	v_fmac_f32_e32 v104, v44, v44
	v_fmac_f32_e32 v81, v44, v251
	v_fmac_f32_e32 v82, v44, v235
	v_fmac_f32_e32 v83, v44, v219
	v_fmac_f32_e32 v84, v44, v203
	v_fmac_f32_e32 v85, v44, v185
	v_fmac_f32_e32 v86, v44, v169
	v_fmac_f32_e32 v87, v44, v149
	v_fmac_f32_e32 v100, v44, v133
	v_fmac_f32_e32 v104, v45, v45
	v_fmac_f32_e32 v81, v45, v244
	v_fmac_f32_e32 v82, v45, v228
	v_fmac_f32_e32 v83, v45, v212
	v_fmac_f32_e32 v84, v45, v196
	v_fmac_f32_e32 v85, v45, v178
	v_fmac_f32_e32 v86, v45, v162
	v_fmac_f32_e32 v87, v45, v142
	v_fmac_f32_e32 v100, v45, v124
	v_fmac_f32_e32 v104, v46, v46
	v_fmac_f32_e32 v81, v46, v245
	v_fmac_f32_e32 v82, v46, v229
	v_fmac_f32_e32 v83, v46, v213
	v_fmac_f32_e32 v84, v46, v197
	v_fmac_f32_e32 v85, v46, v179
	v_fmac_f32_e32 v86, v46, v163
	v_fmac_f32_e32 v87, v46, v143
	v_fmac_f32_e32 v100, v46, v125
	v_fmac_f32_e32 v104, v47, v47
	v_fmac_f32_e32 v81, v47, v246
	v_fmac_f32_e32 v82, v47, v230
	v_fmac_f32_e32 v83, v47, v214
	v_fmac_f32_e32 v84, v47, v198
	v_fmac_f32_e32 v85, v47, v180
	v_fmac_f32_e32 v86, v47, v164
	v_fmac_f32_e32 v87, v47, v144
	v_fmac_f32_e32 v100, v47, v126
	v_fmac_f32_e32 v104, v48, v48
	v_fmac_f32_e32 v81, v48, v247
	v_fmac_f32_e32 v82, v48, v231
	v_fmac_f32_e32 v83, v48, v215
	v_fmac_f32_e32 v84, v48, v199
	v_fmac_f32_e32 v85, v48, v181
	v_fmac_f32_e32 v86, v48, v165
	v_fmac_f32_e32 v87, v48, v145
	v_fmac_f32_e32 v100, v48, v127
	v_fmac_f32_e32 v104, v49, v49
	v_fmac_f32_e32 v81, v49, v240
	v_fmac_f32_e32 v82, v49, v224
	v_fmac_f32_e32 v83, v49, v208
	v_fmac_f32_e32 v84, v49, v192
	v_fmac_f32_e32 v85, v49, v174
	v_fmac_f32_e32 v86, v49, v154
	v_fmac_f32_e32 v87, v49, v138
	v_fmac_f32_e32 v100, v49, v120
	v_fmac_f32_e32 v104, v50, v50
	v_fmac_f32_e32 v81, v50, v241
	v_fmac_f32_e32 v82, v50, v225
	v_fmac_f32_e32 v83, v50, v209
	v_fmac_f32_e32 v84, v50, v193
	v_fmac_f32_e32 v85, v50, v175
	v_fmac_f32_e32 v86, v50, v155
	v_fmac_f32_e32 v87, v50, v139
	v_fmac_f32_e32 v100, v50, v121
	v_fmac_f32_e32 v104, v51, v51
	v_fmac_f32_e32 v81, v51, v242
	v_fmac_f32_e32 v82, v51, v226
	v_fmac_f32_e32 v83, v51, v210
	v_fmac_f32_e32 v84, v51, v194
	v_fmac_f32_e32 v85, v51, v176
	v_fmac_f32_e32 v86, v51, v156
	v_fmac_f32_e32 v87, v51, v140
	v_fmac_f32_e32 v100, v51, v122
	v_fmac_f32_e32 v104, v52, v52
	v_fmac_f32_e32 v81, v52, v243
	v_fmac_f32_e32 v82, v52, v227
	v_fmac_f32_e32 v83, v52, v211
	v_fmac_f32_e32 v84, v52, v195
	v_fmac_f32_e32 v85, v52, v177
	v_fmac_f32_e32 v86, v52, v157
	v_fmac_f32_e32 v87, v52, v141
	v_fmac_f32_e32 v100, v52, v123
	v_fmac_f32_e32 v104, v53, v53
	v_fmac_f32_e32 v81, v53, v236
	v_fmac_f32_e32 v82, v53, v220
	v_fmac_f32_e32 v83, v53, v204
	v_fmac_f32_e32 v84, v53, v188
; __device__ __forceinline__ float lane_get(float v, int src_lane) { return __builtin_bit_cast(float, __builtin_amdgcn_ds_bpermute(src_lane << 2, __builtin_bit_cast(int, v))); }
; __device__ __forceinline__ void fgate_phase(const bfr* x, const float* wf, const float* bfg, float* cl, float* ctot, LAS float* scr, int bx, int G, int tid, int lane, int wave) {
;     ...
;             for (int h = 0; h < NH; ++h) { const f32x4* wr = (const f32x4*)(wf + h * D) + lane + zo; float da = 0.f, db = 0.f;
; #pragma unroll
;                 for (int jj = 0; jj < 4; ++jj) { const f32x4 w = wr[64 * jj]; da += (va[jj].x * w.x + va[jj].y * w.y) + (va[jj].z * w.z + va[jj].w * w.w); db += (vb[jj].x * w.x + vb[jj].y * w.y) + (vb[jj].z * w.z + vb[jj].w * w.w); }
;                 r[h] = da; r[8 + h] = db; }
; #pragma unroll
;             for (int o = 1; o < 64; o <<= 1) {
; #pragma unroll
;                 for (int q = 0; q < 18; ++q) r[q] += lane_get(r[q], lane ^ o); }
	v_fmac_f32_e32 v85, v53, v170
	v_fmac_f32_e32 v86, v53, v150
	v_fmac_f32_e32 v87, v53, v134
	v_fmac_f32_e32 v100, v53, v116
	v_fmac_f32_e32 v104, v54, v54
	v_fmac_f32_e32 v81, v54, v237
	v_fmac_f32_e32 v82, v54, v221
	v_fmac_f32_e32 v83, v54, v205
	v_fmac_f32_e32 v84, v54, v189
	v_fmac_f32_e32 v85, v54, v171
	v_fmac_f32_e32 v86, v54, v151
	v_fmac_f32_e32 v87, v54, v135
	v_fmac_f32_e32 v100, v54, v117
	v_fmac_f32_e32 v104, v55, v55
	v_fmac_f32_e32 v81, v55, v238
	v_fmac_f32_e32 v82, v55, v222
	v_fmac_f32_e32 v83, v55, v206
	v_fmac_f32_e32 v84, v55, v190
	v_fmac_f32_e32 v85, v55, v172
	v_fmac_f32_e32 v86, v55, v152
	v_fmac_f32_e32 v87, v55, v136
	v_fmac_f32_e32 v100, v55, v118
	v_fmac_f32_e32 v104, v56, v56
	v_fmac_f32_e32 v81, v56, v239
	v_fmac_f32_e32 v82, v56, v223
	v_fmac_f32_e32 v83, v56, v207
	v_fmac_f32_e32 v84, v56, v191
	v_fmac_f32_e32 v85, v56, v173
	v_fmac_f32_e32 v86, v56, v153
	v_fmac_f32_e32 v87, v56, v137
	v_fmac_f32_e32 v100, v56, v119
	v_lshl_add_u64 v[26:27], v[26:27], 0, s[100:101]
	v_lshl_add_u64 v[40:41], v[40:41], 0, s[100:101]
	global_load_dwordx2 v[38:39], v[26:27], off
	global_load_dwordx2 v[98:99], v[26:27], off offset:512
	global_load_dwordx2 v[160:161], v[26:27], off offset:1024
	global_load_dwordx2 v[0:1], v[26:27], off offset:1536
	global_load_dwordx2 v[2:3], v[26:27], off offset:2048
	global_load_dwordx2 v[4:5], v[26:27], off offset:2560
	global_load_dwordx2 v[6:7], v[26:27], off offset:3072
	global_load_dwordx2 v[8:9], v[26:27], off offset:3584
	global_load_dwordx2 v[10:11], v[40:41], off
	global_load_dwordx2 v[12:13], v[40:41], off offset:512
	global_load_dwordx2 v[14:15], v[40:41], off offset:1024
	global_load_dwordx2 v[16:17], v[40:41], off offset:1536
	global_load_dwordx2 v[18:19], v[40:41], off offset:2048
	global_load_dwordx2 v[20:21], v[40:41], off offset:2560
	global_load_dwordx2 v[22:23], v[40:41], off offset:3072
	global_load_dwordx2 v[24:25], v[40:41], off offset:3584
	s_nop 1
	v_permlane32_swap_b32_e32 v57, v73
	v_permlane32_swap_b32_e32 v58, v74
	v_permlane32_swap_b32_e32 v59, v75
	v_permlane32_swap_b32_e32 v60, v76
	v_permlane32_swap_b32_e32 v61, v77
	v_permlane32_swap_b32_e32 v62, v78
	v_permlane32_swap_b32_e32 v63, v79
	v_permlane32_swap_b32_e32 v64, v80
	v_permlane32_swap_b32_e32 v65, v81
	v_permlane32_swap_b32_e32 v66, v82
	v_permlane32_swap_b32_e32 v67, v83
	v_permlane32_swap_b32_e32 v68, v84
	v_permlane32_swap_b32_e32 v69, v85
	v_permlane32_swap_b32_e32 v70, v86
	v_permlane32_swap_b32_e32 v71, v87
	v_permlane32_swap_b32_e32 v72, v100
	v_permlane32_swap_b32_e32 v101, v103
	v_permlane32_swap_b32_e32 v102, v104
	s_nop 1
	v_add_f32_e32 v57, v57, v73
	v_add_f32_e32 v58, v58, v74
	v_add_f32_e32 v59, v59, v75
	v_add_f32_e32 v60, v60, v76
	v_add_f32_e32 v61, v61, v77
	v_add_f32_e32 v62, v62, v78
	v_add_f32_e32 v63, v63, v79
	v_add_f32_e32 v64, v64, v80
	v_add_f32_e32 v65, v65, v81
	v_add_f32_e32 v66, v66, v82
	v_add_f32_e32 v67, v67, v83
	v_add_f32_e32 v68, v68, v84
	v_add_f32_e32 v69, v69, v85
	v_add_f32_e32 v70, v70, v86
	v_add_f32_e32 v71, v71, v87
	v_add_f32_e32 v72, v72, v100
	v_add_f32_e32 v101, v101, v103
	v_add_f32_e32 v102, v102, v104
	s_nop 1
	v_permlane16_swap_b32_e32 v57, v65
	v_permlane16_swap_b32_e32 v58, v66
	v_permlane16_swap_b32_e32 v59, v67
	v_permlane16_swap_b32_e32 v60, v68
	v_permlane16_swap_b32_e32 v61, v69
	v_permlane16_swap_b32_e32 v62, v70
	v_permlane16_swap_b32_e32 v63, v71
	v_permlane16_swap_b32_e32 v64, v72
	v_permlane16_swap_b32_e32 v101, v102
	s_nop 1
	v_add_f32_e32 v57, v57, v65
	v_add_f32_e32 v58, v58, v66
	v_add_f32_e32 v59, v59, v67
	v_add_f32_e32 v60, v60, v68
	v_add_f32_e32 v61, v61, v69
	v_add_f32_e32 v62, v62, v70
	v_add_f32_e32 v63, v63, v71
	v_add_f32_e32 v64, v64, v72
	v_add_f32_e32 v101, v101, v102
	s_nop 1
	v_add_f32_dpp v57, v57, v57 quad_perm:[1,0,3,2] row_mask:0xf bank_mask:0xf
	v_add_f32_dpp v58, v58, v58 quad_perm:[1,0,3,2] row_mask:0xf bank_mask:0xf
	v_add_f32_dpp v59, v59, v59 quad_perm:[1,0,3,2] row_mask:0xf bank_mask:0xf
	v_add_f32_dpp v60, v60, v60 quad_perm:[1,0,3,2] row_mask:0xf bank_mask:0xf
	v_add_f32_dpp v61, v61, v61 quad_perm:[1,0,3,2] row_mask:0xf bank_mask:0xf
	v_add_f32_dpp v62, v62, v62 quad_perm:[1,0,3,2] row_mask:0xf bank_mask:0xf
	v_add_f32_dpp v63, v63, v63 quad_perm:[1,0,3,2] row_mask:0xf bank_mask:0xf
	v_add_f32_dpp v64, v64, v64 quad_perm:[1,0,3,2] row_mask:0xf bank_mask:0xf
	v_add_f32_dpp v101, v101, v101 quad_perm:[1,0,3,2] row_mask:0xf bank_mask:0xf
	s_nop 1
	v_add_f32_dpp v57, v57, v57 quad_perm:[2,3,0,1] row_mask:0xf bank_mask:0xf
	v_add_f32_dpp v58, v58, v58 quad_perm:[2,3,0,1] row_mask:0xf bank_mask:0xf
	v_add_f32_dpp v59, v59, v59 quad_perm:[2,3,0,1] row_mask:0xf bank_mask:0xf
	v_add_f32_dpp v60, v60, v60 quad_perm:[2,3,0,1] row_mask:0xf bank_mask:0xf
	v_add_f32_dpp v61, v61, v61 quad_perm:[2,3,0,1] row_mask:0xf bank_mask:0xf
	v_add_f32_dpp v62, v62, v62 quad_perm:[2,3,0,1] row_mask:0xf bank_mask:0xf
	v_add_f32_dpp v63, v63, v63 quad_perm:[2,3,0,1] row_mask:0xf bank_mask:0xf
	v_add_f32_dpp v64, v64, v64 quad_perm:[2,3,0,1] row_mask:0xf bank_mask:0xf
	v_add_f32_dpp v101, v101, v101 quad_perm:[2,3,0,1] row_mask:0xf bank_mask:0xf
	s_nop 1
	v_add_f32_dpp v57, v57, v57 row_half_mirror row_mask:0xf bank_mask:0xf
	v_add_f32_dpp v58, v58, v58 row_half_mirror row_mask:0xf bank_mask:0xf
	v_add_f32_dpp v59, v59, v59 row_half_mirror row_mask:0xf bank_mask:0xf
	v_add_f32_dpp v60, v60, v60 row_half_mirror row_mask:0xf bank_mask:0xf
	v_add_f32_dpp v61, v61, v61 row_half_mirror row_mask:0xf bank_mask:0xf
	v_add_f32_dpp v62, v62, v62 row_half_mirror row_mask:0xf bank_mask:0xf
	v_add_f32_dpp v63, v63, v63 row_half_mirror row_mask:0xf bank_mask:0xf
; __device__ __forceinline__ float lane_get(float v, int src_lane) { return __builtin_bit_cast(float, __builtin_amdgcn_ds_bpermute(src_lane << 2, __builtin_bit_cast(int, v))); }
; __device__ __forceinline__ void fgate_phase(const bfr* x, const float* wf, const float* bfg, float* cl, float* ctot, LAS float* scr, int bx, int G, int tid, int lane, int wave) {
;     ...
;             for (int jj = 0; jj < 4; ++jj) { const u32x2 wa = xa[64 * jj], wb = xb2[64 * jj]; va[jj] = (f32x4){bf_lo(wa.x), bf_hi(wa.x), bf_lo(wa.y), bf_hi(wa.y)}; vb[jj] = (f32x4){bf_lo(wb.x), bf_hi(wb.x), bf_lo(wb.y), bf_hi(wb.y)}; }
;             r[16] = 0.f; r[17] = 0.f;
; #pragma unroll
;             for (int jj = 0; jj < 4; ++jj) { r[16] += (va[jj].x * va[jj].x + va[jj].y * va[jj].y) + (va[jj].z * va[jj].z + va[jj].w * va[jj].w); r[17] += (vb[jj].x * vb[jj].x + vb[jj].y * vb[jj].y) + (vb[jj].z * vb[jj].z + vb[jj].w * vb[jj].w); }
; #pragma unroll
;             for (int h = 0; h < NH; ++h) { const f32x4* wr = (const f32x4*)(wf + h * D) + lane + zo; float da = 0.f, db = 0.f;
; #pragma unroll
;                 for (int jj = 0; jj < 4; ++jj) { const f32x4 w = wr[64 * jj]; da += (va[jj].x * w.x + va[jj].y * w.y) + (va[jj].z * w.z + va[jj].w * w.w); db += (vb[jj].x * w.x + vb[jj].y * w.y) + (vb[jj].z * w.z + vb[jj].w * w.w); }
;                 r[h] = da; r[8 + h] = db; }
;     ...
;             for (int o = 1; o < 64; o <<= 1) {
; #pragma unroll
;                 for (int q = 0; q < 18; ++q) r[q] += lane_get(r[q], lane ^ o); }
;             const float rsa = rsqrtf(r[16] * (1.f / D) + EPS), rsb = rsqrtf(r[17] * (1.f / D) + EPS);
;             if (lane < 16) { const int h = lane & 7; float dsel = r[0];
; #pragma unroll
;                 for (int q = 1; q < 16; ++q) dsel = (lane == q) ? r[q] : dsel;
;                 const float zz = dsel * (lane < 8 ? rsa : rsb) + bfg[h]; const float lf = fminf(zz, 0.f) - 0.6931471805599453f * __builtin_amdgcn_logf(1.0f + __builtin_amdgcn_exp2f(-LOG2E * fabsf(zz)));
;                 scr[(wave * 8 + j + (lane >> 3)) * 8 + h] = lf; } }
	v_add_f32_dpp v64, v64, v64 row_half_mirror row_mask:0xf bank_mask:0xf
	v_add_f32_dpp v101, v101, v101 row_half_mirror row_mask:0xf bank_mask:0xf
	s_nop 1
	v_add_f32_dpp v57, v57, v57 row_mirror row_mask:0xf bank_mask:0xf
	v_add_f32_dpp v58, v58, v58 row_mirror row_mask:0xf bank_mask:0xf
	v_add_f32_dpp v59, v59, v59 row_mirror row_mask:0xf bank_mask:0xf
	v_add_f32_dpp v60, v60, v60 row_mirror row_mask:0xf bank_mask:0xf
	v_add_f32_dpp v61, v61, v61 row_mirror row_mask:0xf bank_mask:0xf
	v_add_f32_dpp v62, v62, v62 row_mirror row_mask:0xf bank_mask:0xf
	v_add_f32_dpp v63, v63, v63 row_mirror row_mask:0xf bank_mask:0xf
	v_add_f32_dpp v64, v64, v64 row_mirror row_mask:0xf bank_mask:0xf
	v_add_f32_dpp v101, v101, v101 row_mirror row_mask:0xf bank_mask:0xf
	s_nop 1
	v_mov_b32_e32 v106, v57
	v_cndmask_b32_e64 v106, v106, v58, s[6:7]
	v_cndmask_b32_e64 v106, v106, v59, s[8:9]
	v_cndmask_b32_e64 v106, v106, v60, s[10:11]
	v_cndmask_b32_e64 v106, v106, v61, s[12:13]
	v_cndmask_b32_e64 v106, v106, v62, s[14:15]
	v_cndmask_b32_e64 v106, v106, v63, s[16:17]
	v_cndmask_b32_e64 v106, v106, v64, s[18:19]
	v_mul_f32_e32 v107, 0x3a800000, v101
	v_add_f32_e32 v107, 0x358637bd, v107
	v_rsq_f32_e32 v107, v107
	s_nop 0
	v_fma_f32 v106, v106, v107, v105
	v_mul_f32_e64 v107, |v106|, s65
	v_exp_f32_e32 v107, v107
	v_min_f32_e32 v106, 0, v106
	v_add_f32_e32 v107, 1.0, v107
	v_log_f32_e32 v107, v107
	s_nop 0
	v_fmac_f32_e32 v106, 0xbf317218, v107
	s_mov_b64 s[54:55], exec
	s_mov_b32 exec_lo, 0xff00ff
	s_mov_b32 exec_hi, 0xff00ff
	ds_write_b32 v109, v106
	s_mov_b64 exec, s[54:55]
	s_waitcnt vmcnt(0)
	v_lshlrev_b32_e32 v97, 16, v38
	v_and_b32_e32 v159, s40, v38
	v_lshlrev_b32_e32 v187, 16, v39
	v_and_b32_e32 v44, s40, v39
	v_lshlrev_b32_e32 v45, 16, v98
	v_and_b32_e32 v46, s40, v98
	v_lshlrev_b32_e32 v47, 16, v99
	v_and_b32_e32 v48, s40, v99
	v_lshlrev_b32_e32 v49, 16, v160
	v_and_b32_e32 v50, s40, v160
	v_lshlrev_b32_e32 v51, 16, v161
	v_and_b32_e32 v52, s40, v161
	v_lshlrev_b32_e32 v53, 16, v0
	v_and_b32_e32 v54, s40, v0
	v_lshlrev_b32_e32 v55, 16, v1
	v_and_b32_e32 v56, s40, v1
	v_mul_f32_e32 v101, v97, v97
	v_mul_f32_e32 v57, v97, v248
	v_mul_f32_e32 v58, v97, v232
	v_mul_f32_e32 v59, v97, v216
	v_mul_f32_e32 v60, v97, v200
	v_mul_f32_e32 v61, v97, v182
	v_mul_f32_e32 v62, v97, v166
	v_mul_f32_e32 v63, v97, v146
	v_mul_f32_e32 v64, v97, v130
	v_fmac_f32_e32 v101, v159, v159
	v_fmac_f32_e32 v57, v159, v249
	v_fmac_f32_e32 v58, v159, v233
	v_fmac_f32_e32 v59, v159, v217
	v_fmac_f32_e32 v60, v159, v201
	v_fmac_f32_e32 v61, v159, v183
	v_fmac_f32_e32 v62, v159, v167
	v_fmac_f32_e32 v63, v159, v147
	v_fmac_f32_e32 v64, v159, v131
	v_fmac_f32_e32 v101, v187, v187
	v_fmac_f32_e32 v57, v187, v250
	v_fmac_f32_e32 v58, v187, v234
	v_fmac_f32_e32 v59, v187, v218
	v_fmac_f32_e32 v60, v187, v202
	v_fmac_f32_e32 v61, v187, v184
	v_fmac_f32_e32 v62, v187, v168
	v_fmac_f32_e32 v63, v187, v148
	v_fmac_f32_e32 v64, v187, v132
	v_fmac_f32_e32 v101, v44, v44
	v_fmac_f32_e32 v57, v44, v251
	v_fmac_f32_e32 v58, v44, v235
	v_fmac_f32_e32 v59, v44, v219
	v_fmac_f32_e32 v60, v44, v203
	v_fmac_f32_e32 v61, v44, v185
	v_fmac_f32_e32 v62, v44, v169
	v_fmac_f32_e32 v63, v44, v149
	v_fmac_f32_e32 v64, v44, v133
	v_fmac_f32_e32 v101, v45, v45
	v_fmac_f32_e32 v57, v45, v244
	v_fmac_f32_e32 v58, v45, v228
	v_fmac_f32_e32 v59, v45, v212
	v_fmac_f32_e32 v60, v45, v196
	v_fmac_f32_e32 v61, v45, v178
	v_fmac_f32_e32 v62, v45, v162
	v_fmac_f32_e32 v63, v45, v142
	v_fmac_f32_e32 v64, v45, v124
	v_fmac_f32_e32 v101, v46, v46
	v_fmac_f32_e32 v57, v46, v245
	v_fmac_f32_e32 v58, v46, v229
	v_fmac_f32_e32 v59, v46, v213
	v_fmac_f32_e32 v60, v46, v197
	v_fmac_f32_e32 v61, v46, v179
	v_fmac_f32_e32 v62, v46, v163
	v_fmac_f32_e32 v63, v46, v143
	v_fmac_f32_e32 v64, v46, v125
	v_fmac_f32_e32 v101, v47, v47
	v_fmac_f32_e32 v57, v47, v246
	v_fmac_f32_e32 v58, v47, v230
	v_fmac_f32_e32 v59, v47, v214
	v_fmac_f32_e32 v60, v47, v198
	v_fmac_f32_e32 v61, v47, v180
	v_fmac_f32_e32 v62, v47, v164
	v_fmac_f32_e32 v63, v47, v144
	v_fmac_f32_e32 v64, v47, v126
	v_fmac_f32_e32 v101, v48, v48
	v_fmac_f32_e32 v57, v48, v247
	v_fmac_f32_e32 v58, v48, v231
	v_fmac_f32_e32 v59, v48, v215
	v_fmac_f32_e32 v60, v48, v199
	v_fmac_f32_e32 v61, v48, v181
	v_fmac_f32_e32 v62, v48, v165
	v_fmac_f32_e32 v63, v48, v145
	v_fmac_f32_e32 v64, v48, v127
	v_fmac_f32_e32 v101, v49, v49
	v_fmac_f32_e32 v57, v49, v240
	v_fmac_f32_e32 v58, v49, v224
	v_fmac_f32_e32 v59, v49, v208
	v_fmac_f32_e32 v60, v49, v192
	v_fmac_f32_e32 v61, v49, v174
	v_fmac_f32_e32 v62, v49, v154
	v_fmac_f32_e32 v63, v49, v138
	v_fmac_f32_e32 v64, v49, v120
	v_fmac_f32_e32 v101, v50, v50
	v_fmac_f32_e32 v57, v50, v241
	v_fmac_f32_e32 v58, v50, v225
	v_fmac_f32_e32 v59, v50, v209
	v_fmac_f32_e32 v60, v50, v193
	v_fmac_f32_e32 v61, v50, v175
	v_fmac_f32_e32 v62, v50, v155
	v_fmac_f32_e32 v63, v50, v139
	v_fmac_f32_e32 v64, v50, v121
	v_fmac_f32_e32 v101, v51, v51
	v_fmac_f32_e32 v57, v51, v242
	v_fmac_f32_e32 v58, v51, v226
	v_fmac_f32_e32 v59, v51, v210
	v_fmac_f32_e32 v60, v51, v194
	v_fmac_f32_e32 v61, v51, v176
	v_fmac_f32_e32 v62, v51, v156
	v_fmac_f32_e32 v63, v51, v140
	v_fmac_f32_e32 v64, v51, v122
	v_fmac_f32_e32 v101, v52, v52
	v_fmac_f32_e32 v57, v52, v243
	v_fmac_f32_e32 v58, v52, v227
	v_fmac_f32_e32 v59, v52, v211
	v_fmac_f32_e32 v60, v52, v195
	v_fmac_f32_e32 v61, v52, v177
	v_fmac_f32_e32 v62, v52, v157
	v_fmac_f32_e32 v63, v52, v141
	v_fmac_f32_e32 v64, v52, v123
	v_fmac_f32_e32 v101, v53, v53
	v_fmac_f32_e32 v57, v53, v236
	v_fmac_f32_e32 v58, v53, v220
	v_fmac_f32_e32 v59, v53, v204
	v_fmac_f32_e32 v60, v53, v188
	v_fmac_f32_e32 v61, v53, v170
; __device__ __forceinline__ void fgate_phase(const bfr* x, const float* wf, const float* bfg, float* cl, float* ctot, LAS float* scr, int bx, int G, int tid, int lane, int wave) {
;     ...
;             for (int jj = 0; jj < 4; ++jj) { const u32x2 wa = xa[64 * jj], wb = xb2[64 * jj]; va[jj] = (f32x4){bf_lo(wa.x), bf_hi(wa.x), bf_lo(wa.y), bf_hi(wa.y)}; vb[jj] = (f32x4){bf_lo(wb.x), bf_hi(wb.x), bf_lo(wb.y), bf_hi(wb.y)}; }
;             r[16] = 0.f; r[17] = 0.f;
; #pragma unroll
;             for (int jj = 0; jj < 4; ++jj) { r[16] += (va[jj].x * va[jj].x + va[jj].y * va[jj].y) + (va[jj].z * va[jj].z + va[jj].w * va[jj].w); r[17] += (vb[jj].x * vb[jj].x + vb[jj].y * vb[jj].y) + (vb[jj].z * vb[jj].z + vb[jj].w * vb[jj].w); }
; #pragma unroll
;             for (int h = 0; h < NH; ++h) { const f32x4* wr = (const f32x4*)(wf + h * D) + lane + zo; float da = 0.f, db = 0.f;
; #pragma unroll
;                 for (int jj = 0; jj < 4; ++jj) { const f32x4 w = wr[64 * jj]; da += (va[jj].x * w.x + va[jj].y * w.y) + (va[jj].z * w.z + va[jj].w * w.w); db += (vb[jj].x * w.x + vb[jj].y * w.y) + (vb[jj].z * w.z + vb[jj].w * w.w); }
;                 r[h] = da; r[8 + h] = db; }
	v_fmac_f32_e32 v62, v53, v150
	v_fmac_f32_e32 v63, v53, v134
	v_fmac_f32_e32 v64, v53, v116
	v_fmac_f32_e32 v101, v54, v54
	v_fmac_f32_e32 v57, v54, v237
	v_fmac_f32_e32 v58, v54, v221
	v_fmac_f32_e32 v59, v54, v205
	v_fmac_f32_e32 v60, v54, v189
	v_fmac_f32_e32 v61, v54, v171
	v_fmac_f32_e32 v62, v54, v151
	v_fmac_f32_e32 v63, v54, v135
	v_fmac_f32_e32 v64, v54, v117
	v_fmac_f32_e32 v101, v55, v55
	v_fmac_f32_e32 v57, v55, v238
	v_fmac_f32_e32 v58, v55, v222
	v_fmac_f32_e32 v59, v55, v206
	v_fmac_f32_e32 v60, v55, v190
	v_fmac_f32_e32 v61, v55, v172
	v_fmac_f32_e32 v62, v55, v152
	v_fmac_f32_e32 v63, v55, v136
	v_fmac_f32_e32 v64, v55, v118
	v_fmac_f32_e32 v101, v56, v56
	v_fmac_f32_e32 v57, v56, v239
	v_fmac_f32_e32 v58, v56, v223
	v_fmac_f32_e32 v59, v56, v207
	v_fmac_f32_e32 v60, v56, v191
	v_fmac_f32_e32 v61, v56, v173
	v_fmac_f32_e32 v62, v56, v153
	v_fmac_f32_e32 v63, v56, v137
	v_fmac_f32_e32 v64, v56, v119
	v_lshlrev_b32_e32 v97, 16, v2
	v_and_b32_e32 v159, s40, v2
	v_lshlrev_b32_e32 v187, 16, v3
	v_and_b32_e32 v44, s40, v3
	v_lshlrev_b32_e32 v45, 16, v4
	v_and_b32_e32 v46, s40, v4
	v_lshlrev_b32_e32 v47, 16, v5
	v_and_b32_e32 v48, s40, v5
	v_lshlrev_b32_e32 v49, 16, v6
	v_and_b32_e32 v50, s40, v6
	v_lshlrev_b32_e32 v51, 16, v7
	v_and_b32_e32 v52, s40, v7
	v_lshlrev_b32_e32 v53, 16, v8
	v_and_b32_e32 v54, s40, v8
	v_lshlrev_b32_e32 v55, 16, v9
	v_and_b32_e32 v56, s40, v9
	v_mul_f32_e32 v102, v97, v97
	v_mul_f32_e32 v65, v97, v248
	v_mul_f32_e32 v66, v97, v232
	v_mul_f32_e32 v67, v97, v216
	v_mul_f32_e32 v68, v97, v200
	v_mul_f32_e32 v69, v97, v182
	v_mul_f32_e32 v70, v97, v166
	v_mul_f32_e32 v71, v97, v146
	v_mul_f32_e32 v72, v97, v130
	v_fmac_f32_e32 v102, v159, v159
	v_fmac_f32_e32 v65, v159, v249
	v_fmac_f32_e32 v66, v159, v233
	v_fmac_f32_e32 v67, v159, v217
	v_fmac_f32_e32 v68, v159, v201
	v_fmac_f32_e32 v69, v159, v183
	v_fmac_f32_e32 v70, v159, v167
	v_fmac_f32_e32 v71, v159, v147
	v_fmac_f32_e32 v72, v159, v131
	v_fmac_f32_e32 v102, v187, v187
	v_fmac_f32_e32 v65, v187, v250
	v_fmac_f32_e32 v66, v187, v234
	v_fmac_f32_e32 v67, v187, v218
	v_fmac_f32_e32 v68, v187, v202
	v_fmac_f32_e32 v69, v187, v184
	v_fmac_f32_e32 v70, v187, v168
	v_fmac_f32_e32 v71, v187, v148
	v_fmac_f32_e32 v72, v187, v132
	v_fmac_f32_e32 v102, v44, v44
	v_fmac_f32_e32 v65, v44, v251
	v_fmac_f32_e32 v66, v44, v235
	v_fmac_f32_e32 v67, v44, v219
	v_fmac_f32_e32 v68, v44, v203
	v_fmac_f32_e32 v69, v44, v185
	v_fmac_f32_e32 v70, v44, v169
	v_fmac_f32_e32 v71, v44, v149
	v_fmac_f32_e32 v72, v44, v133
	v_fmac_f32_e32 v102, v45, v45
	v_fmac_f32_e32 v65, v45, v244
	v_fmac_f32_e32 v66, v45, v228
	v_fmac_f32_e32 v67, v45, v212
	v_fmac_f32_e32 v68, v45, v196
	v_fmac_f32_e32 v69, v45, v178
	v_fmac_f32_e32 v70, v45, v162
	v_fmac_f32_e32 v71, v45, v142
	v_fmac_f32_e32 v72, v45, v124
	v_fmac_f32_e32 v102, v46, v46
	v_fmac_f32_e32 v65, v46, v245
	v_fmac_f32_e32 v66, v46, v229
	v_fmac_f32_e32 v67, v46, v213
	v_fmac_f32_e32 v68, v46, v197
	v_fmac_f32_e32 v69, v46, v179
	v_fmac_f32_e32 v70, v46, v163
	v_fmac_f32_e32 v71, v46, v143
	v_fmac_f32_e32 v72, v46, v125
	v_fmac_f32_e32 v102, v47, v47
	v_fmac_f32_e32 v65, v47, v246
	v_fmac_f32_e32 v66, v47, v230
	v_fmac_f32_e32 v67, v47, v214
	v_fmac_f32_e32 v68, v47, v198
	v_fmac_f32_e32 v69, v47, v180
	v_fmac_f32_e32 v70, v47, v164
	v_fmac_f32_e32 v71, v47, v144
	v_fmac_f32_e32 v72, v47, v126
	v_fmac_f32_e32 v102, v48, v48
	v_fmac_f32_e32 v65, v48, v247
	v_fmac_f32_e32 v66, v48, v231
	v_fmac_f32_e32 v67, v48, v215
	v_fmac_f32_e32 v68, v48, v199
	v_fmac_f32_e32 v69, v48, v181
	v_fmac_f32_e32 v70, v48, v165
	v_fmac_f32_e32 v71, v48, v145
	v_fmac_f32_e32 v72, v48, v127
	v_fmac_f32_e32 v102, v49, v49
	v_fmac_f32_e32 v65, v49, v240
	v_fmac_f32_e32 v66, v49, v224
	v_fmac_f32_e32 v67, v49, v208
	v_fmac_f32_e32 v68, v49, v192
	v_fmac_f32_e32 v69, v49, v174
	v_fmac_f32_e32 v70, v49, v154
	v_fmac_f32_e32 v71, v49, v138
	v_fmac_f32_e32 v72, v49, v120
	v_fmac_f32_e32 v102, v50, v50
	v_fmac_f32_e32 v65, v50, v241
	v_fmac_f32_e32 v66, v50, v225
	v_fmac_f32_e32 v67, v50, v209
	v_fmac_f32_e32 v68, v50, v193
	v_fmac_f32_e32 v69, v50, v175
	v_fmac_f32_e32 v70, v50, v155
	v_fmac_f32_e32 v71, v50, v139
	v_fmac_f32_e32 v72, v50, v121
	v_fmac_f32_e32 v102, v51, v51
	v_fmac_f32_e32 v65, v51, v242
	v_fmac_f32_e32 v66, v51, v226
	v_fmac_f32_e32 v67, v51, v210
	v_fmac_f32_e32 v68, v51, v194
	v_fmac_f32_e32 v69, v51, v176
	v_fmac_f32_e32 v70, v51, v156
	v_fmac_f32_e32 v71, v51, v140
	v_fmac_f32_e32 v72, v51, v122
	v_fmac_f32_e32 v102, v52, v52
	v_fmac_f32_e32 v65, v52, v243
	v_fmac_f32_e32 v66, v52, v227
	v_fmac_f32_e32 v67, v52, v211
	v_fmac_f32_e32 v68, v52, v195
	v_fmac_f32_e32 v69, v52, v177
	v_fmac_f32_e32 v70, v52, v157
	v_fmac_f32_e32 v71, v52, v141
	v_fmac_f32_e32 v72, v52, v123
	v_fmac_f32_e32 v102, v53, v53
	v_fmac_f32_e32 v65, v53, v236
	v_fmac_f32_e32 v66, v53, v220
	v_fmac_f32_e32 v67, v53, v204
	v_fmac_f32_e32 v68, v53, v188
	v_fmac_f32_e32 v69, v53, v170
	v_fmac_f32_e32 v70, v53, v150
	v_fmac_f32_e32 v71, v53, v134
	v_fmac_f32_e32 v72, v53, v116
	v_fmac_f32_e32 v102, v54, v54
	v_fmac_f32_e32 v65, v54, v237
	v_fmac_f32_e32 v66, v54, v221
	v_fmac_f32_e32 v67, v54, v205
	v_fmac_f32_e32 v68, v54, v189
	v_fmac_f32_e32 v69, v54, v171
	v_fmac_f32_e32 v70, v54, v151
	v_fmac_f32_e32 v71, v54, v135
	v_fmac_f32_e32 v72, v54, v117
	v_fmac_f32_e32 v102, v55, v55
	v_fmac_f32_e32 v65, v55, v238
	v_fmac_f32_e32 v66, v55, v222
	v_fmac_f32_e32 v67, v55, v206
	v_fmac_f32_e32 v68, v55, v190
	v_fmac_f32_e32 v69, v55, v172
	v_fmac_f32_e32 v70, v55, v152
	v_fmac_f32_e32 v71, v55, v136
	v_fmac_f32_e32 v72, v55, v118
	v_fmac_f32_e32 v102, v56, v56
; __device__ __forceinline__ void fgate_phase(const bfr* x, const float* wf, const float* bfg, float* cl, float* ctot, LAS float* scr, int bx, int G, int tid, int lane, int wave) {
;     ...
;             for (int jj = 0; jj < 4; ++jj) { const u32x2 wa = xa[64 * jj], wb = xb2[64 * jj]; va[jj] = (f32x4){bf_lo(wa.x), bf_hi(wa.x), bf_lo(wa.y), bf_hi(wa.y)}; vb[jj] = (f32x4){bf_lo(wb.x), bf_hi(wb.x), bf_lo(wb.y), bf_hi(wb.y)}; }
;             r[16] = 0.f; r[17] = 0.f;
; #pragma unroll
;             for (int jj = 0; jj < 4; ++jj) { r[16] += (va[jj].x * va[jj].x + va[jj].y * va[jj].y) + (va[jj].z * va[jj].z + va[jj].w * va[jj].w); r[17] += (vb[jj].x * vb[jj].x + vb[jj].y * vb[jj].y) + (vb[jj].z * vb[jj].z + vb[jj].w * vb[jj].w); }
; #pragma unroll
;             for (int h = 0; h < NH; ++h) { const f32x4* wr = (const f32x4*)(wf + h * D) + lane + zo; float da = 0.f, db = 0.f;
; #pragma unroll
;                 for (int jj = 0; jj < 4; ++jj) { const f32x4 w = wr[64 * jj]; da += (va[jj].x * w.x + va[jj].y * w.y) + (va[jj].z * w.z + va[jj].w * w.w); db += (vb[jj].x * w.x + vb[jj].y * w.y) + (vb[jj].z * w.z + vb[jj].w * w.w); }
;                 r[h] = da; r[8 + h] = db; }
	v_fmac_f32_e32 v65, v56, v239
	v_fmac_f32_e32 v66, v56, v223
	v_fmac_f32_e32 v67, v56, v207
	v_fmac_f32_e32 v68, v56, v191
	v_fmac_f32_e32 v69, v56, v173
	v_fmac_f32_e32 v70, v56, v153
	v_fmac_f32_e32 v71, v56, v137
	v_fmac_f32_e32 v72, v56, v119
	v_lshlrev_b32_e32 v97, 16, v10
	v_and_b32_e32 v159, s40, v10
	v_lshlrev_b32_e32 v187, 16, v11
	v_and_b32_e32 v44, s40, v11
	v_lshlrev_b32_e32 v45, 16, v12
	v_and_b32_e32 v46, s40, v12
	v_lshlrev_b32_e32 v47, 16, v13
	v_and_b32_e32 v48, s40, v13
	v_lshlrev_b32_e32 v49, 16, v14
	v_and_b32_e32 v50, s40, v14
	v_lshlrev_b32_e32 v51, 16, v15
	v_and_b32_e32 v52, s40, v15
	v_lshlrev_b32_e32 v53, 16, v16
	v_and_b32_e32 v54, s40, v16
	v_lshlrev_b32_e32 v55, 16, v17
	v_and_b32_e32 v56, s40, v17
	v_mul_f32_e32 v103, v97, v97
	v_mul_f32_e32 v73, v97, v248
	v_mul_f32_e32 v74, v97, v232
	v_mul_f32_e32 v75, v97, v216
	v_mul_f32_e32 v76, v97, v200
	v_mul_f32_e32 v77, v97, v182
	v_mul_f32_e32 v78, v97, v166
	v_mul_f32_e32 v79, v97, v146
	v_mul_f32_e32 v80, v97, v130
	v_fmac_f32_e32 v103, v159, v159
	v_fmac_f32_e32 v73, v159, v249
	v_fmac_f32_e32 v74, v159, v233
	v_fmac_f32_e32 v75, v159, v217
	v_fmac_f32_e32 v76, v159, v201
	v_fmac_f32_e32 v77, v159, v183
	v_fmac_f32_e32 v78, v159, v167
	v_fmac_f32_e32 v79, v159, v147
	v_fmac_f32_e32 v80, v159, v131
	v_fmac_f32_e32 v103, v187, v187
	v_fmac_f32_e32 v73, v187, v250
	v_fmac_f32_e32 v74, v187, v234
	v_fmac_f32_e32 v75, v187, v218
	v_fmac_f32_e32 v76, v187, v202
	v_fmac_f32_e32 v77, v187, v184
	v_fmac_f32_e32 v78, v187, v168
	v_fmac_f32_e32 v79, v187, v148
	v_fmac_f32_e32 v80, v187, v132
	v_fmac_f32_e32 v103, v44, v44
	v_fmac_f32_e32 v73, v44, v251
	v_fmac_f32_e32 v74, v44, v235
	v_fmac_f32_e32 v75, v44, v219
	v_fmac_f32_e32 v76, v44, v203
	v_fmac_f32_e32 v77, v44, v185
	v_fmac_f32_e32 v78, v44, v169
	v_fmac_f32_e32 v79, v44, v149
	v_fmac_f32_e32 v80, v44, v133
	v_fmac_f32_e32 v103, v45, v45
	v_fmac_f32_e32 v73, v45, v244
	v_fmac_f32_e32 v74, v45, v228
	v_fmac_f32_e32 v75, v45, v212
	v_fmac_f32_e32 v76, v45, v196
	v_fmac_f32_e32 v77, v45, v178
	v_fmac_f32_e32 v78, v45, v162
	v_fmac_f32_e32 v79, v45, v142
	v_fmac_f32_e32 v80, v45, v124
	v_fmac_f32_e32 v103, v46, v46
	v_fmac_f32_e32 v73, v46, v245
	v_fmac_f32_e32 v74, v46, v229
	v_fmac_f32_e32 v75, v46, v213
	v_fmac_f32_e32 v76, v46, v197
	v_fmac_f32_e32 v77, v46, v179
	v_fmac_f32_e32 v78, v46, v163
	v_fmac_f32_e32 v79, v46, v143
	v_fmac_f32_e32 v80, v46, v125
	v_fmac_f32_e32 v103, v47, v47
	v_fmac_f32_e32 v73, v47, v246
	v_fmac_f32_e32 v74, v47, v230
	v_fmac_f32_e32 v75, v47, v214
	v_fmac_f32_e32 v76, v47, v198
	v_fmac_f32_e32 v77, v47, v180
	v_fmac_f32_e32 v78, v47, v164
	v_fmac_f32_e32 v79, v47, v144
	v_fmac_f32_e32 v80, v47, v126
	v_fmac_f32_e32 v103, v48, v48
	v_fmac_f32_e32 v73, v48, v247
	v_fmac_f32_e32 v74, v48, v231
	v_fmac_f32_e32 v75, v48, v215
	v_fmac_f32_e32 v76, v48, v199
	v_fmac_f32_e32 v77, v48, v181
	v_fmac_f32_e32 v78, v48, v165
	v_fmac_f32_e32 v79, v48, v145
	v_fmac_f32_e32 v80, v48, v127
	v_fmac_f32_e32 v103, v49, v49
	v_fmac_f32_e32 v73, v49, v240
	v_fmac_f32_e32 v74, v49, v224
	v_fmac_f32_e32 v75, v49, v208
	v_fmac_f32_e32 v76, v49, v192
	v_fmac_f32_e32 v77, v49, v174
	v_fmac_f32_e32 v78, v49, v154
	v_fmac_f32_e32 v79, v49, v138
	v_fmac_f32_e32 v80, v49, v120
	v_fmac_f32_e32 v103, v50, v50
	v_fmac_f32_e32 v73, v50, v241
	v_fmac_f32_e32 v74, v50, v225
	v_fmac_f32_e32 v75, v50, v209
	v_fmac_f32_e32 v76, v50, v193
	v_fmac_f32_e32 v77, v50, v175
	v_fmac_f32_e32 v78, v50, v155
	v_fmac_f32_e32 v79, v50, v139
	v_fmac_f32_e32 v80, v50, v121
	v_fmac_f32_e32 v103, v51, v51
	v_fmac_f32_e32 v73, v51, v242
	v_fmac_f32_e32 v74, v51, v226
	v_fmac_f32_e32 v75, v51, v210
	v_fmac_f32_e32 v76, v51, v194
	v_fmac_f32_e32 v77, v51, v176
	v_fmac_f32_e32 v78, v51, v156
	v_fmac_f32_e32 v79, v51, v140
	v_fmac_f32_e32 v80, v51, v122
	v_fmac_f32_e32 v103, v52, v52
	v_fmac_f32_e32 v73, v52, v243
	v_fmac_f32_e32 v74, v52, v227
	v_fmac_f32_e32 v75, v52, v211
	v_fmac_f32_e32 v76, v52, v195
	v_fmac_f32_e32 v77, v52, v177
	v_fmac_f32_e32 v78, v52, v157
	v_fmac_f32_e32 v79, v52, v141
	v_fmac_f32_e32 v80, v52, v123
	v_fmac_f32_e32 v103, v53, v53
	v_fmac_f32_e32 v73, v53, v236
	v_fmac_f32_e32 v74, v53, v220
	v_fmac_f32_e32 v75, v53, v204
	v_fmac_f32_e32 v76, v53, v188
	v_fmac_f32_e32 v77, v53, v170
	v_fmac_f32_e32 v78, v53, v150
	v_fmac_f32_e32 v79, v53, v134
	v_fmac_f32_e32 v80, v53, v116
	v_fmac_f32_e32 v103, v54, v54
	v_fmac_f32_e32 v73, v54, v237
	v_fmac_f32_e32 v74, v54, v221
	v_fmac_f32_e32 v75, v54, v205
	v_fmac_f32_e32 v76, v54, v189
	v_fmac_f32_e32 v77, v54, v171
	v_fmac_f32_e32 v78, v54, v151
	v_fmac_f32_e32 v79, v54, v135
	v_fmac_f32_e32 v80, v54, v117
	v_fmac_f32_e32 v103, v55, v55
	v_fmac_f32_e32 v73, v55, v238
	v_fmac_f32_e32 v74, v55, v222
	v_fmac_f32_e32 v75, v55, v206
	v_fmac_f32_e32 v76, v55, v190
	v_fmac_f32_e32 v77, v55, v172
	v_fmac_f32_e32 v78, v55, v152
	v_fmac_f32_e32 v79, v55, v136
	v_fmac_f32_e32 v80, v55, v118
	v_fmac_f32_e32 v103, v56, v56
	v_fmac_f32_e32 v73, v56, v239
	v_fmac_f32_e32 v74, v56, v223
	v_fmac_f32_e32 v75, v56, v207
	v_fmac_f32_e32 v76, v56, v191
	v_fmac_f32_e32 v77, v56, v173
	v_fmac_f32_e32 v78, v56, v153
	v_fmac_f32_e32 v79, v56, v137
	v_fmac_f32_e32 v80, v56, v119
	v_lshlrev_b32_e32 v97, 16, v18
	v_and_b32_e32 v159, s40, v18
	v_lshlrev_b32_e32 v187, 16, v19
	v_and_b32_e32 v44, s40, v19
	v_lshlrev_b32_e32 v45, 16, v20
	v_and_b32_e32 v46, s40, v20
	v_lshlrev_b32_e32 v47, 16, v21
	v_and_b32_e32 v48, s40, v21
	v_lshlrev_b32_e32 v49, 16, v22
	v_and_b32_e32 v50, s40, v22
	v_lshlrev_b32_e32 v51, 16, v23
	v_and_b32_e32 v52, s40, v23
	v_lshlrev_b32_e32 v53, 16, v24
	v_and_b32_e32 v54, s40, v24
; __device__ __forceinline__ float lane_get(float v, int src_lane) { return __builtin_bit_cast(float, __builtin_amdgcn_ds_bpermute(src_lane << 2, __builtin_bit_cast(int, v))); }
; __device__ __forceinline__ void fgate_phase(const bfr* x, const float* wf, const float* bfg, float* cl, float* ctot, LAS float* scr, int bx, int G, int tid, int lane, int wave) {
;     ...
;             for (int h = 0; h < NH; ++h) { const f32x4* wr = (const f32x4*)(wf + h * D) + lane + zo; float da = 0.f, db = 0.f;
; #pragma unroll
;                 for (int jj = 0; jj < 4; ++jj) { const f32x4 w = wr[64 * jj]; da += (va[jj].x * w.x + va[jj].y * w.y) + (va[jj].z * w.z + va[jj].w * w.w); db += (vb[jj].x * w.x + vb[jj].y * w.y) + (vb[jj].z * w.z + vb[jj].w * w.w); }
;                 r[h] = da; r[8 + h] = db; }
; #pragma unroll
;             for (int o = 1; o < 64; o <<= 1) {
; #pragma unroll
;                 for (int q = 0; q < 18; ++q) r[q] += lane_get(r[q], lane ^ o); }
	v_lshlrev_b32_e32 v55, 16, v25
	v_and_b32_e32 v56, s40, v25
	v_mul_f32_e32 v104, v97, v97
	v_mul_f32_e32 v81, v97, v248
	v_mul_f32_e32 v82, v97, v232
	v_mul_f32_e32 v83, v97, v216
	v_mul_f32_e32 v84, v97, v200
	v_mul_f32_e32 v85, v97, v182
	v_mul_f32_e32 v86, v97, v166
	v_mul_f32_e32 v87, v97, v146
	v_mul_f32_e32 v100, v97, v130
	v_fmac_f32_e32 v104, v159, v159
	v_fmac_f32_e32 v81, v159, v249
	v_fmac_f32_e32 v82, v159, v233
	v_fmac_f32_e32 v83, v159, v217
	v_fmac_f32_e32 v84, v159, v201
	v_fmac_f32_e32 v85, v159, v183
	v_fmac_f32_e32 v86, v159, v167
	v_fmac_f32_e32 v87, v159, v147
	v_fmac_f32_e32 v100, v159, v131
	v_fmac_f32_e32 v104, v187, v187
	v_fmac_f32_e32 v81, v187, v250
	v_fmac_f32_e32 v82, v187, v234
	v_fmac_f32_e32 v83, v187, v218
	v_fmac_f32_e32 v84, v187, v202
	v_fmac_f32_e32 v85, v187, v184
	v_fmac_f32_e32 v86, v187, v168
	v_fmac_f32_e32 v87, v187, v148
	v_fmac_f32_e32 v100, v187, v132
	v_fmac_f32_e32 v104, v44, v44
	v_fmac_f32_e32 v81, v44, v251
	v_fmac_f32_e32 v82, v44, v235
	v_fmac_f32_e32 v83, v44, v219
	v_fmac_f32_e32 v84, v44, v203
	v_fmac_f32_e32 v85, v44, v185
	v_fmac_f32_e32 v86, v44, v169
	v_fmac_f32_e32 v87, v44, v149
	v_fmac_f32_e32 v100, v44, v133
	v_fmac_f32_e32 v104, v45, v45
	v_fmac_f32_e32 v81, v45, v244
	v_fmac_f32_e32 v82, v45, v228
	v_fmac_f32_e32 v83, v45, v212
	v_fmac_f32_e32 v84, v45, v196
	v_fmac_f32_e32 v85, v45, v178
	v_fmac_f32_e32 v86, v45, v162
	v_fmac_f32_e32 v87, v45, v142
	v_fmac_f32_e32 v100, v45, v124
	v_fmac_f32_e32 v104, v46, v46
	v_fmac_f32_e32 v81, v46, v245
	v_fmac_f32_e32 v82, v46, v229
	v_fmac_f32_e32 v83, v46, v213
	v_fmac_f32_e32 v84, v46, v197
	v_fmac_f32_e32 v85, v46, v179
	v_fmac_f32_e32 v86, v46, v163
	v_fmac_f32_e32 v87, v46, v143
	v_fmac_f32_e32 v100, v46, v125
	v_fmac_f32_e32 v104, v47, v47
	v_fmac_f32_e32 v81, v47, v246
	v_fmac_f32_e32 v82, v47, v230
	v_fmac_f32_e32 v83, v47, v214
	v_fmac_f32_e32 v84, v47, v198
	v_fmac_f32_e32 v85, v47, v180
	v_fmac_f32_e32 v86, v47, v164
	v_fmac_f32_e32 v87, v47, v144
	v_fmac_f32_e32 v100, v47, v126
	v_fmac_f32_e32 v104, v48, v48
	v_fmac_f32_e32 v81, v48, v247
	v_fmac_f32_e32 v82, v48, v231
	v_fmac_f32_e32 v83, v48, v215
	v_fmac_f32_e32 v84, v48, v199
	v_fmac_f32_e32 v85, v48, v181
	v_fmac_f32_e32 v86, v48, v165
	v_fmac_f32_e32 v87, v48, v145
	v_fmac_f32_e32 v100, v48, v127
	v_fmac_f32_e32 v104, v49, v49
	v_fmac_f32_e32 v81, v49, v240
	v_fmac_f32_e32 v82, v49, v224
	v_fmac_f32_e32 v83, v49, v208
	v_fmac_f32_e32 v84, v49, v192
	v_fmac_f32_e32 v85, v49, v174
	v_fmac_f32_e32 v86, v49, v154
	v_fmac_f32_e32 v87, v49, v138
	v_fmac_f32_e32 v100, v49, v120
	v_fmac_f32_e32 v104, v50, v50
	v_fmac_f32_e32 v81, v50, v241
	v_fmac_f32_e32 v82, v50, v225
	v_fmac_f32_e32 v83, v50, v209
	v_fmac_f32_e32 v84, v50, v193
	v_fmac_f32_e32 v85, v50, v175
	v_fmac_f32_e32 v86, v50, v155
	v_fmac_f32_e32 v87, v50, v139
	v_fmac_f32_e32 v100, v50, v121
	v_fmac_f32_e32 v104, v51, v51
	v_fmac_f32_e32 v81, v51, v242
	v_fmac_f32_e32 v82, v51, v226
	v_fmac_f32_e32 v83, v51, v210
	v_fmac_f32_e32 v84, v51, v194
	v_fmac_f32_e32 v85, v51, v176
	v_fmac_f32_e32 v86, v51, v156
	v_fmac_f32_e32 v87, v51, v140
	v_fmac_f32_e32 v100, v51, v122
	v_fmac_f32_e32 v104, v52, v52
	v_fmac_f32_e32 v81, v52, v243
	v_fmac_f32_e32 v82, v52, v227
	v_fmac_f32_e32 v83, v52, v211
	v_fmac_f32_e32 v84, v52, v195
	v_fmac_f32_e32 v85, v52, v177
	v_fmac_f32_e32 v86, v52, v157
	v_fmac_f32_e32 v87, v52, v141
	v_fmac_f32_e32 v100, v52, v123
	v_fmac_f32_e32 v104, v53, v53
	v_fmac_f32_e32 v81, v53, v236
	v_fmac_f32_e32 v82, v53, v220
	v_fmac_f32_e32 v83, v53, v204
	v_fmac_f32_e32 v84, v53, v188
	v_fmac_f32_e32 v85, v53, v170
	v_fmac_f32_e32 v86, v53, v150
	v_fmac_f32_e32 v87, v53, v134
	v_fmac_f32_e32 v100, v53, v116
	v_fmac_f32_e32 v104, v54, v54
	v_fmac_f32_e32 v81, v54, v237
	v_fmac_f32_e32 v82, v54, v221
	v_fmac_f32_e32 v83, v54, v205
	v_fmac_f32_e32 v84, v54, v189
	v_fmac_f32_e32 v85, v54, v171
	v_fmac_f32_e32 v86, v54, v151
	v_fmac_f32_e32 v87, v54, v135
	v_fmac_f32_e32 v100, v54, v117
	v_fmac_f32_e32 v104, v55, v55
	v_fmac_f32_e32 v81, v55, v238
	v_fmac_f32_e32 v82, v55, v222
	v_fmac_f32_e32 v83, v55, v206
	v_fmac_f32_e32 v84, v55, v190
	v_fmac_f32_e32 v85, v55, v172
	v_fmac_f32_e32 v86, v55, v152
	v_fmac_f32_e32 v87, v55, v136
	v_fmac_f32_e32 v100, v55, v118
	v_fmac_f32_e32 v104, v56, v56
	v_fmac_f32_e32 v81, v56, v239
	v_fmac_f32_e32 v82, v56, v223
	v_fmac_f32_e32 v83, v56, v207
	v_fmac_f32_e32 v84, v56, v191
	v_fmac_f32_e32 v85, v56, v173
	v_fmac_f32_e32 v86, v56, v153
	v_fmac_f32_e32 v87, v56, v137
	v_fmac_f32_e32 v100, v56, v119
	s_nop 1
	v_permlane32_swap_b32_e32 v57, v73
	v_permlane32_swap_b32_e32 v58, v74
	v_permlane32_swap_b32_e32 v59, v75
	v_permlane32_swap_b32_e32 v60, v76
	v_permlane32_swap_b32_e32 v61, v77
	v_permlane32_swap_b32_e32 v62, v78
	v_permlane32_swap_b32_e32 v63, v79
	v_permlane32_swap_b32_e32 v64, v80
	v_permlane32_swap_b32_e32 v65, v81
	v_permlane32_swap_b32_e32 v66, v82
; __device__ __forceinline__ float lane_get(float v, int src_lane) { return __builtin_bit_cast(float, __builtin_amdgcn_ds_bpermute(src_lane << 2, __builtin_bit_cast(int, v))); }
; __device__ __forceinline__ void fgate_phase(const bfr* x, const float* wf, const float* bfg, float* cl, float* ctot, LAS float* scr, int bx, int G, int tid, int lane, int wave) {
;     ...
;             for (int o = 1; o < 64; o <<= 1) {
; #pragma unroll
;                 for (int q = 0; q < 18; ++q) r[q] += lane_get(r[q], lane ^ o); }
;             const float rsa = rsqrtf(r[16] * (1.f / D) + EPS), rsb = rsqrtf(r[17] * (1.f / D) + EPS);
;             if (lane < 16) { const int h = lane & 7; float dsel = r[0];
; #pragma unroll
;                 for (int q = 1; q < 16; ++q) dsel = (lane == q) ? r[q] : dsel;
;                 const float zz = dsel * (lane < 8 ? rsa : rsb) + bfg[h]; const float lf = fminf(zz, 0.f) - 0.6931471805599453f * __builtin_amdgcn_logf(1.0f + __builtin_amdgcn_exp2f(-LOG2E * fabsf(zz)));
;                 scr[(wave * 8 + j + (lane >> 3)) * 8 + h] = lf; } }
	v_permlane32_swap_b32_e32 v67, v83
	v_permlane32_swap_b32_e32 v68, v84
	v_permlane32_swap_b32_e32 v69, v85
	v_permlane32_swap_b32_e32 v70, v86
	v_permlane32_swap_b32_e32 v71, v87
	v_permlane32_swap_b32_e32 v72, v100
	v_permlane32_swap_b32_e32 v101, v103
	v_permlane32_swap_b32_e32 v102, v104
	s_nop 1
	v_add_f32_e32 v57, v57, v73
	v_add_f32_e32 v58, v58, v74
	v_add_f32_e32 v59, v59, v75
	v_add_f32_e32 v60, v60, v76
	v_add_f32_e32 v61, v61, v77
	v_add_f32_e32 v62, v62, v78
	v_add_f32_e32 v63, v63, v79
	v_add_f32_e32 v64, v64, v80
	v_add_f32_e32 v65, v65, v81
	v_add_f32_e32 v66, v66, v82
	v_add_f32_e32 v67, v67, v83
	v_add_f32_e32 v68, v68, v84
	v_add_f32_e32 v69, v69, v85
	v_add_f32_e32 v70, v70, v86
	v_add_f32_e32 v71, v71, v87
	v_add_f32_e32 v72, v72, v100
	v_add_f32_e32 v101, v101, v103
	v_add_f32_e32 v102, v102, v104
	s_nop 1
	v_permlane16_swap_b32_e32 v57, v65
	v_permlane16_swap_b32_e32 v58, v66
	v_permlane16_swap_b32_e32 v59, v67
	v_permlane16_swap_b32_e32 v60, v68
	v_permlane16_swap_b32_e32 v61, v69
	v_permlane16_swap_b32_e32 v62, v70
	v_permlane16_swap_b32_e32 v63, v71
	v_permlane16_swap_b32_e32 v64, v72
	v_permlane16_swap_b32_e32 v101, v102
	s_nop 1
	v_add_f32_e32 v57, v57, v65
	v_add_f32_e32 v58, v58, v66
	v_add_f32_e32 v59, v59, v67
	v_add_f32_e32 v60, v60, v68
	v_add_f32_e32 v61, v61, v69
	v_add_f32_e32 v62, v62, v70
	v_add_f32_e32 v63, v63, v71
	v_add_f32_e32 v64, v64, v72
	v_add_f32_e32 v101, v101, v102
	s_nop 1
	v_add_f32_dpp v57, v57, v57 quad_perm:[1,0,3,2] row_mask:0xf bank_mask:0xf
	v_add_f32_dpp v58, v58, v58 quad_perm:[1,0,3,2] row_mask:0xf bank_mask:0xf
	v_add_f32_dpp v59, v59, v59 quad_perm:[1,0,3,2] row_mask:0xf bank_mask:0xf
	v_add_f32_dpp v60, v60, v60 quad_perm:[1,0,3,2] row_mask:0xf bank_mask:0xf
	v_add_f32_dpp v61, v61, v61 quad_perm:[1,0,3,2] row_mask:0xf bank_mask:0xf
	v_add_f32_dpp v62, v62, v62 quad_perm:[1,0,3,2] row_mask:0xf bank_mask:0xf
	v_add_f32_dpp v63, v63, v63 quad_perm:[1,0,3,2] row_mask:0xf bank_mask:0xf
	v_add_f32_dpp v64, v64, v64 quad_perm:[1,0,3,2] row_mask:0xf bank_mask:0xf
	v_add_f32_dpp v101, v101, v101 quad_perm:[1,0,3,2] row_mask:0xf bank_mask:0xf
	s_nop 1
	v_add_f32_dpp v57, v57, v57 quad_perm:[2,3,0,1] row_mask:0xf bank_mask:0xf
	v_add_f32_dpp v58, v58, v58 quad_perm:[2,3,0,1] row_mask:0xf bank_mask:0xf
	v_add_f32_dpp v59, v59, v59 quad_perm:[2,3,0,1] row_mask:0xf bank_mask:0xf
	v_add_f32_dpp v60, v60, v60 quad_perm:[2,3,0,1] row_mask:0xf bank_mask:0xf
	v_add_f32_dpp v61, v61, v61 quad_perm:[2,3,0,1] row_mask:0xf bank_mask:0xf
	v_add_f32_dpp v62, v62, v62 quad_perm:[2,3,0,1] row_mask:0xf bank_mask:0xf
	v_add_f32_dpp v63, v63, v63 quad_perm:[2,3,0,1] row_mask:0xf bank_mask:0xf
	v_add_f32_dpp v64, v64, v64 quad_perm:[2,3,0,1] row_mask:0xf bank_mask:0xf
	v_add_f32_dpp v101, v101, v101 quad_perm:[2,3,0,1] row_mask:0xf bank_mask:0xf
	s_nop 1
	v_add_f32_dpp v57, v57, v57 row_half_mirror row_mask:0xf bank_mask:0xf
	v_add_f32_dpp v58, v58, v58 row_half_mirror row_mask:0xf bank_mask:0xf
	v_add_f32_dpp v59, v59, v59 row_half_mirror row_mask:0xf bank_mask:0xf
	v_add_f32_dpp v60, v60, v60 row_half_mirror row_mask:0xf bank_mask:0xf
	v_add_f32_dpp v61, v61, v61 row_half_mirror row_mask:0xf bank_mask:0xf
	v_add_f32_dpp v62, v62, v62 row_half_mirror row_mask:0xf bank_mask:0xf
	v_add_f32_dpp v63, v63, v63 row_half_mirror row_mask:0xf bank_mask:0xf
	v_add_f32_dpp v64, v64, v64 row_half_mirror row_mask:0xf bank_mask:0xf
	v_add_f32_dpp v101, v101, v101 row_half_mirror row_mask:0xf bank_mask:0xf
	s_nop 1
	v_add_f32_dpp v57, v57, v57 row_mirror row_mask:0xf bank_mask:0xf
	v_add_f32_dpp v58, v58, v58 row_mirror row_mask:0xf bank_mask:0xf
	v_add_f32_dpp v59, v59, v59 row_mirror row_mask:0xf bank_mask:0xf
	v_add_f32_dpp v60, v60, v60 row_mirror row_mask:0xf bank_mask:0xf
	v_add_f32_dpp v61, v61, v61 row_mirror row_mask:0xf bank_mask:0xf
	v_add_f32_dpp v62, v62, v62 row_mirror row_mask:0xf bank_mask:0xf
	v_add_f32_dpp v63, v63, v63 row_mirror row_mask:0xf bank_mask:0xf
	v_add_f32_dpp v64, v64, v64 row_mirror row_mask:0xf bank_mask:0xf
	v_add_f32_dpp v101, v101, v101 row_mirror row_mask:0xf bank_mask:0xf
	s_nop 1
	v_mov_b32_e32 v106, v57
	v_cndmask_b32_e64 v106, v106, v58, s[6:7]
	v_cndmask_b32_e64 v106, v106, v59, s[8:9]
	v_cndmask_b32_e64 v106, v106, v60, s[10:11]
	v_cndmask_b32_e64 v106, v106, v61, s[12:13]
	v_cndmask_b32_e64 v106, v106, v62, s[14:15]
	v_cndmask_b32_e64 v106, v106, v63, s[16:17]
	v_cndmask_b32_e64 v106, v106, v64, s[18:19]
	v_mul_f32_e32 v107, 0x3a800000, v101
	v_add_f32_e32 v107, 0x358637bd, v107
	v_rsq_f32_e32 v107, v107
	s_nop 0
	v_fma_f32 v106, v106, v107, v105
	v_mul_f32_e64 v107, |v106|, s65
	v_exp_f32_e32 v107, v107
	v_min_f32_e32 v106, 0, v106
	v_add_f32_e32 v107, 1.0, v107
	v_log_f32_e32 v107, v107
	s_nop 0
	v_fmac_f32_e32 v106, 0xbf317218, v107
	s_mov_b64 s[54:55], exec
	s_mov_b32 exec_lo, 0xff00ff
	s_mov_b32 exec_hi, 0xff00ff
	ds_write_b32 v109, v106 offset:128
	s_mov_b64 exec, s[54:55]
